# GEMM K-loops: priority held through each 32-MFMA block (mid-block s_setprio 0/1 flip deleted)
# speedup vs baseline: 1.0004x; 1.0004x over previous
; #define PG8_STAGE(bufoff, gbase, voff) do { _Pragma("unroll") for (int _i = 0; _i < 2; ++_i) \
;         __builtin_amdgcn_global_load_lds((const unsigned*)((const char*)(gbase) + (voff)[_i]), (LAS unsigned*)(lds + (bufoff) + ldsw + _i * 8192), 16, 0, 0); } while (0)
; #define PG8_LDA(dst, b, h) do { _Pragma("unroll") for (int m = 0; m < 4; ++m) _Pragma("unroll") for (int k = 0; k < 2; ++k) dst[m][k] = *(const LAS bf16x8*)(lds + PG8_SA(b, h) + aoff + m * 2048 + k * 1024); } while (0)
; #define PG8_LDB(dst, b, h) do { _Pragma("unroll") for (int n = 0; n < 2; ++n) _Pragma("unroll") for (int k = 0; k < 2; ++k) dst[n][k] = *(const LAS bf16x8*)(lds + PG8_SB(b, h) + boff + n * 2048 + k * 1024); } while (0)
; #define PG8_MMA(ai, bj, At, Bt) do { __builtin_amdgcn_s_setprio(1); _Pragma("unroll") for (int m = 0; m < 4; ++m) _Pragma("unroll") for (int n = 0; n < 2; ++n) _Pragma("unroll") for (int k = 0; k < 2; ++k) \
;         acc[ai][bj][m][n] = __builtin_amdgcn_mfma_f32_16x16x32_bf16(Bt[n][k], At[m][k], acc[ai][bj][m][n], 0, 0, 0); __builtin_amdgcn_s_setprio(0); } while (0)
; #define PG8_WAIT_V(n) asm volatile("s_waitcnt vmcnt(" #n ")" ::: "memory")
; #define PG8_WAIT_L(n) asm volatile("s_waitcnt lgkmcnt(" #n ")" ::: "memory")
; #define PG8_BAR __builtin_amdgcn_s_barrier()
; #define PG8_SCHED __builtin_amdgcn_sched_barrier(0)
; template <class Epi, class Sched, bool ALIGN_EPI = false, bool SP2 = false>
; __device__ __forceinline__ void gemm_phase(LAS unsigned char* lds, const Gemm g, const Sched S, const Epi E) {
;     ...
;             PG8_LDB(B0, 0, 0); PG8_LDB(B1, 0, 1); PG8_SCHED; PG8_LDA(At, 0, 0); PG8_STAGE(PG8_SA(1, 1), a1 + hstepA, voffA);
;             PG8_WAIT_V(8); PG8_WAIT_L(0); PG8_BAR; PG8_MMA(0, 0, At, B0); PG8_MMA(0, 1, At, B1); PG8_BAR; PG8_SCHED;
;             PG8_LDA(At, 0, 1); PG8_STAGE(PG8_SB(0, 0), b2, voffB); PG8_STAGE(PG8_SB(0, 1), b2 + hstepB, voffB); PG8_STAGE(PG8_SA(0, 0), a2, voffA);
;             PG8_WAIT_V(8); PG8_WAIT_L(0); PG8_BAR; PG8_MMA(1, 0, At, B0); PG8_MMA(1, 1, At, B1); PG8_BAR; PG8_SCHED;
.LBB0_623:
	ds_read_b128 v[152:155], v149
	ds_read_b128 v[156:159], v149 offset:1024
	ds_read_b128 v[160:163], v149 offset:2048
	ds_read_b128 v[164:167], v149 offset:3072
	ds_read_b128 v[168:171], v150
	ds_read_b128 v[172:175], v150 offset:1024
	ds_read_b128 v[176:179], v150 offset:2048
	ds_read_b128 v[180:183], v150 offset:3072
	s_add_u32 s34, s68, 0xfffc0080
	s_addc_u32 s35, s69, -1
	s_cmp_eq_u32 s84, 12
	s_cselect_b32 s73, s61, s35
	s_cselect_b32 s72, s80, s34
	s_cselect_b32 s71, s51, s83
	s_cselect_b32 s70, s81, s82
	s_add_i32 m0, s29, 0xc000
	ds_read_b128 v[184:187], v151
	ds_read_b128 v[188:191], v151 offset:1024
	ds_read_b128 v[192:195], v151 offset:2048
	ds_read_b128 v[196:199], v151 offset:3072
	ds_read_b128 v[200:203], v151 offset:4096
	ds_read_b128 v[204:207], v151 offset:5120
	ds_read_b128 v[208:211], v151 offset:6144
	ds_read_b128 v[212:215], v151 offset:7168
	global_load_lds_dwordx4 v136, s[68:69]
	s_add_i32 m0, s29, 0xe000
	s_nop 0
	global_load_lds_dwordx4 v138, s[68:69]
	s_waitcnt vmcnt(8)
	s_waitcnt lgkmcnt(0)
	s_barrier
	s_setprio 1
	s_waitcnt lgkmcnt(0)
	v_mfma_f32_16x16x32_bf16 v[124:127], v[152:155], v[184:187], v[124:127]
	v_mfma_f32_16x16x32_bf16 v[120:123], v[160:163], v[184:187], v[120:123]
	v_mfma_f32_16x16x32_bf16 v[108:111], v[152:155], v[192:195], v[108:111]
	v_mfma_f32_16x16x32_bf16 v[104:107], v[160:163], v[192:195], v[104:107]
	v_mfma_f32_16x16x32_bf16 v[92:95], v[152:155], v[200:203], v[92:95]
	v_mfma_f32_16x16x32_bf16 v[88:91], v[160:163], v[200:203], v[88:91]
	v_mfma_f32_16x16x32_bf16 v[76:79], v[152:155], v[208:211], v[76:79]
	v_mfma_f32_16x16x32_bf16 v[72:75], v[160:163], v[208:211], v[72:75]
	v_mfma_f32_16x16x32_bf16 v[124:127], v[156:159], v[188:191], v[124:127]
	v_mfma_f32_16x16x32_bf16 v[120:123], v[164:167], v[188:191], v[120:123]
	v_mfma_f32_16x16x32_bf16 v[108:111], v[156:159], v[196:199], v[108:111]
	v_mfma_f32_16x16x32_bf16 v[104:107], v[164:167], v[196:199], v[104:107]
	v_mfma_f32_16x16x32_bf16 v[92:95], v[156:159], v[204:207], v[92:95]
	v_mfma_f32_16x16x32_bf16 v[88:91], v[164:167], v[204:207], v[88:91]
	v_mfma_f32_16x16x32_bf16 v[76:79], v[156:159], v[212:215], v[76:79]
	v_mfma_f32_16x16x32_bf16 v[72:75], v[164:167], v[212:215], v[72:75]
	v_mfma_f32_16x16x32_bf16 v[116:119], v[168:171], v[184:187], v[116:119]
	v_mfma_f32_16x16x32_bf16 v[112:115], v[176:179], v[184:187], v[112:115]
	v_mfma_f32_16x16x32_bf16 v[100:103], v[168:171], v[192:195], v[100:103]
	v_mfma_f32_16x16x32_bf16 v[96:99], v[176:179], v[192:195], v[96:99]
	v_mfma_f32_16x16x32_bf16 v[84:87], v[168:171], v[200:203], v[84:87]
	v_mfma_f32_16x16x32_bf16 v[80:83], v[176:179], v[200:203], v[80:83]
	v_mfma_f32_16x16x32_bf16 v[68:71], v[168:171], v[208:211], v[68:71]
	v_mfma_f32_16x16x32_bf16 v[64:67], v[176:179], v[208:211], v[64:67]
	v_mfma_f32_16x16x32_bf16 v[116:119], v[172:175], v[188:191], v[116:119]
	v_mfma_f32_16x16x32_bf16 v[112:115], v[180:183], v[188:191], v[112:115]
	v_mfma_f32_16x16x32_bf16 v[100:103], v[172:175], v[196:199], v[100:103]
	v_mfma_f32_16x16x32_bf16 v[96:99], v[180:183], v[196:199], v[96:99]
	v_mfma_f32_16x16x32_bf16 v[84:87], v[172:175], v[204:207], v[84:87]
	v_mfma_f32_16x16x32_bf16 v[80:83], v[180:183], v[204:207], v[80:83]
	v_mfma_f32_16x16x32_bf16 v[68:71], v[172:175], v[212:215], v[68:71]
	v_mfma_f32_16x16x32_bf16 v[64:67], v[180:183], v[212:215], v[64:67]
	s_setprio 0
	s_barrier
	s_add_i32 s34, s76, s20
	v_lshl_add_u64 v[144:145], s[70:71], 0, v[132:133]
	s_mov_b32 m0, s34
	ds_read_b128 v[184:187], v151 offset:16384
	ds_read_b128 v[188:191], v151 offset:17408
	ds_read_b128 v[192:195], v151 offset:18432
	ds_read_b128 v[196:199], v151 offset:19456
	ds_read_b128 v[200:203], v151 offset:20480
	ds_read_b128 v[204:207], v151 offset:21504
	ds_read_b128 v[208:211], v151 offset:22528
	ds_read_b128 v[212:215], v151 offset:23552
	global_load_lds_dwordx4 v[144:145], off
	s_add_i32 m0, s34, 0x2000
	s_add_u32 s34, s70, 0x40000
	v_lshl_add_u64 v[216:217], s[70:71], 0, v[128:129]
	s_addc_u32 s35, s71, 0
	s_add_i32 s85, s77, s20
	global_load_lds_dwordx4 v[216:217], off
	s_mov_b32 m0, s85
	v_lshl_add_u64 v[220:221], s[72:73], 0, v[130:131]
	global_load_lds_dwordx4 v132, s[34:35]
	s_add_i32 m0, s85, 0x2000
	s_nop 0
	global_load_lds_dwordx4 v128, s[34:35]
	v_lshl_add_u64 v[218:219], s[72:73], 0, v[134:135]
	s_mov_b32 m0, s29
	s_nop 0
	global_load_lds_dwordx4 v[218:219], off
	s_mov_b32 m0, s30
	s_nop 0
	global_load_lds_dwordx4 v[220:221], off
	s_waitcnt vmcnt(8)
	s_waitcnt lgkmcnt(0)
	s_barrier
	s_setprio 1
	s_waitcnt lgkmcnt(0)
	v_mfma_f32_16x16x32_bf16 v[60:63], v[152:155], v[184:187], v[60:63]
	v_mfma_f32_16x16x32_bf16 v[56:59], v[160:163], v[184:187], v[56:59]
	v_mfma_f32_16x16x32_bf16 v[44:47], v[152:155], v[192:195], v[44:47]
	v_mfma_f32_16x16x32_bf16 v[40:43], v[160:163], v[192:195], v[40:43]
	v_mfma_f32_16x16x32_bf16 v[28:31], v[152:155], v[200:203], v[28:31]
	v_mfma_f32_16x16x32_bf16 v[24:27], v[160:163], v[200:203], v[24:27]
	v_mfma_f32_16x16x32_bf16 v[12:15], v[152:155], v[208:211], v[12:15]
	v_mfma_f32_16x16x32_bf16 v[8:11], v[160:163], v[208:211], v[8:11]
	v_mfma_f32_16x16x32_bf16 v[60:63], v[156:159], v[188:191], v[60:63]
	v_mfma_f32_16x16x32_bf16 v[56:59], v[164:167], v[188:191], v[56:59]
	v_mfma_f32_16x16x32_bf16 v[44:47], v[156:159], v[196:199], v[44:47]
	v_mfma_f32_16x16x32_bf16 v[40:43], v[164:167], v[196:199], v[40:43]
	v_mfma_f32_16x16x32_bf16 v[28:31], v[156:159], v[204:207], v[28:31]
	v_mfma_f32_16x16x32_bf16 v[24:27], v[164:167], v[204:207], v[24:27]
	v_mfma_f32_16x16x32_bf16 v[12:15], v[156:159], v[212:215], v[12:15]
	v_mfma_f32_16x16x32_bf16 v[8:11], v[164:167], v[212:215], v[8:11]
	v_mfma_f32_16x16x32_bf16 v[52:55], v[168:171], v[184:187], v[52:55]
	v_mfma_f32_16x16x32_bf16 v[48:51], v[176:179], v[184:187], v[48:51]
	v_mfma_f32_16x16x32_bf16 v[36:39], v[168:171], v[192:195], v[36:39]
	v_mfma_f32_16x16x32_bf16 v[32:35], v[176:179], v[192:195], v[32:35]
	v_mfma_f32_16x16x32_bf16 v[20:23], v[168:171], v[200:203], v[20:23]
	v_mfma_f32_16x16x32_bf16 v[16:19], v[176:179], v[200:203], v[16:19]
	v_mfma_f32_16x16x32_bf16 v[4:7], v[168:171], v[208:211], v[4:7]
	v_mfma_f32_16x16x32_bf16 v[0:3], v[176:179], v[208:211], v[0:3]
	v_mfma_f32_16x16x32_bf16 v[52:55], v[172:175], v[188:191], v[52:55]
	v_mfma_f32_16x16x32_bf16 v[48:51], v[180:183], v[188:191], v[48:51]
	v_mfma_f32_16x16x32_bf16 v[36:39], v[172:175], v[196:199], v[36:39]
	v_mfma_f32_16x16x32_bf16 v[32:35], v[180:183], v[196:199], v[32:35]
	v_mfma_f32_16x16x32_bf16 v[20:23], v[172:175], v[204:207], v[20:23]
	v_mfma_f32_16x16x32_bf16 v[16:19], v[180:183], v[204:207], v[16:19]
	v_mfma_f32_16x16x32_bf16 v[4:7], v[172:175], v[212:215], v[4:7]
	v_mfma_f32_16x16x32_bf16 v[0:3], v[180:183], v[212:215], v[0:3]
	s_setprio 0
	s_barrier
; #define PG8_STAGE(bufoff, gbase, voff) do { _Pragma("unroll") for (int _i = 0; _i < 2; ++_i) \
;         __builtin_amdgcn_global_load_lds((const unsigned*)((const char*)(gbase) + (voff)[_i]), (LAS unsigned*)(lds + (bufoff) + ldsw + _i * 8192), 16, 0, 0); } while (0)
; #define PG8_LDA(dst, b, h) do { _Pragma("unroll") for (int m = 0; m < 4; ++m) _Pragma("unroll") for (int k = 0; k < 2; ++k) dst[m][k] = *(const LAS bf16x8*)(lds + PG8_SA(b, h) + aoff + m * 2048 + k * 1024); } while (0)
; #define PG8_LDB(dst, b, h) do { _Pragma("unroll") for (int n = 0; n < 2; ++n) _Pragma("unroll") for (int k = 0; k < 2; ++k) dst[n][k] = *(const LAS bf16x8*)(lds + PG8_SB(b, h) + boff + n * 2048 + k * 1024); } while (0)
; #define PG8_MMA(ai, bj, At, Bt) do { __builtin_amdgcn_s_setprio(1); _Pragma("unroll") for (int m = 0; m < 4; ++m) _Pragma("unroll") for (int n = 0; n < 2; ++n) _Pragma("unroll") for (int k = 0; k < 2; ++k) \
;         acc[ai][bj][m][n] = __builtin_amdgcn_mfma_f32_16x16x32_bf16(Bt[n][k], At[m][k], acc[ai][bj][m][n], 0, 0, 0); __builtin_amdgcn_s_setprio(0); } while (0)
; #define PG8_WAIT_V(n) asm volatile("s_waitcnt vmcnt(" #n ")" ::: "memory")
; #define PG8_WAIT_L(n) asm volatile("s_waitcnt lgkmcnt(" #n ")" ::: "memory")
; #define PG8_BAR __builtin_amdgcn_s_barrier()
; #define PG8_SCHED __builtin_amdgcn_sched_barrier(0)
; template <class Epi, class Sched, bool ALIGN_EPI = false, bool SP2 = false>
; __device__ __forceinline__ void gemm_phase(LAS unsigned char* lds, const Gemm g, const Sched S, const Epi E) {
;     ...
;             PG8_LDB(B0, 1, 0); PG8_LDB(B1, 1, 1); PG8_SCHED; PG8_LDA(At, 1, 0); PG8_STAGE(PG8_SA(0, 1), a2 + hstepA, voffA);
;             PG8_WAIT_V(8); PG8_WAIT_L(0); PG8_BAR; PG8_MMA(0, 0, At, B0); PG8_MMA(0, 1, At, B1); PG8_BAR; PG8_SCHED;
;             PG8_LDA(At, 1, 1); PG8_STAGE(PG8_SB(1, 0), b3, voffB); PG8_STAGE(PG8_SB(1, 1), b3 + hstepB, voffB); PG8_STAGE(PG8_SA(1, 0), a3, voffA);
;             PG8_WAIT_V(8); PG8_WAIT_L(0); PG8_BAR; PG8_MMA(1, 0, At, B0); PG8_MMA(1, 1, At, B1); PG8_BAR; PG8_SCHED;
	s_add_i32 s85, 0, 0x18000
	s_add_i32 s86, 0, 0x1c000
	v_add_u32_e32 v164, s85, v147
	v_add_u32_e32 v180, s86, v147
	ds_read_b128 v[152:155], v164
	ds_read_b128 v[156:159], v164 offset:1024
	ds_read_b128 v[160:163], v164 offset:2048
	ds_read_b128 v[164:167], v164 offset:3072
	ds_read_b128 v[168:171], v180
	ds_read_b128 v[172:175], v180 offset:1024
	ds_read_b128 v[176:179], v180 offset:2048
	ds_read_b128 v[180:183], v180 offset:3072
	s_add_u32 s34, s72, 0x40000
	s_addc_u32 s35, s73, 0
	s_mov_b32 m0, s31
	ds_read_b128 v[184:187], v151 offset:32768
	ds_read_b128 v[188:191], v151 offset:33792
	ds_read_b128 v[192:195], v151 offset:34816
	ds_read_b128 v[196:199], v151 offset:35840
	ds_read_b128 v[200:203], v151 offset:36864
	ds_read_b128 v[204:207], v151 offset:37888
	ds_read_b128 v[208:211], v151 offset:38912
	ds_read_b128 v[212:215], v151 offset:39936
	global_load_lds_dwordx4 v134, s[34:35]
	s_mov_b32 m0, s33
	s_nop 0
	global_load_lds_dwordx4 v130, s[34:35]
	s_waitcnt vmcnt(8)
	s_waitcnt lgkmcnt(0)
	s_barrier
	s_setprio 1
	s_waitcnt lgkmcnt(0)
	v_mfma_f32_16x16x32_bf16 v[124:127], v[152:155], v[184:187], v[124:127]
	v_mfma_f32_16x16x32_bf16 v[120:123], v[160:163], v[184:187], v[120:123]
	v_mfma_f32_16x16x32_bf16 v[108:111], v[152:155], v[192:195], v[108:111]
	v_mfma_f32_16x16x32_bf16 v[104:107], v[160:163], v[192:195], v[104:107]
	v_mfma_f32_16x16x32_bf16 v[92:95], v[152:155], v[200:203], v[92:95]
	v_mfma_f32_16x16x32_bf16 v[88:91], v[160:163], v[200:203], v[88:91]
	v_mfma_f32_16x16x32_bf16 v[76:79], v[152:155], v[208:211], v[76:79]
	v_mfma_f32_16x16x32_bf16 v[72:75], v[160:163], v[208:211], v[72:75]
	v_mfma_f32_16x16x32_bf16 v[124:127], v[156:159], v[188:191], v[124:127]
	v_mfma_f32_16x16x32_bf16 v[120:123], v[164:167], v[188:191], v[120:123]
	v_mfma_f32_16x16x32_bf16 v[108:111], v[156:159], v[196:199], v[108:111]
	v_mfma_f32_16x16x32_bf16 v[104:107], v[164:167], v[196:199], v[104:107]
	v_mfma_f32_16x16x32_bf16 v[92:95], v[156:159], v[204:207], v[92:95]
	v_mfma_f32_16x16x32_bf16 v[88:91], v[164:167], v[204:207], v[88:91]
	v_mfma_f32_16x16x32_bf16 v[76:79], v[156:159], v[212:215], v[76:79]
	v_mfma_f32_16x16x32_bf16 v[72:75], v[164:167], v[212:215], v[72:75]
	v_mfma_f32_16x16x32_bf16 v[116:119], v[168:171], v[184:187], v[116:119]
	v_mfma_f32_16x16x32_bf16 v[112:115], v[176:179], v[184:187], v[112:115]
	v_mfma_f32_16x16x32_bf16 v[100:103], v[168:171], v[192:195], v[100:103]
	v_mfma_f32_16x16x32_bf16 v[96:99], v[176:179], v[192:195], v[96:99]
	v_mfma_f32_16x16x32_bf16 v[84:87], v[168:171], v[200:203], v[84:87]
	v_mfma_f32_16x16x32_bf16 v[80:83], v[176:179], v[200:203], v[80:83]
	v_mfma_f32_16x16x32_bf16 v[68:71], v[168:171], v[208:211], v[68:71]
	v_mfma_f32_16x16x32_bf16 v[64:67], v[176:179], v[208:211], v[64:67]
	v_mfma_f32_16x16x32_bf16 v[116:119], v[172:175], v[188:191], v[116:119]
	v_mfma_f32_16x16x32_bf16 v[112:115], v[180:183], v[188:191], v[112:115]
	v_mfma_f32_16x16x32_bf16 v[100:103], v[172:175], v[196:199], v[100:103]
	v_mfma_f32_16x16x32_bf16 v[96:99], v[180:183], v[196:199], v[96:99]
	v_mfma_f32_16x16x32_bf16 v[84:87], v[172:175], v[204:207], v[84:87]
	v_mfma_f32_16x16x32_bf16 v[80:83], v[180:183], v[204:207], v[80:83]
	v_mfma_f32_16x16x32_bf16 v[68:71], v[172:175], v[212:215], v[68:71]
	v_mfma_f32_16x16x32_bf16 v[64:67], v[180:183], v[212:215], v[64:67]
	s_setprio 0
	s_barrier
	s_add_i32 s34, s85, s20
	v_lshl_add_u64 v[144:145], v[144:145], 0, s[10:11]
	s_mov_b32 m0, s34
	ds_read_b128 v[184:187], v151 offset:49152
	ds_read_b128 v[188:191], v151 offset:50176
	ds_read_b128 v[192:195], v151 offset:51200
	ds_read_b128 v[196:199], v151 offset:52224
	ds_read_b128 v[200:203], v151 offset:53248
	ds_read_b128 v[204:207], v151 offset:54272
	ds_read_b128 v[208:211], v151 offset:55296
	ds_read_b128 v[212:215], v151 offset:56320
	global_load_lds_dwordx4 v[144:145], off
	s_add_i32 m0, s34, 0x2000
	s_add_u32 s34, s70, 0x40080
	v_lshl_add_u64 v[144:145], v[216:217], 0, s[10:11]
	s_addc_u32 s35, s71, 0
	s_add_i32 s70, s86, s20
	global_load_lds_dwordx4 v[144:145], off
	s_mov_b32 m0, s70
	s_nop 0
	global_load_lds_dwordx4 v132, s[34:35]
	s_add_i32 m0, s70, 0x2000
	s_nop 0
	global_load_lds_dwordx4 v128, s[34:35]
	v_lshl_add_u64 v[144:145], v[218:219], 0, s[10:11]
	s_mov_b32 m0, s45
	s_nop 0
	global_load_lds_dwordx4 v[144:145], off
	v_lshl_add_u64 v[144:145], v[220:221], 0, s[10:11]
	s_mov_b32 m0, s67
	s_nop 0
	global_load_lds_dwordx4 v[144:145], off
	s_waitcnt vmcnt(8)
	s_waitcnt lgkmcnt(0)
	s_barrier
	s_setprio 1
	s_waitcnt lgkmcnt(0)
	v_mfma_f32_16x16x32_bf16 v[60:63], v[152:155], v[184:187], v[60:63]
	v_mfma_f32_16x16x32_bf16 v[56:59], v[160:163], v[184:187], v[56:59]
	v_mfma_f32_16x16x32_bf16 v[44:47], v[152:155], v[192:195], v[44:47]
	v_mfma_f32_16x16x32_bf16 v[40:43], v[160:163], v[192:195], v[40:43]
	v_mfma_f32_16x16x32_bf16 v[28:31], v[152:155], v[200:203], v[28:31]
	v_mfma_f32_16x16x32_bf16 v[24:27], v[160:163], v[200:203], v[24:27]
	v_mfma_f32_16x16x32_bf16 v[12:15], v[152:155], v[208:211], v[12:15]
	v_mfma_f32_16x16x32_bf16 v[8:11], v[160:163], v[208:211], v[8:11]
	v_mfma_f32_16x16x32_bf16 v[60:63], v[156:159], v[188:191], v[60:63]
	v_mfma_f32_16x16x32_bf16 v[56:59], v[164:167], v[188:191], v[56:59]
	v_mfma_f32_16x16x32_bf16 v[44:47], v[156:159], v[196:199], v[44:47]
	v_mfma_f32_16x16x32_bf16 v[40:43], v[164:167], v[196:199], v[40:43]
	v_mfma_f32_16x16x32_bf16 v[28:31], v[156:159], v[204:207], v[28:31]
	v_mfma_f32_16x16x32_bf16 v[24:27], v[164:167], v[204:207], v[24:27]
	v_mfma_f32_16x16x32_bf16 v[12:15], v[156:159], v[212:215], v[12:15]
	v_mfma_f32_16x16x32_bf16 v[8:11], v[164:167], v[212:215], v[8:11]
	v_mfma_f32_16x16x32_bf16 v[52:55], v[168:171], v[184:187], v[52:55]
	v_mfma_f32_16x16x32_bf16 v[48:51], v[176:179], v[184:187], v[48:51]
	v_mfma_f32_16x16x32_bf16 v[36:39], v[168:171], v[192:195], v[36:39]
	v_mfma_f32_16x16x32_bf16 v[32:35], v[176:179], v[192:195], v[32:35]
	v_mfma_f32_16x16x32_bf16 v[20:23], v[168:171], v[200:203], v[20:23]
	v_mfma_f32_16x16x32_bf16 v[16:19], v[176:179], v[200:203], v[16:19]
	v_mfma_f32_16x16x32_bf16 v[4:7], v[168:171], v[208:211], v[4:7]
	v_mfma_f32_16x16x32_bf16 v[0:3], v[176:179], v[208:211], v[0:3]
	v_mfma_f32_16x16x32_bf16 v[52:55], v[172:175], v[188:191], v[52:55]
	v_mfma_f32_16x16x32_bf16 v[48:51], v[180:183], v[188:191], v[48:51]
	v_mfma_f32_16x16x32_bf16 v[36:39], v[172:175], v[196:199], v[36:39]
	v_mfma_f32_16x16x32_bf16 v[32:35], v[180:183], v[196:199], v[32:35]
	v_mfma_f32_16x16x32_bf16 v[20:23], v[172:175], v[204:207], v[20:23]
	v_mfma_f32_16x16x32_bf16 v[16:19], v[180:183], v[204:207], v[16:19]
	v_mfma_f32_16x16x32_bf16 v[4:7], v[172:175], v[212:215], v[4:7]
	v_mfma_f32_16x16x32_bf16 v[0:3], v[180:183], v[212:215], v[0:3]
	s_setprio 0
	s_add_i32 s84, s84, 2
	s_add_u32 s68, s68, 0x100
	s_addc_u32 s69, s69, 0
	s_add_u32 s82, s82, 0x100
	s_addc_u32 s83, s83, 0
	s_cmp_gt_u32 s84, 13
	s_barrier
	s_cbranch_scc0 .LBB0_623
	s_and_b64 vcc, exec, s[14:15]
	s_cbranch_vccz .LBB0_626
	s_barrier

; #define PG8_STAGE(bufoff, gbase, voff) do { _Pragma("unroll") for (int _i = 0; _i < 2; ++_i) \
;         __builtin_amdgcn_global_load_lds((const unsigned*)((const char*)(gbase) + (voff)[_i]), (LAS unsigned*)(lds + (bufoff) + ldsw + _i * 8192), 16, 0, 0); } while (0)
; #define PG8_LDA(dst, b, h) do { _Pragma("unroll") for (int m = 0; m < 4; ++m) _Pragma("unroll") for (int k = 0; k < 2; ++k) dst[m][k] = *(const LAS bf16x8*)(lds + PG8_SA(b, h) + aoff + m * 2048 + k * 1024); } while (0)
; #define PG8_LDB(dst, b, h) do { _Pragma("unroll") for (int n = 0; n < 2; ++n) _Pragma("unroll") for (int k = 0; k < 2; ++k) dst[n][k] = *(const LAS bf16x8*)(lds + PG8_SB(b, h) + boff + n * 2048 + k * 1024); } while (0)
; #define PG8_MMA(ai, bj, At, Bt) do { __builtin_amdgcn_s_setprio(1); _Pragma("unroll") for (int m = 0; m < 4; ++m) _Pragma("unroll") for (int n = 0; n < 2; ++n) _Pragma("unroll") for (int k = 0; k < 2; ++k) \
;         acc[ai][bj][m][n] = __builtin_amdgcn_mfma_f32_16x16x32_bf16(Bt[n][k], At[m][k], acc[ai][bj][m][n], 0, 0, 0); __builtin_amdgcn_s_setprio(0); } while (0)
; #define PG8_WAIT_V(n) asm volatile("s_waitcnt vmcnt(" #n ")" ::: "memory")
; #define PG8_WAIT_L(n) asm volatile("s_waitcnt lgkmcnt(" #n ")" ::: "memory")
; #define PG8_BAR __builtin_amdgcn_s_barrier()
; #define PG8_SCHED __builtin_amdgcn_sched_barrier(0)
; template <class Epi, class Sched, bool ALIGN_EPI = false, bool SP2 = false>
; __device__ __forceinline__ void gemm_phase(LAS unsigned char* lds, const Gemm g, const Sched S, const Epi E) {
;     ...
;             PG8_LDB(B0, 0, 0); PG8_LDB(B1, 0, 1); PG8_SCHED; PG8_LDA(At, 0, 0); PG8_STAGE(PG8_SA(1, 1), a1 + hstepA, voffA);
;             PG8_WAIT_V(8); PG8_WAIT_L(0); PG8_BAR; PG8_MMA(0, 0, At, B0); PG8_MMA(0, 1, At, B1); PG8_BAR; PG8_SCHED;
;             PG8_LDA(At, 0, 1); PG8_STAGE(PG8_SB(0, 0), b2, voffB); PG8_STAGE(PG8_SB(0, 1), b2 + hstepB, voffB); PG8_STAGE(PG8_SA(0, 0), a2, voffA);
;             PG8_WAIT_V(8); PG8_WAIT_L(0); PG8_BAR; PG8_MMA(1, 0, At, B0); PG8_MMA(1, 1, At, B1); PG8_BAR; PG8_SCHED;
.LBB0_705:
	ds_read_b128 v[128:131], v173
	ds_read_b128 v[132:135], v173 offset:1024
	ds_read_b128 v[136:139], v173 offset:2048
	ds_read_b128 v[140:143], v173 offset:3072
	ds_read_b128 v[160:163], v174
	ds_read_b128 v[164:167], v174 offset:1024
	ds_read_b128 v[178:181], v174 offset:2048
	ds_read_b128 v[182:185], v174 offset:3072
	s_add_u32 s74, s72, 0x100
	s_addc_u32 s75, s73, 0
	s_cmp_eq_u32 s88, 40
	s_cselect_b32 s79, s11, s75
	s_cselect_b32 s78, s10, s74
	s_cselect_b32 s77, s71, s87
	s_cselect_b32 s76, s70, s86
	s_add_i32 m0, s5, 0xc000
	ds_read_b128 v[186:189], v175
	ds_read_b128 v[190:193], v175 offset:1024
	ds_read_b128 v[194:197], v175 offset:2048
	ds_read_b128 v[198:201], v175 offset:3072
	ds_read_b128 v[202:205], v175 offset:4096
	ds_read_b128 v[206:209], v175 offset:5120
	ds_read_b128 v[210:213], v175 offset:6144
	ds_read_b128 v[214:217], v175 offset:7168
	global_load_lds_dwordx4 v152, s[72:73]
	s_add_i32 m0, s5, 0xe000
	s_nop 0
	global_load_lds_dwordx4 v154, s[72:73]
	s_waitcnt vmcnt(8)
	s_waitcnt lgkmcnt(0)
	s_barrier
	s_setprio 1
	s_waitcnt lgkmcnt(0)
	v_mfma_f32_16x16x32_bf16 v[124:127], v[128:131], v[186:189], v[124:127]
	v_mfma_f32_16x16x32_bf16 v[120:123], v[136:139], v[186:189], v[120:123]
	v_mfma_f32_16x16x32_bf16 v[108:111], v[128:131], v[194:197], v[108:111]
	v_mfma_f32_16x16x32_bf16 v[104:107], v[136:139], v[194:197], v[104:107]
	v_mfma_f32_16x16x32_bf16 v[92:95], v[128:131], v[202:205], v[92:95]
	v_mfma_f32_16x16x32_bf16 v[88:91], v[136:139], v[202:205], v[88:91]
	v_mfma_f32_16x16x32_bf16 v[76:79], v[128:131], v[210:213], v[76:79]
	v_mfma_f32_16x16x32_bf16 v[72:75], v[136:139], v[210:213], v[72:75]
	v_mfma_f32_16x16x32_bf16 v[124:127], v[132:135], v[190:193], v[124:127]
	v_mfma_f32_16x16x32_bf16 v[120:123], v[140:143], v[190:193], v[120:123]
	v_mfma_f32_16x16x32_bf16 v[108:111], v[132:135], v[198:201], v[108:111]
	v_mfma_f32_16x16x32_bf16 v[104:107], v[140:143], v[198:201], v[104:107]
	v_mfma_f32_16x16x32_bf16 v[92:95], v[132:135], v[206:209], v[92:95]
	v_mfma_f32_16x16x32_bf16 v[88:91], v[140:143], v[206:209], v[88:91]
	v_mfma_f32_16x16x32_bf16 v[76:79], v[132:135], v[214:217], v[76:79]
	v_mfma_f32_16x16x32_bf16 v[72:75], v[140:143], v[214:217], v[72:75]
	v_mfma_f32_16x16x32_bf16 v[116:119], v[160:163], v[186:189], v[116:119]
	v_mfma_f32_16x16x32_bf16 v[112:115], v[178:181], v[186:189], v[112:115]
	v_mfma_f32_16x16x32_bf16 v[100:103], v[160:163], v[194:197], v[100:103]
	v_mfma_f32_16x16x32_bf16 v[96:99], v[178:181], v[194:197], v[96:99]
	v_mfma_f32_16x16x32_bf16 v[84:87], v[160:163], v[202:205], v[84:87]
	v_mfma_f32_16x16x32_bf16 v[80:83], v[178:181], v[202:205], v[80:83]
	v_mfma_f32_16x16x32_bf16 v[68:71], v[160:163], v[210:213], v[68:71]
	v_mfma_f32_16x16x32_bf16 v[64:67], v[178:181], v[210:213], v[64:67]
	v_mfma_f32_16x16x32_bf16 v[116:119], v[164:167], v[190:193], v[116:119]
	v_mfma_f32_16x16x32_bf16 v[112:115], v[182:185], v[190:193], v[112:115]
	v_mfma_f32_16x16x32_bf16 v[100:103], v[164:167], v[198:201], v[100:103]
	v_mfma_f32_16x16x32_bf16 v[96:99], v[182:185], v[198:201], v[96:99]
	v_mfma_f32_16x16x32_bf16 v[84:87], v[164:167], v[206:209], v[84:87]
	v_mfma_f32_16x16x32_bf16 v[80:83], v[182:185], v[206:209], v[80:83]
	v_mfma_f32_16x16x32_bf16 v[68:71], v[164:167], v[214:217], v[68:71]
	v_mfma_f32_16x16x32_bf16 v[64:67], v[182:185], v[214:217], v[64:67]
	s_setprio 0
	s_barrier
	s_add_i32 s34, s80, s4
	v_lshl_add_u64 v[168:169], s[76:77], 0, v[146:147]
	s_mov_b32 m0, s34
	ds_read_b128 v[186:189], v175 offset:16384
	ds_read_b128 v[190:193], v175 offset:17408
	ds_read_b128 v[194:197], v175 offset:18432
	ds_read_b128 v[198:201], v175 offset:19456
	ds_read_b128 v[202:205], v175 offset:20480
	ds_read_b128 v[206:209], v175 offset:21504
	ds_read_b128 v[210:213], v175 offset:22528
	ds_read_b128 v[214:217], v175 offset:23552
	global_load_lds_dwordx4 v[168:169], off
	s_add_i32 m0, s34, 0x2000
	s_add_u32 s34, s76, 0xb0000
	v_lshl_add_u64 v[218:219], s[76:77], 0, v[150:151]
	s_addc_u32 s35, s77, 0
	s_add_i32 s72, s81, s4
	global_load_lds_dwordx4 v[218:219], off
	s_mov_b32 m0, s72
	v_lshl_add_u64 v[222:223], s[78:79], 0, v[148:149]
	global_load_lds_dwordx4 v146, s[34:35]
	s_add_i32 m0, s72, 0x2000
	s_nop 0
	global_load_lds_dwordx4 v150, s[34:35]
	v_lshl_add_u64 v[220:221], s[78:79], 0, v[144:145]
	s_mov_b32 m0, s5
	s_nop 0
	global_load_lds_dwordx4 v[220:221], off
	s_mov_b32 m0, s20
	s_nop 0
	global_load_lds_dwordx4 v[222:223], off
	s_waitcnt vmcnt(8)
	s_waitcnt lgkmcnt(0)
	s_barrier
	s_setprio 1
	s_waitcnt lgkmcnt(0)
	v_mfma_f32_16x16x32_bf16 v[60:63], v[128:131], v[186:189], v[60:63]
	v_mfma_f32_16x16x32_bf16 v[56:59], v[136:139], v[186:189], v[56:59]
	v_mfma_f32_16x16x32_bf16 v[44:47], v[128:131], v[194:197], v[44:47]
	v_mfma_f32_16x16x32_bf16 v[40:43], v[136:139], v[194:197], v[40:43]
	v_mfma_f32_16x16x32_bf16 v[28:31], v[128:131], v[202:205], v[28:31]
	v_mfma_f32_16x16x32_bf16 v[24:27], v[136:139], v[202:205], v[24:27]
	v_mfma_f32_16x16x32_bf16 v[12:15], v[128:131], v[210:213], v[12:15]
	v_mfma_f32_16x16x32_bf16 v[8:11], v[136:139], v[210:213], v[8:11]
	v_mfma_f32_16x16x32_bf16 v[60:63], v[132:135], v[190:193], v[60:63]
	v_mfma_f32_16x16x32_bf16 v[56:59], v[140:143], v[190:193], v[56:59]
	v_mfma_f32_16x16x32_bf16 v[44:47], v[132:135], v[198:201], v[44:47]
	v_mfma_f32_16x16x32_bf16 v[40:43], v[140:143], v[198:201], v[40:43]
	v_mfma_f32_16x16x32_bf16 v[28:31], v[132:135], v[206:209], v[28:31]
	v_mfma_f32_16x16x32_bf16 v[24:27], v[140:143], v[206:209], v[24:27]
	v_mfma_f32_16x16x32_bf16 v[12:15], v[132:135], v[214:217], v[12:15]
	v_mfma_f32_16x16x32_bf16 v[8:11], v[140:143], v[214:217], v[8:11]
	v_mfma_f32_16x16x32_bf16 v[52:55], v[160:163], v[186:189], v[52:55]
	v_mfma_f32_16x16x32_bf16 v[48:51], v[178:181], v[186:189], v[48:51]
	v_mfma_f32_16x16x32_bf16 v[36:39], v[160:163], v[194:197], v[36:39]
	v_mfma_f32_16x16x32_bf16 v[32:35], v[178:181], v[194:197], v[32:35]
	v_mfma_f32_16x16x32_bf16 v[20:23], v[160:163], v[202:205], v[20:23]
	v_mfma_f32_16x16x32_bf16 v[16:19], v[178:181], v[202:205], v[16:19]
	v_mfma_f32_16x16x32_bf16 v[4:7], v[160:163], v[210:213], v[4:7]
	v_mfma_f32_16x16x32_bf16 v[0:3], v[178:181], v[210:213], v[0:3]
	v_mfma_f32_16x16x32_bf16 v[52:55], v[164:167], v[190:193], v[52:55]
	v_mfma_f32_16x16x32_bf16 v[48:51], v[182:185], v[190:193], v[48:51]
	v_mfma_f32_16x16x32_bf16 v[36:39], v[164:167], v[198:201], v[36:39]
	v_mfma_f32_16x16x32_bf16 v[32:35], v[182:185], v[198:201], v[32:35]
	v_mfma_f32_16x16x32_bf16 v[20:23], v[164:167], v[206:209], v[20:23]
	v_mfma_f32_16x16x32_bf16 v[16:19], v[182:185], v[206:209], v[16:19]
	v_mfma_f32_16x16x32_bf16 v[4:7], v[164:167], v[214:217], v[4:7]
	v_mfma_f32_16x16x32_bf16 v[0:3], v[182:185], v[214:217], v[0:3]
	s_setprio 0
	s_barrier
; #define PG8_STAGE(bufoff, gbase, voff) do { _Pragma("unroll") for (int _i = 0; _i < 2; ++_i) \
;         __builtin_amdgcn_global_load_lds((const unsigned*)((const char*)(gbase) + (voff)[_i]), (LAS unsigned*)(lds + (bufoff) + ldsw + _i * 8192), 16, 0, 0); } while (0)
; #define PG8_LDA(dst, b, h) do { _Pragma("unroll") for (int m = 0; m < 4; ++m) _Pragma("unroll") for (int k = 0; k < 2; ++k) dst[m][k] = *(const LAS bf16x8*)(lds + PG8_SA(b, h) + aoff + m * 2048 + k * 1024); } while (0)
; #define PG8_LDB(dst, b, h) do { _Pragma("unroll") for (int n = 0; n < 2; ++n) _Pragma("unroll") for (int k = 0; k < 2; ++k) dst[n][k] = *(const LAS bf16x8*)(lds + PG8_SB(b, h) + boff + n * 2048 + k * 1024); } while (0)
; #define PG8_MMA(ai, bj, At, Bt) do { __builtin_amdgcn_s_setprio(1); _Pragma("unroll") for (int m = 0; m < 4; ++m) _Pragma("unroll") for (int n = 0; n < 2; ++n) _Pragma("unroll") for (int k = 0; k < 2; ++k) \
;         acc[ai][bj][m][n] = __builtin_amdgcn_mfma_f32_16x16x32_bf16(Bt[n][k], At[m][k], acc[ai][bj][m][n], 0, 0, 0); __builtin_amdgcn_s_setprio(0); } while (0)
; #define PG8_WAIT_V(n) asm volatile("s_waitcnt vmcnt(" #n ")" ::: "memory")
; #define PG8_WAIT_L(n) asm volatile("s_waitcnt lgkmcnt(" #n ")" ::: "memory")
; #define PG8_BAR __builtin_amdgcn_s_barrier()
; #define PG8_SCHED __builtin_amdgcn_sched_barrier(0)
; template <class Epi, class Sched, bool ALIGN_EPI = false, bool SP2 = false>
; __device__ __forceinline__ void gemm_phase(LAS unsigned char* lds, const Gemm g, const Sched S, const Epi E) {
;     ...
;             PG8_LDB(B0, 1, 0); PG8_LDB(B1, 1, 1); PG8_SCHED; PG8_LDA(At, 1, 0); PG8_STAGE(PG8_SA(0, 1), a2 + hstepA, voffA);
;             PG8_WAIT_V(8); PG8_WAIT_L(0); PG8_BAR; PG8_MMA(0, 0, At, B0); PG8_MMA(0, 1, At, B1); PG8_BAR; PG8_SCHED;
;             PG8_LDA(At, 1, 1); PG8_STAGE(PG8_SB(1, 0), b3, voffB); PG8_STAGE(PG8_SB(1, 1), b3 + hstepB, voffB); PG8_STAGE(PG8_SA(1, 0), a3, voffA);
;             PG8_WAIT_V(8); PG8_WAIT_L(0); PG8_BAR; PG8_MMA(1, 0, At, B0); PG8_MMA(1, 1, At, B1); PG8_BAR; PG8_SCHED;
	s_add_i32 s72, 0, 0x18000
	s_add_i32 s73, 0, 0x1c000
	v_add_u32_e32 v140, s72, v171
	v_add_u32_e32 v177, s73, v171
	ds_read_b128 v[128:131], v140
	ds_read_b128 v[132:135], v140 offset:1024
	ds_read_b128 v[136:139], v140 offset:2048
	ds_read_b128 v[140:143], v140 offset:3072
	ds_read_b128 v[160:163], v177
	ds_read_b128 v[164:167], v177 offset:1024
	ds_read_b128 v[178:181], v177 offset:2048
	ds_read_b128 v[182:185], v177 offset:3072
	s_add_u32 s34, s78, 0xb0000
	s_addc_u32 s35, s79, 0
	s_mov_b32 m0, s21
	ds_read_b128 v[186:189], v175 offset:32768
	ds_read_b128 v[190:193], v175 offset:33792
	ds_read_b128 v[194:197], v175 offset:34816
	ds_read_b128 v[198:201], v175 offset:35840
	ds_read_b128 v[202:205], v175 offset:36864
	ds_read_b128 v[206:209], v175 offset:37888
	ds_read_b128 v[210:213], v175 offset:38912
	ds_read_b128 v[214:217], v175 offset:39936
	global_load_lds_dwordx4 v144, s[34:35]
	s_mov_b32 m0, s29
	s_nop 0
	global_load_lds_dwordx4 v148, s[34:35]
	s_waitcnt vmcnt(8)
	s_waitcnt lgkmcnt(0)
	s_barrier
	s_setprio 1
	s_waitcnt lgkmcnt(0)
	v_mfma_f32_16x16x32_bf16 v[124:127], v[128:131], v[186:189], v[124:127]
	v_mfma_f32_16x16x32_bf16 v[120:123], v[136:139], v[186:189], v[120:123]
	v_mfma_f32_16x16x32_bf16 v[108:111], v[128:131], v[194:197], v[108:111]
	v_mfma_f32_16x16x32_bf16 v[104:107], v[136:139], v[194:197], v[104:107]
	v_mfma_f32_16x16x32_bf16 v[92:95], v[128:131], v[202:205], v[92:95]
	v_mfma_f32_16x16x32_bf16 v[88:91], v[136:139], v[202:205], v[88:91]
	v_mfma_f32_16x16x32_bf16 v[76:79], v[128:131], v[210:213], v[76:79]
	v_mfma_f32_16x16x32_bf16 v[72:75], v[136:139], v[210:213], v[72:75]
	v_mfma_f32_16x16x32_bf16 v[124:127], v[132:135], v[190:193], v[124:127]
	v_mfma_f32_16x16x32_bf16 v[120:123], v[140:143], v[190:193], v[120:123]
	v_mfma_f32_16x16x32_bf16 v[108:111], v[132:135], v[198:201], v[108:111]
	v_mfma_f32_16x16x32_bf16 v[104:107], v[140:143], v[198:201], v[104:107]
	v_mfma_f32_16x16x32_bf16 v[92:95], v[132:135], v[206:209], v[92:95]
	v_mfma_f32_16x16x32_bf16 v[88:91], v[140:143], v[206:209], v[88:91]
	v_mfma_f32_16x16x32_bf16 v[76:79], v[132:135], v[214:217], v[76:79]
	v_mfma_f32_16x16x32_bf16 v[72:75], v[140:143], v[214:217], v[72:75]
	v_mfma_f32_16x16x32_bf16 v[116:119], v[160:163], v[186:189], v[116:119]
	v_mfma_f32_16x16x32_bf16 v[112:115], v[178:181], v[186:189], v[112:115]
	v_mfma_f32_16x16x32_bf16 v[100:103], v[160:163], v[194:197], v[100:103]
	v_mfma_f32_16x16x32_bf16 v[96:99], v[178:181], v[194:197], v[96:99]
	v_mfma_f32_16x16x32_bf16 v[84:87], v[160:163], v[202:205], v[84:87]
	v_mfma_f32_16x16x32_bf16 v[80:83], v[178:181], v[202:205], v[80:83]
	v_mfma_f32_16x16x32_bf16 v[68:71], v[160:163], v[210:213], v[68:71]
	v_mfma_f32_16x16x32_bf16 v[64:67], v[178:181], v[210:213], v[64:67]
	v_mfma_f32_16x16x32_bf16 v[116:119], v[164:167], v[190:193], v[116:119]
	v_mfma_f32_16x16x32_bf16 v[112:115], v[182:185], v[190:193], v[112:115]
	v_mfma_f32_16x16x32_bf16 v[100:103], v[164:167], v[198:201], v[100:103]
	v_mfma_f32_16x16x32_bf16 v[96:99], v[182:185], v[198:201], v[96:99]
	v_mfma_f32_16x16x32_bf16 v[84:87], v[164:167], v[206:209], v[84:87]
	v_mfma_f32_16x16x32_bf16 v[80:83], v[182:185], v[206:209], v[80:83]
	v_mfma_f32_16x16x32_bf16 v[68:71], v[164:167], v[214:217], v[68:71]
	v_mfma_f32_16x16x32_bf16 v[64:67], v[182:185], v[214:217], v[64:67]
	s_setprio 0
	s_barrier
	s_add_i32 s34, s72, s4
	v_lshl_add_u64 v[168:169], v[168:169], 0, s[60:61]
	s_mov_b32 m0, s34
	ds_read_b128 v[186:189], v175 offset:49152
	ds_read_b128 v[190:193], v175 offset:50176
	ds_read_b128 v[194:197], v175 offset:51200
	ds_read_b128 v[198:201], v175 offset:52224
	ds_read_b128 v[202:205], v175 offset:53248
	ds_read_b128 v[206:209], v175 offset:54272
	ds_read_b128 v[210:213], v175 offset:55296
	ds_read_b128 v[214:217], v175 offset:56320
	global_load_lds_dwordx4 v[168:169], off
	s_add_i32 m0, s34, 0x2000
	s_add_u32 s34, s76, 0xb0080
	v_lshl_add_u64 v[168:169], v[218:219], 0, s[60:61]
	s_addc_u32 s35, s77, 0
	s_add_i32 s72, s73, s4
	global_load_lds_dwordx4 v[168:169], off
	s_mov_b32 m0, s72
	s_nop 0
	global_load_lds_dwordx4 v146, s[34:35]
	s_add_i32 m0, s72, 0x2000
	s_nop 0
	global_load_lds_dwordx4 v150, s[34:35]
	v_lshl_add_u64 v[168:169], v[220:221], 0, s[60:61]
	s_mov_b32 m0, s31
	s_nop 0
	global_load_lds_dwordx4 v[168:169], off
	v_lshl_add_u64 v[168:169], v[222:223], 0, s[60:61]
	s_mov_b32 m0, s33
	s_nop 0
	global_load_lds_dwordx4 v[168:169], off
	s_waitcnt vmcnt(8)
	s_waitcnt lgkmcnt(0)
	s_barrier
	s_setprio 1
	s_waitcnt lgkmcnt(0)
	v_mfma_f32_16x16x32_bf16 v[60:63], v[128:131], v[186:189], v[60:63]
	v_mfma_f32_16x16x32_bf16 v[56:59], v[136:139], v[186:189], v[56:59]
	v_mfma_f32_16x16x32_bf16 v[44:47], v[128:131], v[194:197], v[44:47]
	v_mfma_f32_16x16x32_bf16 v[40:43], v[136:139], v[194:197], v[40:43]
	v_mfma_f32_16x16x32_bf16 v[28:31], v[128:131], v[202:205], v[28:31]
	v_mfma_f32_16x16x32_bf16 v[24:27], v[136:139], v[202:205], v[24:27]
	v_mfma_f32_16x16x32_bf16 v[12:15], v[128:131], v[210:213], v[12:15]
	v_mfma_f32_16x16x32_bf16 v[8:11], v[136:139], v[210:213], v[8:11]
	v_mfma_f32_16x16x32_bf16 v[60:63], v[132:135], v[190:193], v[60:63]
	v_mfma_f32_16x16x32_bf16 v[56:59], v[140:143], v[190:193], v[56:59]
	v_mfma_f32_16x16x32_bf16 v[44:47], v[132:135], v[198:201], v[44:47]
	v_mfma_f32_16x16x32_bf16 v[40:43], v[140:143], v[198:201], v[40:43]
	v_mfma_f32_16x16x32_bf16 v[28:31], v[132:135], v[206:209], v[28:31]
	v_mfma_f32_16x16x32_bf16 v[24:27], v[140:143], v[206:209], v[24:27]
	v_mfma_f32_16x16x32_bf16 v[12:15], v[132:135], v[214:217], v[12:15]
	v_mfma_f32_16x16x32_bf16 v[8:11], v[140:143], v[214:217], v[8:11]
	v_mfma_f32_16x16x32_bf16 v[52:55], v[160:163], v[186:189], v[52:55]
	v_mfma_f32_16x16x32_bf16 v[48:51], v[178:181], v[186:189], v[48:51]
	v_mfma_f32_16x16x32_bf16 v[36:39], v[160:163], v[194:197], v[36:39]
	v_mfma_f32_16x16x32_bf16 v[32:35], v[178:181], v[194:197], v[32:35]
	v_mfma_f32_16x16x32_bf16 v[20:23], v[160:163], v[202:205], v[20:23]
	v_mfma_f32_16x16x32_bf16 v[16:19], v[178:181], v[202:205], v[16:19]
	v_mfma_f32_16x16x32_bf16 v[4:7], v[160:163], v[210:213], v[4:7]
	v_mfma_f32_16x16x32_bf16 v[0:3], v[178:181], v[210:213], v[0:3]
	v_mfma_f32_16x16x32_bf16 v[52:55], v[164:167], v[190:193], v[52:55]
	v_mfma_f32_16x16x32_bf16 v[48:51], v[182:185], v[190:193], v[48:51]
	v_mfma_f32_16x16x32_bf16 v[36:39], v[164:167], v[198:201], v[36:39]
	v_mfma_f32_16x16x32_bf16 v[32:35], v[182:185], v[198:201], v[32:35]
	v_mfma_f32_16x16x32_bf16 v[20:23], v[164:167], v[206:209], v[20:23]
	v_mfma_f32_16x16x32_bf16 v[16:19], v[182:185], v[206:209], v[16:19]
	v_mfma_f32_16x16x32_bf16 v[4:7], v[164:167], v[214:217], v[4:7]
	v_mfma_f32_16x16x32_bf16 v[0:3], v[182:185], v[214:217], v[0:3]
	s_setprio 0
	s_add_i32 s88, s88, 2
	s_add_u32 s86, s86, 0x100
	s_addc_u32 s87, s87, 0
	s_cmp_gt_u32 s88, 41
	s_mov_b64 s[72:73], s[74:75]
	s_barrier
	s_cbranch_scc0 .LBB0_705
	s_and_b64 vcc, exec, s[62:63]
	s_cbranch_vccz .LBB0_708
	s_barrier

; #define PG8_STAGE(bufoff, gbase, voff) do { _Pragma("unroll") for (int _i = 0; _i < 2; ++_i) \
;         __builtin_amdgcn_global_load_lds((const unsigned*)((const char*)(gbase) + (voff)[_i]), (LAS unsigned*)(lds + (bufoff) + ldsw + _i * 8192), 16, 0, 0); } while (0)
; #define PG8_LDA(dst, b, h) do { _Pragma("unroll") for (int m = 0; m < 4; ++m) _Pragma("unroll") for (int k = 0; k < 2; ++k) dst[m][k] = *(const LAS bf16x8*)(lds + PG8_SA(b, h) + aoff + m * 2048 + k * 1024); } while (0)
; #define PG8_LDB(dst, b, h) do { _Pragma("unroll") for (int n = 0; n < 2; ++n) _Pragma("unroll") for (int k = 0; k < 2; ++k) dst[n][k] = *(const LAS bf16x8*)(lds + PG8_SB(b, h) + boff + n * 2048 + k * 1024); } while (0)
; #define PG8_MMA(ai, bj, At, Bt) do { __builtin_amdgcn_s_setprio(1); _Pragma("unroll") for (int m = 0; m < 4; ++m) _Pragma("unroll") for (int n = 0; n < 2; ++n) _Pragma("unroll") for (int k = 0; k < 2; ++k) \
;         acc[ai][bj][m][n] = __builtin_amdgcn_mfma_f32_16x16x32_bf16(Bt[n][k], At[m][k], acc[ai][bj][m][n], 0, 0, 0); __builtin_amdgcn_s_setprio(0); } while (0)
; #define PG8_WAIT_V(n) asm volatile("s_waitcnt vmcnt(" #n ")" ::: "memory")
; #define PG8_WAIT_L(n) asm volatile("s_waitcnt lgkmcnt(" #n ")" ::: "memory")
; #define PG8_BAR __builtin_amdgcn_s_barrier()
; #define PG8_SCHED __builtin_amdgcn_sched_barrier(0)
; template <class Epi, class Sched, bool ALIGN_EPI = false, bool SP2 = false>
; __device__ __forceinline__ void gemm_phase(LAS unsigned char* lds, const Gemm g, const Sched S, const Epi E) {
;     ...
;             PG8_LDB(B0, 0, 0); PG8_LDB(B1, 0, 1); PG8_SCHED; PG8_LDA(At, 0, 0); PG8_STAGE(PG8_SA(1, 1), a1 + hstepA, voffA);
;             PG8_WAIT_V(8); PG8_WAIT_L(0); PG8_BAR; PG8_MMA(0, 0, At, B0); PG8_MMA(0, 1, At, B1); PG8_BAR; PG8_SCHED;
;             PG8_LDA(At, 0, 1); PG8_STAGE(PG8_SB(0, 0), b2, voffB); PG8_STAGE(PG8_SB(0, 1), b2 + hstepB, voffB); PG8_STAGE(PG8_SA(0, 0), a2, voffA);
;             PG8_WAIT_V(8); PG8_WAIT_L(0); PG8_BAR; PG8_MMA(1, 0, At, B0); PG8_MMA(1, 1, At, B1); PG8_BAR; PG8_SCHED;
.LBB0_791:
	ds_read_b128 v[146:149], v153
	ds_read_b128 v[158:161], v153 offset:1024
	ds_read_b128 v[162:165], v153 offset:2048
	ds_read_b128 v[166:169], v153 offset:3072
	ds_read_b128 v[170:173], v154
	ds_read_b128 v[174:177], v154 offset:1024
	ds_read_b128 v[178:181], v154 offset:2048
	ds_read_b128 v[182:185], v154 offset:3072
	s_add_u32 s34, s72, 0xfff80080
	s_addc_u32 s35, s73, -1
	s_cmp_eq_u32 s88, 12
	s_cselect_b32 s77, s11, s35
	s_cselect_b32 s76, s63, s34
	s_cselect_b32 s75, s61, s87
	s_cselect_b32 s74, s71, s86
	s_add_i32 m0, s5, 0xc000
	ds_read_b128 v[186:189], v155
	ds_read_b128 v[190:193], v155 offset:1024
	ds_read_b128 v[194:197], v155 offset:2048
	ds_read_b128 v[198:201], v155 offset:3072
	ds_read_b128 v[202:205], v155 offset:4096
	ds_read_b128 v[206:209], v155 offset:5120
	ds_read_b128 v[210:213], v155 offset:6144
	ds_read_b128 v[214:217], v155 offset:7168
	global_load_lds_dwordx4 v138, s[72:73]
	s_add_i32 m0, s5, 0xe000
	s_nop 0
	global_load_lds_dwordx4 v140, s[72:73]
	s_waitcnt vmcnt(8)
	s_waitcnt lgkmcnt(0)
	s_barrier
	s_setprio 1
	s_waitcnt lgkmcnt(0)
	v_mfma_f32_16x16x32_bf16 v[124:127], v[146:149], v[186:189], v[124:127]
	v_mfma_f32_16x16x32_bf16 v[120:123], v[162:165], v[186:189], v[120:123]
	v_mfma_f32_16x16x32_bf16 v[108:111], v[146:149], v[194:197], v[108:111]
	v_mfma_f32_16x16x32_bf16 v[104:107], v[162:165], v[194:197], v[104:107]
	v_mfma_f32_16x16x32_bf16 v[92:95], v[146:149], v[202:205], v[92:95]
	v_mfma_f32_16x16x32_bf16 v[88:91], v[162:165], v[202:205], v[88:91]
	v_mfma_f32_16x16x32_bf16 v[76:79], v[146:149], v[210:213], v[76:79]
	v_mfma_f32_16x16x32_bf16 v[72:75], v[162:165], v[210:213], v[72:75]
	v_mfma_f32_16x16x32_bf16 v[124:127], v[158:161], v[190:193], v[124:127]
	v_mfma_f32_16x16x32_bf16 v[120:123], v[166:169], v[190:193], v[120:123]
	v_mfma_f32_16x16x32_bf16 v[108:111], v[158:161], v[198:201], v[108:111]
	v_mfma_f32_16x16x32_bf16 v[104:107], v[166:169], v[198:201], v[104:107]
	v_mfma_f32_16x16x32_bf16 v[92:95], v[158:161], v[206:209], v[92:95]
	v_mfma_f32_16x16x32_bf16 v[88:91], v[166:169], v[206:209], v[88:91]
	v_mfma_f32_16x16x32_bf16 v[76:79], v[158:161], v[214:217], v[76:79]
	v_mfma_f32_16x16x32_bf16 v[72:75], v[166:169], v[214:217], v[72:75]
	v_mfma_f32_16x16x32_bf16 v[116:119], v[170:173], v[186:189], v[116:119]
	v_mfma_f32_16x16x32_bf16 v[112:115], v[178:181], v[186:189], v[112:115]
	v_mfma_f32_16x16x32_bf16 v[100:103], v[170:173], v[194:197], v[100:103]
	v_mfma_f32_16x16x32_bf16 v[96:99], v[178:181], v[194:197], v[96:99]
	v_mfma_f32_16x16x32_bf16 v[84:87], v[170:173], v[202:205], v[84:87]
	v_mfma_f32_16x16x32_bf16 v[80:83], v[178:181], v[202:205], v[80:83]
	v_mfma_f32_16x16x32_bf16 v[68:71], v[170:173], v[210:213], v[68:71]
	v_mfma_f32_16x16x32_bf16 v[64:67], v[178:181], v[210:213], v[64:67]
	v_mfma_f32_16x16x32_bf16 v[116:119], v[174:177], v[190:193], v[116:119]
	v_mfma_f32_16x16x32_bf16 v[112:115], v[182:185], v[190:193], v[112:115]
	v_mfma_f32_16x16x32_bf16 v[100:103], v[174:177], v[198:201], v[100:103]
	v_mfma_f32_16x16x32_bf16 v[96:99], v[182:185], v[198:201], v[96:99]
	v_mfma_f32_16x16x32_bf16 v[84:87], v[174:177], v[206:209], v[84:87]
	v_mfma_f32_16x16x32_bf16 v[80:83], v[182:185], v[206:209], v[80:83]
	v_mfma_f32_16x16x32_bf16 v[68:71], v[174:177], v[214:217], v[68:71]
	v_mfma_f32_16x16x32_bf16 v[64:67], v[182:185], v[214:217], v[64:67]
	s_setprio 0
	s_barrier
	s_add_i32 s34, s80, s4
	v_lshl_add_u64 v[218:219], s[74:75], 0, v[130:131]
	s_mov_b32 m0, s34
	ds_read_b128 v[186:189], v155 offset:16384
	ds_read_b128 v[190:193], v155 offset:17408
	ds_read_b128 v[194:197], v155 offset:18432
	ds_read_b128 v[198:201], v155 offset:19456
	ds_read_b128 v[202:205], v155 offset:20480
	ds_read_b128 v[206:209], v155 offset:21504
	ds_read_b128 v[210:213], v155 offset:22528
	ds_read_b128 v[214:217], v155 offset:23552
	global_load_lds_dwordx4 v[218:219], off
	s_add_i32 m0, s34, 0x2000
	s_add_u32 s34, s74, 0x40000
	v_lshl_add_u64 v[220:221], s[74:75], 0, v[134:135]
	s_addc_u32 s35, s75, 0
	s_add_i32 s89, s81, s4
	global_load_lds_dwordx4 v[220:221], off
	s_mov_b32 m0, s89
	v_lshl_add_u64 v[224:225], s[76:77], 0, v[132:133]
	global_load_lds_dwordx4 v130, s[34:35]
	s_add_i32 m0, s89, 0x2000
	s_nop 0
	global_load_lds_dwordx4 v134, s[34:35]
	v_lshl_add_u64 v[222:223], s[76:77], 0, v[128:129]
	s_mov_b32 m0, s5
	s_nop 0
	global_load_lds_dwordx4 v[222:223], off
	s_mov_b32 m0, s20
	s_nop 0
	global_load_lds_dwordx4 v[224:225], off
	s_waitcnt vmcnt(8)
	s_waitcnt lgkmcnt(0)
	s_barrier
	s_setprio 1
	s_waitcnt lgkmcnt(0)
	v_mfma_f32_16x16x32_bf16 v[60:63], v[146:149], v[186:189], v[60:63]
	v_mfma_f32_16x16x32_bf16 v[56:59], v[162:165], v[186:189], v[56:59]
	v_mfma_f32_16x16x32_bf16 v[44:47], v[146:149], v[194:197], v[44:47]
	v_mfma_f32_16x16x32_bf16 v[40:43], v[162:165], v[194:197], v[40:43]
	v_mfma_f32_16x16x32_bf16 v[28:31], v[146:149], v[202:205], v[28:31]
	v_mfma_f32_16x16x32_bf16 v[24:27], v[162:165], v[202:205], v[24:27]
	v_mfma_f32_16x16x32_bf16 v[12:15], v[146:149], v[210:213], v[12:15]
	v_mfma_f32_16x16x32_bf16 v[8:11], v[162:165], v[210:213], v[8:11]
	v_mfma_f32_16x16x32_bf16 v[60:63], v[158:161], v[190:193], v[60:63]
	v_mfma_f32_16x16x32_bf16 v[56:59], v[166:169], v[190:193], v[56:59]
	v_mfma_f32_16x16x32_bf16 v[44:47], v[158:161], v[198:201], v[44:47]
	v_mfma_f32_16x16x32_bf16 v[40:43], v[166:169], v[198:201], v[40:43]
	v_mfma_f32_16x16x32_bf16 v[28:31], v[158:161], v[206:209], v[28:31]
	v_mfma_f32_16x16x32_bf16 v[24:27], v[166:169], v[206:209], v[24:27]
	v_mfma_f32_16x16x32_bf16 v[12:15], v[158:161], v[214:217], v[12:15]
	v_mfma_f32_16x16x32_bf16 v[8:11], v[166:169], v[214:217], v[8:11]
	v_mfma_f32_16x16x32_bf16 v[52:55], v[170:173], v[186:189], v[52:55]
	v_mfma_f32_16x16x32_bf16 v[48:51], v[178:181], v[186:189], v[48:51]
	v_mfma_f32_16x16x32_bf16 v[36:39], v[170:173], v[194:197], v[36:39]
	v_mfma_f32_16x16x32_bf16 v[32:35], v[178:181], v[194:197], v[32:35]
	v_mfma_f32_16x16x32_bf16 v[20:23], v[170:173], v[202:205], v[20:23]
	v_mfma_f32_16x16x32_bf16 v[16:19], v[178:181], v[202:205], v[16:19]
	v_mfma_f32_16x16x32_bf16 v[4:7], v[170:173], v[210:213], v[4:7]
	v_mfma_f32_16x16x32_bf16 v[0:3], v[178:181], v[210:213], v[0:3]
	v_mfma_f32_16x16x32_bf16 v[52:55], v[174:177], v[190:193], v[52:55]
	v_mfma_f32_16x16x32_bf16 v[48:51], v[182:185], v[190:193], v[48:51]
	v_mfma_f32_16x16x32_bf16 v[36:39], v[174:177], v[198:201], v[36:39]
	v_mfma_f32_16x16x32_bf16 v[32:35], v[182:185], v[198:201], v[32:35]
	v_mfma_f32_16x16x32_bf16 v[20:23], v[174:177], v[206:209], v[20:23]
	v_mfma_f32_16x16x32_bf16 v[16:19], v[182:185], v[206:209], v[16:19]
	v_mfma_f32_16x16x32_bf16 v[4:7], v[174:177], v[214:217], v[4:7]
	v_mfma_f32_16x16x32_bf16 v[0:3], v[182:185], v[214:217], v[0:3]
	s_setprio 0
	s_barrier
; #define PG8_STAGE(bufoff, gbase, voff) do { _Pragma("unroll") for (int _i = 0; _i < 2; ++_i) \
;         __builtin_amdgcn_global_load_lds((const unsigned*)((const char*)(gbase) + (voff)[_i]), (LAS unsigned*)(lds + (bufoff) + ldsw + _i * 8192), 16, 0, 0); } while (0)
; #define PG8_LDA(dst, b, h) do { _Pragma("unroll") for (int m = 0; m < 4; ++m) _Pragma("unroll") for (int k = 0; k < 2; ++k) dst[m][k] = *(const LAS bf16x8*)(lds + PG8_SA(b, h) + aoff + m * 2048 + k * 1024); } while (0)
; #define PG8_LDB(dst, b, h) do { _Pragma("unroll") for (int n = 0; n < 2; ++n) _Pragma("unroll") for (int k = 0; k < 2; ++k) dst[n][k] = *(const LAS bf16x8*)(lds + PG8_SB(b, h) + boff + n * 2048 + k * 1024); } while (0)
; #define PG8_MMA(ai, bj, At, Bt) do { __builtin_amdgcn_s_setprio(1); _Pragma("unroll") for (int m = 0; m < 4; ++m) _Pragma("unroll") for (int n = 0; n < 2; ++n) _Pragma("unroll") for (int k = 0; k < 2; ++k) \
;         acc[ai][bj][m][n] = __builtin_amdgcn_mfma_f32_16x16x32_bf16(Bt[n][k], At[m][k], acc[ai][bj][m][n], 0, 0, 0); __builtin_amdgcn_s_setprio(0); } while (0)
; #define PG8_WAIT_V(n) asm volatile("s_waitcnt vmcnt(" #n ")" ::: "memory")
; #define PG8_WAIT_L(n) asm volatile("s_waitcnt lgkmcnt(" #n ")" ::: "memory")
; #define PG8_BAR __builtin_amdgcn_s_barrier()
; #define PG8_SCHED __builtin_amdgcn_sched_barrier(0)
; template <class Epi, class Sched, bool ALIGN_EPI = false, bool SP2 = false>
; __device__ __forceinline__ void gemm_phase(LAS unsigned char* lds, const Gemm g, const Sched S, const Epi E) {
;     ...
;             PG8_LDB(B0, 1, 0); PG8_LDB(B1, 1, 1); PG8_SCHED; PG8_LDA(At, 1, 0); PG8_STAGE(PG8_SA(0, 1), a2 + hstepA, voffA);
;             PG8_WAIT_V(8); PG8_WAIT_L(0); PG8_BAR; PG8_MMA(0, 0, At, B0); PG8_MMA(0, 1, At, B1); PG8_BAR; PG8_SCHED;
;             PG8_LDA(At, 1, 1); PG8_STAGE(PG8_SB(1, 0), b3, voffB); PG8_STAGE(PG8_SB(1, 1), b3 + hstepB, voffB); PG8_STAGE(PG8_SA(1, 0), a3, voffA);
;             PG8_WAIT_V(8); PG8_WAIT_L(0); PG8_BAR; PG8_MMA(1, 0, At, B0); PG8_MMA(1, 1, At, B1); PG8_BAR; PG8_SCHED;
	s_add_i32 s89, 0, 0x18000
	s_add_i32 s90, 0, 0x1c000
	v_add_u32_e32 v166, s89, v151
	v_add_u32_e32 v182, s90, v151
	ds_read_b128 v[146:149], v166
	ds_read_b128 v[158:161], v166 offset:1024
	ds_read_b128 v[162:165], v166 offset:2048
	ds_read_b128 v[166:169], v166 offset:3072
	ds_read_b128 v[170:173], v182
	ds_read_b128 v[174:177], v182 offset:1024
	ds_read_b128 v[178:181], v182 offset:2048
	ds_read_b128 v[182:185], v182 offset:3072
	s_add_u32 s34, s76, 0x80000
	s_addc_u32 s35, s77, 0
	s_mov_b32 m0, s21
	ds_read_b128 v[186:189], v155 offset:32768
	ds_read_b128 v[190:193], v155 offset:33792
	ds_read_b128 v[194:197], v155 offset:34816
	ds_read_b128 v[198:201], v155 offset:35840
	ds_read_b128 v[202:205], v155 offset:36864
	ds_read_b128 v[206:209], v155 offset:37888
	ds_read_b128 v[210:213], v155 offset:38912
	ds_read_b128 v[214:217], v155 offset:39936
	global_load_lds_dwordx4 v128, s[34:35]
	s_mov_b32 m0, s29
	s_nop 0
	global_load_lds_dwordx4 v132, s[34:35]
	s_waitcnt vmcnt(8)
	s_waitcnt lgkmcnt(0)
	s_barrier
	s_setprio 1
	s_waitcnt lgkmcnt(0)
	v_mfma_f32_16x16x32_bf16 v[124:127], v[146:149], v[186:189], v[124:127]
	v_mfma_f32_16x16x32_bf16 v[120:123], v[162:165], v[186:189], v[120:123]
	v_mfma_f32_16x16x32_bf16 v[108:111], v[146:149], v[194:197], v[108:111]
	v_mfma_f32_16x16x32_bf16 v[104:107], v[162:165], v[194:197], v[104:107]
	v_mfma_f32_16x16x32_bf16 v[92:95], v[146:149], v[202:205], v[92:95]
	v_mfma_f32_16x16x32_bf16 v[88:91], v[162:165], v[202:205], v[88:91]
	v_mfma_f32_16x16x32_bf16 v[76:79], v[146:149], v[210:213], v[76:79]
	v_mfma_f32_16x16x32_bf16 v[72:75], v[162:165], v[210:213], v[72:75]
	v_mfma_f32_16x16x32_bf16 v[124:127], v[158:161], v[190:193], v[124:127]
	v_mfma_f32_16x16x32_bf16 v[120:123], v[166:169], v[190:193], v[120:123]
	v_mfma_f32_16x16x32_bf16 v[108:111], v[158:161], v[198:201], v[108:111]
	v_mfma_f32_16x16x32_bf16 v[104:107], v[166:169], v[198:201], v[104:107]
	v_mfma_f32_16x16x32_bf16 v[92:95], v[158:161], v[206:209], v[92:95]
	v_mfma_f32_16x16x32_bf16 v[88:91], v[166:169], v[206:209], v[88:91]
	v_mfma_f32_16x16x32_bf16 v[76:79], v[158:161], v[214:217], v[76:79]
	v_mfma_f32_16x16x32_bf16 v[72:75], v[166:169], v[214:217], v[72:75]
	v_mfma_f32_16x16x32_bf16 v[116:119], v[170:173], v[186:189], v[116:119]
	v_mfma_f32_16x16x32_bf16 v[112:115], v[178:181], v[186:189], v[112:115]
	v_mfma_f32_16x16x32_bf16 v[100:103], v[170:173], v[194:197], v[100:103]
	v_mfma_f32_16x16x32_bf16 v[96:99], v[178:181], v[194:197], v[96:99]
	v_mfma_f32_16x16x32_bf16 v[84:87], v[170:173], v[202:205], v[84:87]
	v_mfma_f32_16x16x32_bf16 v[80:83], v[178:181], v[202:205], v[80:83]
	v_mfma_f32_16x16x32_bf16 v[68:71], v[170:173], v[210:213], v[68:71]
	v_mfma_f32_16x16x32_bf16 v[64:67], v[178:181], v[210:213], v[64:67]
	v_mfma_f32_16x16x32_bf16 v[116:119], v[174:177], v[190:193], v[116:119]
	v_mfma_f32_16x16x32_bf16 v[112:115], v[182:185], v[190:193], v[112:115]
	v_mfma_f32_16x16x32_bf16 v[100:103], v[174:177], v[198:201], v[100:103]
	v_mfma_f32_16x16x32_bf16 v[96:99], v[182:185], v[198:201], v[96:99]
	v_mfma_f32_16x16x32_bf16 v[84:87], v[174:177], v[206:209], v[84:87]
	v_mfma_f32_16x16x32_bf16 v[80:83], v[182:185], v[206:209], v[80:83]
	v_mfma_f32_16x16x32_bf16 v[68:71], v[174:177], v[214:217], v[68:71]
	v_mfma_f32_16x16x32_bf16 v[64:67], v[182:185], v[214:217], v[64:67]
	s_setprio 0
	s_barrier
	s_add_i32 s34, s89, s4
	v_lshl_add_u64 v[218:219], v[218:219], 0, s[14:15]
	s_mov_b32 m0, s34
	ds_read_b128 v[186:189], v155 offset:49152
	ds_read_b128 v[190:193], v155 offset:50176
	ds_read_b128 v[194:197], v155 offset:51200
	ds_read_b128 v[198:201], v155 offset:52224
	ds_read_b128 v[202:205], v155 offset:53248
	ds_read_b128 v[206:209], v155 offset:54272
	ds_read_b128 v[210:213], v155 offset:55296
	ds_read_b128 v[214:217], v155 offset:56320
	global_load_lds_dwordx4 v[218:219], off
	s_add_i32 m0, s34, 0x2000
	s_add_u32 s34, s74, 0x40080
	v_lshl_add_u64 v[218:219], v[220:221], 0, s[14:15]
	s_addc_u32 s35, s75, 0
	s_add_i32 s74, s90, s4
	global_load_lds_dwordx4 v[218:219], off
	s_mov_b32 m0, s74
	s_nop 0
	global_load_lds_dwordx4 v130, s[34:35]
	s_add_i32 m0, s74, 0x2000
	s_nop 0
	global_load_lds_dwordx4 v134, s[34:35]
	v_lshl_add_u64 v[218:219], v[222:223], 0, s[14:15]
	s_mov_b32 m0, s33
	s_nop 0
	global_load_lds_dwordx4 v[218:219], off
	v_lshl_add_u64 v[218:219], v[224:225], 0, s[14:15]
	s_mov_b32 m0, s44
	s_nop 0
	global_load_lds_dwordx4 v[218:219], off
	s_waitcnt vmcnt(8)
	s_waitcnt lgkmcnt(0)
	s_barrier
	s_setprio 1
	s_waitcnt lgkmcnt(0)
	v_mfma_f32_16x16x32_bf16 v[60:63], v[146:149], v[186:189], v[60:63]
	v_mfma_f32_16x16x32_bf16 v[56:59], v[162:165], v[186:189], v[56:59]
	v_mfma_f32_16x16x32_bf16 v[44:47], v[146:149], v[194:197], v[44:47]
	v_mfma_f32_16x16x32_bf16 v[40:43], v[162:165], v[194:197], v[40:43]
	v_mfma_f32_16x16x32_bf16 v[28:31], v[146:149], v[202:205], v[28:31]
	v_mfma_f32_16x16x32_bf16 v[24:27], v[162:165], v[202:205], v[24:27]
	v_mfma_f32_16x16x32_bf16 v[12:15], v[146:149], v[210:213], v[12:15]
	v_mfma_f32_16x16x32_bf16 v[8:11], v[162:165], v[210:213], v[8:11]
	v_mfma_f32_16x16x32_bf16 v[60:63], v[158:161], v[190:193], v[60:63]
	v_mfma_f32_16x16x32_bf16 v[56:59], v[166:169], v[190:193], v[56:59]
	v_mfma_f32_16x16x32_bf16 v[44:47], v[158:161], v[198:201], v[44:47]
	v_mfma_f32_16x16x32_bf16 v[40:43], v[166:169], v[198:201], v[40:43]
	v_mfma_f32_16x16x32_bf16 v[28:31], v[158:161], v[206:209], v[28:31]
	v_mfma_f32_16x16x32_bf16 v[24:27], v[166:169], v[206:209], v[24:27]
	v_mfma_f32_16x16x32_bf16 v[12:15], v[158:161], v[214:217], v[12:15]
	v_mfma_f32_16x16x32_bf16 v[8:11], v[166:169], v[214:217], v[8:11]
	v_mfma_f32_16x16x32_bf16 v[52:55], v[170:173], v[186:189], v[52:55]
	v_mfma_f32_16x16x32_bf16 v[48:51], v[178:181], v[186:189], v[48:51]
	v_mfma_f32_16x16x32_bf16 v[36:39], v[170:173], v[194:197], v[36:39]
	v_mfma_f32_16x16x32_bf16 v[32:35], v[178:181], v[194:197], v[32:35]
	v_mfma_f32_16x16x32_bf16 v[20:23], v[170:173], v[202:205], v[20:23]
	v_mfma_f32_16x16x32_bf16 v[16:19], v[178:181], v[202:205], v[16:19]
	v_mfma_f32_16x16x32_bf16 v[4:7], v[170:173], v[210:213], v[4:7]
	v_mfma_f32_16x16x32_bf16 v[0:3], v[178:181], v[210:213], v[0:3]
	v_mfma_f32_16x16x32_bf16 v[52:55], v[174:177], v[190:193], v[52:55]
	v_mfma_f32_16x16x32_bf16 v[48:51], v[182:185], v[190:193], v[48:51]
	v_mfma_f32_16x16x32_bf16 v[36:39], v[174:177], v[198:201], v[36:39]
	v_mfma_f32_16x16x32_bf16 v[32:35], v[182:185], v[198:201], v[32:35]
	v_mfma_f32_16x16x32_bf16 v[20:23], v[174:177], v[206:209], v[20:23]
	v_mfma_f32_16x16x32_bf16 v[16:19], v[182:185], v[206:209], v[16:19]
	v_mfma_f32_16x16x32_bf16 v[4:7], v[174:177], v[214:217], v[4:7]
	v_mfma_f32_16x16x32_bf16 v[0:3], v[182:185], v[214:217], v[0:3]
	s_setprio 0
	s_add_i32 s88, s88, 2
	s_add_u32 s72, s72, 0x100
	s_addc_u32 s73, s73, 0
	s_add_u32 s86, s86, 0x100
	s_addc_u32 s87, s87, 0
	s_cmp_gt_u32 s88, 13
	s_barrier
	s_cbranch_scc0 .LBB0_791
	s_and_b64 vcc, exec, s[50:51]
	s_cbranch_vccz .LBB0_794
	s_barrier

; #define PG8_STAGE(bufoff, gbase, voff) do { _Pragma("unroll") for (int _i = 0; _i < 2; ++_i) \
;         __builtin_amdgcn_global_load_lds((const unsigned*)((const char*)(gbase) + (voff)[_i]), (LAS unsigned*)(lds + (bufoff) + ldsw + _i * 8192), 16, 0, 0); } while (0)
; #define PG8_LDA(dst, b, h) do { _Pragma("unroll") for (int m = 0; m < 4; ++m) _Pragma("unroll") for (int k = 0; k < 2; ++k) dst[m][k] = *(const LAS bf16x8*)(lds + PG8_SA(b, h) + aoff + m * 2048 + k * 1024); } while (0)
; #define PG8_LDB(dst, b, h) do { _Pragma("unroll") for (int n = 0; n < 2; ++n) _Pragma("unroll") for (int k = 0; k < 2; ++k) dst[n][k] = *(const LAS bf16x8*)(lds + PG8_SB(b, h) + boff + n * 2048 + k * 1024); } while (0)
; #define PG8_MMA(ai, bj, At, Bt) do { __builtin_amdgcn_s_setprio(1); _Pragma("unroll") for (int m = 0; m < 4; ++m) _Pragma("unroll") for (int n = 0; n < 2; ++n) _Pragma("unroll") for (int k = 0; k < 2; ++k) \
;         acc[ai][bj][m][n] = __builtin_amdgcn_mfma_f32_16x16x32_bf16(Bt[n][k], At[m][k], acc[ai][bj][m][n], 0, 0, 0); __builtin_amdgcn_s_setprio(0); } while (0)
; #define PG8_WAIT_V(n) asm volatile("s_waitcnt vmcnt(" #n ")" ::: "memory")
; #define PG8_WAIT_L(n) asm volatile("s_waitcnt lgkmcnt(" #n ")" ::: "memory")
; #define PG8_BAR __builtin_amdgcn_s_barrier()
; #define PG8_SCHED __builtin_amdgcn_sched_barrier(0)
; template <class Epi, class Sched, bool ALIGN_EPI = false, bool SP2 = false>
; __device__ __forceinline__ void gemm_phase(LAS unsigned char* lds, const Gemm g, const Sched S, const Epi E) {
;     ...
;             PG8_LDB(B0, 0, 0); PG8_LDB(B1, 0, 1); PG8_SCHED; PG8_LDA(At, 0, 0); PG8_STAGE(PG8_SA(1, 1), a1 + hstepA, voffA);
;             PG8_WAIT_V(8); PG8_WAIT_L(0); PG8_BAR; PG8_MMA(0, 0, At, B0); PG8_MMA(0, 1, At, B1); PG8_BAR; PG8_SCHED;
;             PG8_LDA(At, 0, 1); PG8_STAGE(PG8_SB(0, 0), b2, voffB); PG8_STAGE(PG8_SB(0, 1), b2 + hstepB, voffB); PG8_STAGE(PG8_SA(0, 0), a2, voffA);
;             PG8_WAIT_V(8); PG8_WAIT_L(0); PG8_BAR; PG8_MMA(1, 0, At, B0); PG8_MMA(1, 1, At, B1); PG8_BAR; PG8_SCHED;
.LBB0_1407:
	ds_read_b128 v[150:153], v180
	ds_read_b128 v[154:157], v180 offset:1024
	ds_read_b128 v[158:161], v180 offset:2048
	ds_read_b128 v[162:165], v180 offset:3072
	ds_read_b128 v[166:169], v181
	ds_read_b128 v[170:173], v181 offset:1024
	ds_read_b128 v[184:187], v181 offset:2048
	ds_read_b128 v[188:191], v181 offset:3072
	s_add_u32 s56, s64, 0x100
	s_addc_u32 s57, s65, 0
	s_cmp_eq_u32 s80, 2
	s_cselect_b32 s67, s9, s57
	s_cselect_b32 s66, s8, s56
	s_cselect_b32 s59, s19, s79
	s_cselect_b32 s58, s18, s78
	s_add_i32 m0, s29, 0xc000
	ds_read_b128 v[192:195], v182
	ds_read_b128 v[196:199], v182 offset:1024
	ds_read_b128 v[200:203], v182 offset:2048
	ds_read_b128 v[204:207], v182 offset:3072
	ds_read_b128 v[208:211], v182 offset:4096
	ds_read_b128 v[212:215], v182 offset:5120
	ds_read_b128 v[216:219], v182 offset:6144
	ds_read_b128 v[220:223], v182 offset:7168
	global_load_lds_dwordx4 v142, s[64:65]
	s_add_i32 m0, s29, 0xe000
	s_nop 0
	global_load_lds_dwordx4 v144, s[64:65]
	s_waitcnt vmcnt(8)
	s_waitcnt lgkmcnt(0)
	s_barrier
	s_setprio 1
	s_waitcnt lgkmcnt(0)
	v_mfma_f32_16x16x32_bf16 v[124:127], v[150:153], v[192:195], v[124:127]
	v_mfma_f32_16x16x32_bf16 v[120:123], v[158:161], v[192:195], v[120:123]
	v_mfma_f32_16x16x32_bf16 v[108:111], v[150:153], v[200:203], v[108:111]
	v_mfma_f32_16x16x32_bf16 v[104:107], v[158:161], v[200:203], v[104:107]
	v_mfma_f32_16x16x32_bf16 v[92:95], v[150:153], v[208:211], v[92:95]
	v_mfma_f32_16x16x32_bf16 v[88:91], v[158:161], v[208:211], v[88:91]
	v_mfma_f32_16x16x32_bf16 v[76:79], v[150:153], v[216:219], v[76:79]
	v_mfma_f32_16x16x32_bf16 v[72:75], v[158:161], v[216:219], v[72:75]
	v_mfma_f32_16x16x32_bf16 v[124:127], v[154:157], v[196:199], v[124:127]
	v_mfma_f32_16x16x32_bf16 v[120:123], v[162:165], v[196:199], v[120:123]
	v_mfma_f32_16x16x32_bf16 v[108:111], v[154:157], v[204:207], v[108:111]
	v_mfma_f32_16x16x32_bf16 v[104:107], v[162:165], v[204:207], v[104:107]
	v_mfma_f32_16x16x32_bf16 v[92:95], v[154:157], v[212:215], v[92:95]
	v_mfma_f32_16x16x32_bf16 v[88:91], v[162:165], v[212:215], v[88:91]
	v_mfma_f32_16x16x32_bf16 v[76:79], v[154:157], v[220:223], v[76:79]
	v_mfma_f32_16x16x32_bf16 v[72:75], v[162:165], v[220:223], v[72:75]
	v_mfma_f32_16x16x32_bf16 v[116:119], v[166:169], v[192:195], v[116:119]
	v_mfma_f32_16x16x32_bf16 v[112:115], v[184:187], v[192:195], v[112:115]
	v_mfma_f32_16x16x32_bf16 v[100:103], v[166:169], v[200:203], v[100:103]
	v_mfma_f32_16x16x32_bf16 v[96:99], v[184:187], v[200:203], v[96:99]
	v_mfma_f32_16x16x32_bf16 v[84:87], v[166:169], v[208:211], v[84:87]
	v_mfma_f32_16x16x32_bf16 v[80:83], v[184:187], v[208:211], v[80:83]
	v_mfma_f32_16x16x32_bf16 v[68:71], v[166:169], v[216:219], v[68:71]
	v_mfma_f32_16x16x32_bf16 v[64:67], v[184:187], v[216:219], v[64:67]
	v_mfma_f32_16x16x32_bf16 v[116:119], v[170:173], v[196:199], v[116:119]
	v_mfma_f32_16x16x32_bf16 v[112:115], v[188:191], v[196:199], v[112:115]
	v_mfma_f32_16x16x32_bf16 v[100:103], v[170:173], v[204:207], v[100:103]
	v_mfma_f32_16x16x32_bf16 v[96:99], v[188:191], v[204:207], v[96:99]
	v_mfma_f32_16x16x32_bf16 v[84:87], v[170:173], v[212:215], v[84:87]
	v_mfma_f32_16x16x32_bf16 v[80:83], v[188:191], v[212:215], v[80:83]
	v_mfma_f32_16x16x32_bf16 v[68:71], v[170:173], v[220:223], v[68:71]
	v_mfma_f32_16x16x32_bf16 v[64:67], v[188:191], v[220:223], v[64:67]
	s_setprio 0
	s_barrier
	s_add_i32 s34, s71, s20
	v_lshl_add_u64 v[176:177], s[58:59], 0, v[132:133]
	s_mov_b32 m0, s34
	ds_read_b128 v[192:195], v182 offset:16384
	ds_read_b128 v[196:199], v182 offset:17408
	ds_read_b128 v[200:203], v182 offset:18432
	ds_read_b128 v[204:207], v182 offset:19456
	ds_read_b128 v[208:211], v182 offset:20480
	ds_read_b128 v[212:215], v182 offset:21504
	ds_read_b128 v[216:219], v182 offset:22528
	ds_read_b128 v[220:223], v182 offset:23552
	global_load_lds_dwordx4 v[176:177], off
	s_add_i32 m0, s34, 0x2000
	s_add_u32 s34, s58, 0x18000
	v_lshl_add_u64 v[224:225], s[58:59], 0, v[128:129]
	s_addc_u32 s35, s59, 0
	s_add_i32 s64, s72, s20
	global_load_lds_dwordx4 v[224:225], off
	s_mov_b32 m0, s64
	v_lshl_add_u64 v[228:229], s[66:67], 0, v[130:131]
	global_load_lds_dwordx4 v132, s[34:35]
	s_add_i32 m0, s64, 0x2000
	s_nop 0
	global_load_lds_dwordx4 v128, s[34:35]
	v_lshl_add_u64 v[226:227], s[66:67], 0, v[134:135]
	s_mov_b32 m0, s29
	s_nop 0
	global_load_lds_dwordx4 v[226:227], off
	s_mov_b32 m0, s30
	s_nop 0
	global_load_lds_dwordx4 v[228:229], off
	s_waitcnt vmcnt(8)
	s_waitcnt lgkmcnt(0)
	s_barrier
	s_setprio 1
	s_waitcnt lgkmcnt(0)
	v_mfma_f32_16x16x32_bf16 v[60:63], v[150:153], v[192:195], v[60:63]
	v_mfma_f32_16x16x32_bf16 v[56:59], v[158:161], v[192:195], v[56:59]
	v_mfma_f32_16x16x32_bf16 v[44:47], v[150:153], v[200:203], v[44:47]
	v_mfma_f32_16x16x32_bf16 v[40:43], v[158:161], v[200:203], v[40:43]
	v_mfma_f32_16x16x32_bf16 v[28:31], v[150:153], v[208:211], v[28:31]
	v_mfma_f32_16x16x32_bf16 v[24:27], v[158:161], v[208:211], v[24:27]
	v_mfma_f32_16x16x32_bf16 v[12:15], v[150:153], v[216:219], v[12:15]
	v_mfma_f32_16x16x32_bf16 v[8:11], v[158:161], v[216:219], v[8:11]
	v_mfma_f32_16x16x32_bf16 v[60:63], v[154:157], v[196:199], v[60:63]
	v_mfma_f32_16x16x32_bf16 v[56:59], v[162:165], v[196:199], v[56:59]
	v_mfma_f32_16x16x32_bf16 v[44:47], v[154:157], v[204:207], v[44:47]
	v_mfma_f32_16x16x32_bf16 v[40:43], v[162:165], v[204:207], v[40:43]
	v_mfma_f32_16x16x32_bf16 v[28:31], v[154:157], v[212:215], v[28:31]
	v_mfma_f32_16x16x32_bf16 v[24:27], v[162:165], v[212:215], v[24:27]
	v_mfma_f32_16x16x32_bf16 v[12:15], v[154:157], v[220:223], v[12:15]
	v_mfma_f32_16x16x32_bf16 v[8:11], v[162:165], v[220:223], v[8:11]
	v_mfma_f32_16x16x32_bf16 v[52:55], v[166:169], v[192:195], v[52:55]
	v_mfma_f32_16x16x32_bf16 v[48:51], v[184:187], v[192:195], v[48:51]
	v_mfma_f32_16x16x32_bf16 v[36:39], v[166:169], v[200:203], v[36:39]
	v_mfma_f32_16x16x32_bf16 v[32:35], v[184:187], v[200:203], v[32:35]
	v_mfma_f32_16x16x32_bf16 v[20:23], v[166:169], v[208:211], v[20:23]
	v_mfma_f32_16x16x32_bf16 v[16:19], v[184:187], v[208:211], v[16:19]
	v_mfma_f32_16x16x32_bf16 v[4:7], v[166:169], v[216:219], v[4:7]
	v_mfma_f32_16x16x32_bf16 v[0:3], v[184:187], v[216:219], v[0:3]
	v_mfma_f32_16x16x32_bf16 v[52:55], v[170:173], v[196:199], v[52:55]
	v_mfma_f32_16x16x32_bf16 v[48:51], v[188:191], v[196:199], v[48:51]
	v_mfma_f32_16x16x32_bf16 v[36:39], v[170:173], v[204:207], v[36:39]
	v_mfma_f32_16x16x32_bf16 v[32:35], v[188:191], v[204:207], v[32:35]
	v_mfma_f32_16x16x32_bf16 v[20:23], v[170:173], v[212:215], v[20:23]
	v_mfma_f32_16x16x32_bf16 v[16:19], v[188:191], v[212:215], v[16:19]
	v_mfma_f32_16x16x32_bf16 v[4:7], v[170:173], v[220:223], v[4:7]
	v_mfma_f32_16x16x32_bf16 v[0:3], v[188:191], v[220:223], v[0:3]
	s_setprio 0
	s_barrier
; #define PG8_STAGE(bufoff, gbase, voff) do { _Pragma("unroll") for (int _i = 0; _i < 2; ++_i) \
;         __builtin_amdgcn_global_load_lds((const unsigned*)((const char*)(gbase) + (voff)[_i]), (LAS unsigned*)(lds + (bufoff) + ldsw + _i * 8192), 16, 0, 0); } while (0)
; #define PG8_LDA(dst, b, h) do { _Pragma("unroll") for (int m = 0; m < 4; ++m) _Pragma("unroll") for (int k = 0; k < 2; ++k) dst[m][k] = *(const LAS bf16x8*)(lds + PG8_SA(b, h) + aoff + m * 2048 + k * 1024); } while (0)
; #define PG8_LDB(dst, b, h) do { _Pragma("unroll") for (int n = 0; n < 2; ++n) _Pragma("unroll") for (int k = 0; k < 2; ++k) dst[n][k] = *(const LAS bf16x8*)(lds + PG8_SB(b, h) + boff + n * 2048 + k * 1024); } while (0)
; #define PG8_MMA(ai, bj, At, Bt) do { __builtin_amdgcn_s_setprio(1); _Pragma("unroll") for (int m = 0; m < 4; ++m) _Pragma("unroll") for (int n = 0; n < 2; ++n) _Pragma("unroll") for (int k = 0; k < 2; ++k) \
;         acc[ai][bj][m][n] = __builtin_amdgcn_mfma_f32_16x16x32_bf16(Bt[n][k], At[m][k], acc[ai][bj][m][n], 0, 0, 0); __builtin_amdgcn_s_setprio(0); } while (0)
; #define PG8_WAIT_V(n) asm volatile("s_waitcnt vmcnt(" #n ")" ::: "memory")
; #define PG8_WAIT_L(n) asm volatile("s_waitcnt lgkmcnt(" #n ")" ::: "memory")
; #define PG8_BAR __builtin_amdgcn_s_barrier()
; #define PG8_SCHED __builtin_amdgcn_sched_barrier(0)
; template <class Epi, class Sched, bool ALIGN_EPI = false, bool SP2 = false>
; __device__ __forceinline__ void gemm_phase(LAS unsigned char* lds, const Gemm g, const Sched S, const Epi E) {
;     ...
;             PG8_LDB(B0, 1, 0); PG8_LDB(B1, 1, 1); PG8_SCHED; PG8_LDA(At, 1, 0); PG8_STAGE(PG8_SA(0, 1), a2 + hstepA, voffA);
;             PG8_WAIT_V(8); PG8_WAIT_L(0); PG8_BAR; PG8_MMA(0, 0, At, B0); PG8_MMA(0, 1, At, B1); PG8_BAR; PG8_SCHED;
;             PG8_LDA(At, 1, 1); PG8_STAGE(PG8_SB(1, 0), b3, voffB); PG8_STAGE(PG8_SB(1, 1), b3 + hstepB, voffB); PG8_STAGE(PG8_SA(1, 0), a3, voffA);
;             PG8_WAIT_V(8); PG8_WAIT_L(0); PG8_BAR; PG8_MMA(1, 0, At, B0); PG8_MMA(1, 1, At, B1); PG8_BAR; PG8_SCHED;
	s_add_i32 s64, 0, 0x18000
	s_add_i32 s65, 0, 0x1c000
	v_add_u32_e32 v162, s64, v178
	v_add_u32_e32 v174, s65, v178
	ds_read_b128 v[150:153], v162
	ds_read_b128 v[154:157], v162 offset:1024
	ds_read_b128 v[158:161], v162 offset:2048
	ds_read_b128 v[162:165], v162 offset:3072
	ds_read_b128 v[166:169], v174
	ds_read_b128 v[170:173], v174 offset:1024
	ds_read_b128 v[184:187], v174 offset:2048
	ds_read_b128 v[188:191], v174 offset:3072
	s_add_u32 s34, s66, 0x130000
	s_addc_u32 s35, s67, 0
	s_mov_b32 m0, s31
	ds_read_b128 v[192:195], v182 offset:32768
	ds_read_b128 v[196:199], v182 offset:33792
	ds_read_b128 v[200:203], v182 offset:34816
	ds_read_b128 v[204:207], v182 offset:35840
	ds_read_b128 v[208:211], v182 offset:36864
	ds_read_b128 v[212:215], v182 offset:37888
	ds_read_b128 v[216:219], v182 offset:38912
	ds_read_b128 v[220:223], v182 offset:39936
	global_load_lds_dwordx4 v134, s[34:35]
	s_mov_b32 m0, s33
	s_nop 0
	global_load_lds_dwordx4 v130, s[34:35]
	s_waitcnt vmcnt(8)
	s_waitcnt lgkmcnt(0)
	s_barrier
	s_setprio 1
	s_waitcnt lgkmcnt(0)
	v_mfma_f32_16x16x32_bf16 v[124:127], v[150:153], v[192:195], v[124:127]
	v_mfma_f32_16x16x32_bf16 v[120:123], v[158:161], v[192:195], v[120:123]
	v_mfma_f32_16x16x32_bf16 v[108:111], v[150:153], v[200:203], v[108:111]
	v_mfma_f32_16x16x32_bf16 v[104:107], v[158:161], v[200:203], v[104:107]
	v_mfma_f32_16x16x32_bf16 v[92:95], v[150:153], v[208:211], v[92:95]
	v_mfma_f32_16x16x32_bf16 v[88:91], v[158:161], v[208:211], v[88:91]
	v_mfma_f32_16x16x32_bf16 v[76:79], v[150:153], v[216:219], v[76:79]
	v_mfma_f32_16x16x32_bf16 v[72:75], v[158:161], v[216:219], v[72:75]
	v_mfma_f32_16x16x32_bf16 v[124:127], v[154:157], v[196:199], v[124:127]
	v_mfma_f32_16x16x32_bf16 v[120:123], v[162:165], v[196:199], v[120:123]
	v_mfma_f32_16x16x32_bf16 v[108:111], v[154:157], v[204:207], v[108:111]
	v_mfma_f32_16x16x32_bf16 v[104:107], v[162:165], v[204:207], v[104:107]
	v_mfma_f32_16x16x32_bf16 v[92:95], v[154:157], v[212:215], v[92:95]
	v_mfma_f32_16x16x32_bf16 v[88:91], v[162:165], v[212:215], v[88:91]
	v_mfma_f32_16x16x32_bf16 v[76:79], v[154:157], v[220:223], v[76:79]
	v_mfma_f32_16x16x32_bf16 v[72:75], v[162:165], v[220:223], v[72:75]
	v_mfma_f32_16x16x32_bf16 v[116:119], v[166:169], v[192:195], v[116:119]
	v_mfma_f32_16x16x32_bf16 v[112:115], v[184:187], v[192:195], v[112:115]
	v_mfma_f32_16x16x32_bf16 v[100:103], v[166:169], v[200:203], v[100:103]
	v_mfma_f32_16x16x32_bf16 v[96:99], v[184:187], v[200:203], v[96:99]
	v_mfma_f32_16x16x32_bf16 v[84:87], v[166:169], v[208:211], v[84:87]
	v_mfma_f32_16x16x32_bf16 v[80:83], v[184:187], v[208:211], v[80:83]
	v_mfma_f32_16x16x32_bf16 v[68:71], v[166:169], v[216:219], v[68:71]
	v_mfma_f32_16x16x32_bf16 v[64:67], v[184:187], v[216:219], v[64:67]
	v_mfma_f32_16x16x32_bf16 v[116:119], v[170:173], v[196:199], v[116:119]
	v_mfma_f32_16x16x32_bf16 v[112:115], v[188:191], v[196:199], v[112:115]
	v_mfma_f32_16x16x32_bf16 v[100:103], v[170:173], v[204:207], v[100:103]
	v_mfma_f32_16x16x32_bf16 v[96:99], v[188:191], v[204:207], v[96:99]
	v_mfma_f32_16x16x32_bf16 v[84:87], v[170:173], v[212:215], v[84:87]
	v_mfma_f32_16x16x32_bf16 v[80:83], v[188:191], v[212:215], v[80:83]
	v_mfma_f32_16x16x32_bf16 v[68:71], v[170:173], v[220:223], v[68:71]
	v_mfma_f32_16x16x32_bf16 v[64:67], v[188:191], v[220:223], v[64:67]
	s_setprio 0
	s_barrier
	s_add_i32 s34, s64, s20
	v_lshl_add_u64 v[176:177], v[176:177], 0, s[14:15]
	s_mov_b32 m0, s34
	ds_read_b128 v[192:195], v182 offset:49152
	ds_read_b128 v[196:199], v182 offset:50176
	ds_read_b128 v[200:203], v182 offset:51200
	ds_read_b128 v[204:207], v182 offset:52224
	ds_read_b128 v[208:211], v182 offset:53248
	ds_read_b128 v[212:215], v182 offset:54272
	ds_read_b128 v[216:219], v182 offset:55296
	ds_read_b128 v[220:223], v182 offset:56320
	global_load_lds_dwordx4 v[176:177], off
	s_add_i32 m0, s34, 0x2000
	s_add_u32 s34, s58, 0x18080
	v_lshl_add_u64 v[176:177], v[224:225], 0, s[14:15]
	s_addc_u32 s35, s59, 0
	s_add_i32 s58, s65, s20
	global_load_lds_dwordx4 v[176:177], off
	s_mov_b32 m0, s58
	s_nop 0
	global_load_lds_dwordx4 v132, s[34:35]
	s_add_i32 m0, s58, 0x2000
	s_nop 0
	global_load_lds_dwordx4 v128, s[34:35]
	v_lshl_add_u64 v[176:177], v[226:227], 0, s[14:15]
	s_mov_b32 m0, s44
	s_nop 0
	global_load_lds_dwordx4 v[176:177], off
	v_lshl_add_u64 v[176:177], v[228:229], 0, s[14:15]
	s_mov_b32 m0, s45
	s_nop 0
	global_load_lds_dwordx4 v[176:177], off
	s_waitcnt vmcnt(8)
	s_waitcnt lgkmcnt(0)
	s_barrier
	s_setprio 1
	s_waitcnt lgkmcnt(0)
	v_mfma_f32_16x16x32_bf16 v[60:63], v[150:153], v[192:195], v[60:63]
	v_mfma_f32_16x16x32_bf16 v[56:59], v[158:161], v[192:195], v[56:59]
	v_mfma_f32_16x16x32_bf16 v[44:47], v[150:153], v[200:203], v[44:47]
	v_mfma_f32_16x16x32_bf16 v[40:43], v[158:161], v[200:203], v[40:43]
	v_mfma_f32_16x16x32_bf16 v[28:31], v[150:153], v[208:211], v[28:31]
	v_mfma_f32_16x16x32_bf16 v[24:27], v[158:161], v[208:211], v[24:27]
	v_mfma_f32_16x16x32_bf16 v[12:15], v[150:153], v[216:219], v[12:15]
	v_mfma_f32_16x16x32_bf16 v[8:11], v[158:161], v[216:219], v[8:11]
	v_mfma_f32_16x16x32_bf16 v[60:63], v[154:157], v[196:199], v[60:63]
	v_mfma_f32_16x16x32_bf16 v[56:59], v[162:165], v[196:199], v[56:59]
	v_mfma_f32_16x16x32_bf16 v[44:47], v[154:157], v[204:207], v[44:47]
	v_mfma_f32_16x16x32_bf16 v[40:43], v[162:165], v[204:207], v[40:43]
	v_mfma_f32_16x16x32_bf16 v[28:31], v[154:157], v[212:215], v[28:31]
	v_mfma_f32_16x16x32_bf16 v[24:27], v[162:165], v[212:215], v[24:27]
	v_mfma_f32_16x16x32_bf16 v[12:15], v[154:157], v[220:223], v[12:15]
	v_mfma_f32_16x16x32_bf16 v[8:11], v[162:165], v[220:223], v[8:11]
	v_mfma_f32_16x16x32_bf16 v[52:55], v[166:169], v[192:195], v[52:55]
	v_mfma_f32_16x16x32_bf16 v[48:51], v[184:187], v[192:195], v[48:51]
	v_mfma_f32_16x16x32_bf16 v[36:39], v[166:169], v[200:203], v[36:39]
	v_mfma_f32_16x16x32_bf16 v[32:35], v[184:187], v[200:203], v[32:35]
	v_mfma_f32_16x16x32_bf16 v[20:23], v[166:169], v[208:211], v[20:23]
	v_mfma_f32_16x16x32_bf16 v[16:19], v[184:187], v[208:211], v[16:19]
	v_mfma_f32_16x16x32_bf16 v[4:7], v[166:169], v[216:219], v[4:7]
	v_mfma_f32_16x16x32_bf16 v[0:3], v[184:187], v[216:219], v[0:3]
	v_mfma_f32_16x16x32_bf16 v[52:55], v[170:173], v[196:199], v[52:55]
	v_mfma_f32_16x16x32_bf16 v[48:51], v[188:191], v[196:199], v[48:51]
	v_mfma_f32_16x16x32_bf16 v[36:39], v[170:173], v[204:207], v[36:39]
	v_mfma_f32_16x16x32_bf16 v[32:35], v[188:191], v[204:207], v[32:35]
	v_mfma_f32_16x16x32_bf16 v[20:23], v[170:173], v[212:215], v[20:23]
	v_mfma_f32_16x16x32_bf16 v[16:19], v[188:191], v[212:215], v[16:19]
	v_mfma_f32_16x16x32_bf16 v[4:7], v[170:173], v[220:223], v[4:7]
	v_mfma_f32_16x16x32_bf16 v[0:3], v[188:191], v[220:223], v[0:3]
	s_setprio 0
	s_add_i32 s80, s80, 2
	s_add_u32 s78, s78, 0x100
	s_addc_u32 s79, s79, 0
	s_cmp_gt_u32 s80, 3
	s_mov_b64 s[64:65], s[56:57]
	s_barrier
	s_cbranch_scc0 .LBB0_1407
	s_and_b64 vcc, exec, s[16:17]
	s_cbranch_vccz .LBB0_1410
	s_barrier

; #define PG8_STAGE(bufoff, gbase, voff) do { _Pragma("unroll") for (int _i = 0; _i < 2; ++_i) \
;         __builtin_amdgcn_global_load_lds((const unsigned*)((const char*)(gbase) + (voff)[_i]), (LAS unsigned*)(lds + (bufoff) + ldsw + _i * 8192), 16, 0, 0); } while (0)
; #define PG8_LDA(dst, b, h) do { _Pragma("unroll") for (int m = 0; m < 4; ++m) _Pragma("unroll") for (int k = 0; k < 2; ++k) dst[m][k] = *(const LAS bf16x8*)(lds + PG8_SA(b, h) + aoff + m * 2048 + k * 1024); } while (0)
; #define PG8_LDB(dst, b, h) do { _Pragma("unroll") for (int n = 0; n < 2; ++n) _Pragma("unroll") for (int k = 0; k < 2; ++k) dst[n][k] = *(const LAS bf16x8*)(lds + PG8_SB(b, h) + boff + n * 2048 + k * 1024); } while (0)
; #define PG8_MMA(ai, bj, At, Bt) do { __builtin_amdgcn_s_setprio(1); _Pragma("unroll") for (int m = 0; m < 4; ++m) _Pragma("unroll") for (int n = 0; n < 2; ++n) _Pragma("unroll") for (int k = 0; k < 2; ++k) \
;         acc[ai][bj][m][n] = __builtin_amdgcn_mfma_f32_16x16x32_bf16(Bt[n][k], At[m][k], acc[ai][bj][m][n], 0, 0, 0); __builtin_amdgcn_s_setprio(0); } while (0)
; #define PG8_WAIT_V(n) asm volatile("s_waitcnt vmcnt(" #n ")" ::: "memory")
; #define PG8_WAIT_L(n) asm volatile("s_waitcnt lgkmcnt(" #n ")" ::: "memory")
; template <class Epi, class Sched, bool ALIGN_EPI = false, bool SP2 = false>
; __device__ __forceinline__ void gemm_phase(LAS unsigned char* lds, const Gemm g, const Sched S, const Epi E) {
;     ...
;         for (int t = 0; t < nt; t += 2) {
;             const bool last = (t == nt - 2);
;             const char* a1 = cA + (size_t)(t + 1) * kstep;
;             const char* a2 = last ? nA : cA + (size_t)(t + 2) * kstep; const char* b2 = last ? nB : cB + (size_t)(t + 2) * kstep;
;             const char* a3 = a2 + kstep; const char* b3 = b2 + kstep;
;             if (last && has_next) S.a_ready(nxt);
;             if constexpr (SP2) {
;             PG8_LDB(B0, 0, 0); PG8_LDB(B1, 0, 1); PG8_SCHED; PG8_LDA(At, 0, 0); PG8_STAGE(PG8_SA(1, 1), a1 + hstepA, voffA);
;             PG8_WAIT_V(8); PG8_WAIT_L(0); PG8_BAR; PG8_MMA(0, 0, At, B0); PG8_MMA(0, 1, At, B1); PG8_BAR; PG8_SCHED;
;             PG8_LDA(At, 0, 1); PG8_STAGE(PG8_SB(0, 0), b2, voffB); PG8_STAGE(PG8_SB(0, 1), b2 + hstepB, voffB); PG8_STAGE(PG8_SA(0, 0), a2, voffA);
;             PG8_WAIT_V(8); PG8_WAIT_L(0); PG8_BAR; PG8_MMA(1, 0, At, B0); PG8_MMA(1, 1, At, B1); PG8_BAR; PG8_SCHED;
.LBB0_1437:
	s_add_u32 s34, s68, s72
	s_addc_u32 s35, s69, s73
	s_add_u32 s74, s34, 0x100
	s_addc_u32 s75, s35, 0
	s_and_b64 s[12:13], s[70:71], exec
	s_cselect_b32 s75, s59, s75
	s_cselect_b32 s74, s58, s74
	s_add_u32 s12, s66, s72
	s_addc_u32 s13, s67, s73
	s_add_u32 s72, s12, 0x100
	s_addc_u32 s73, s13, 0
	s_and_b64 s[12:13], s[70:71], exec
	s_cselect_b32 s77, s57, s73
	s_cselect_b32 s76, s89, s72
	s_add_u32 s80, s34, 0x130080
	ds_read_b128 v[146:149], v158
	ds_read_b128 v[150:153], v158 offset:1024
	ds_read_b128 v[164:167], v158 offset:2048
	ds_read_b128 v[168:171], v158 offset:3072
	ds_read_b128 v[172:175], v159
	ds_read_b128 v[176:179], v159 offset:1024
	ds_read_b128 v[180:183], v159 offset:2048
	ds_read_b128 v[184:187], v159 offset:3072
	s_addc_u32 s81, s35, 0
	s_add_i32 s97, s84, s20
	s_add_i32 m0, s21, 0xc000
	s_add_i32 s13, s21, 0xe000
	s_add_i32 s12, s97, 0x2000
	s_add_u32 s78, s76, 0x10000
	s_addc_u32 s79, s77, 0
	s_add_i32 vcc_hi, s85, s20
	s_add_i32 vcc_lo, vcc_hi, 0x2000
	s_add_i32 s96, 0, 0x18000
	s_add_i32 s95, 0, 0x1c000
	s_add_u32 s72, s74, 0x130000
	s_addc_u32 s73, s75, 0
	s_add_i32 s93, s96, s20
	s_add_i32 s91, s93, 0x2000
	s_add_u32 s70, s76, 0x10080
	s_addc_u32 s71, s77, 0
	s_add_i32 s92, s95, s20
	s_add_i32 s90, s92, 0x2000
	v_lshl_add_u64 v[154:155], s[80:81], 0, v[128:129]
	ds_read_b128 v[188:191], v160
	ds_read_b128 v[192:195], v160 offset:1024
	ds_read_b128 v[196:199], v160 offset:2048
	ds_read_b128 v[200:203], v160 offset:3072
	ds_read_b128 v[204:207], v160 offset:4096
	ds_read_b128 v[208:211], v160 offset:5120
	ds_read_b128 v[212:215], v160 offset:6144
	ds_read_b128 v[216:219], v160 offset:7168
	global_load_lds_dwordx4 v[154:155], off
	v_lshl_add_u64 v[154:155], s[80:81], 0, v[132:133]
	s_mov_b32 m0, s13
	s_nop 0
	global_load_lds_dwordx4 v[154:155], off
	s_waitcnt vmcnt(8)
	s_waitcnt lgkmcnt(0)
	s_barrier
	s_setprio 1
	s_waitcnt lgkmcnt(0)
	v_mfma_f32_16x16x32_bf16 v[124:127], v[146:149], v[188:191], v[124:127]
	v_mfma_f32_16x16x32_bf16 v[120:123], v[164:167], v[188:191], v[120:123]
	v_mfma_f32_16x16x32_bf16 v[108:111], v[146:149], v[196:199], v[108:111]
	v_mfma_f32_16x16x32_bf16 v[104:107], v[164:167], v[196:199], v[104:107]
	v_mfma_f32_16x16x32_bf16 v[92:95], v[146:149], v[204:207], v[92:95]
	v_mfma_f32_16x16x32_bf16 v[88:91], v[164:167], v[204:207], v[88:91]
	v_mfma_f32_16x16x32_bf16 v[76:79], v[146:149], v[212:215], v[76:79]
	v_mfma_f32_16x16x32_bf16 v[72:75], v[164:167], v[212:215], v[72:75]
	v_mfma_f32_16x16x32_bf16 v[124:127], v[150:153], v[192:195], v[124:127]
	v_mfma_f32_16x16x32_bf16 v[120:123], v[168:171], v[192:195], v[120:123]
	v_mfma_f32_16x16x32_bf16 v[108:111], v[150:153], v[200:203], v[108:111]
	v_mfma_f32_16x16x32_bf16 v[104:107], v[168:171], v[200:203], v[104:107]
	v_mfma_f32_16x16x32_bf16 v[92:95], v[150:153], v[208:211], v[92:95]
	v_mfma_f32_16x16x32_bf16 v[88:91], v[168:171], v[208:211], v[88:91]
	v_mfma_f32_16x16x32_bf16 v[76:79], v[150:153], v[216:219], v[76:79]
	v_mfma_f32_16x16x32_bf16 v[72:75], v[168:171], v[216:219], v[72:75]
	v_mfma_f32_16x16x32_bf16 v[116:119], v[172:175], v[188:191], v[116:119]
	v_mfma_f32_16x16x32_bf16 v[112:115], v[180:183], v[188:191], v[112:115]
	v_mfma_f32_16x16x32_bf16 v[100:103], v[172:175], v[196:199], v[100:103]
	v_mfma_f32_16x16x32_bf16 v[96:99], v[180:183], v[196:199], v[96:99]
	v_mfma_f32_16x16x32_bf16 v[84:87], v[172:175], v[204:207], v[84:87]
	v_mfma_f32_16x16x32_bf16 v[80:83], v[180:183], v[204:207], v[80:83]
	v_mfma_f32_16x16x32_bf16 v[68:71], v[172:175], v[212:215], v[68:71]
	v_mfma_f32_16x16x32_bf16 v[64:67], v[180:183], v[212:215], v[64:67]
	v_mfma_f32_16x16x32_bf16 v[116:119], v[176:179], v[192:195], v[116:119]
	v_mfma_f32_16x16x32_bf16 v[112:115], v[184:187], v[192:195], v[112:115]
	v_mfma_f32_16x16x32_bf16 v[100:103], v[176:179], v[200:203], v[100:103]
	v_mfma_f32_16x16x32_bf16 v[96:99], v[184:187], v[200:203], v[96:99]
	v_mfma_f32_16x16x32_bf16 v[84:87], v[176:179], v[208:211], v[84:87]
	v_mfma_f32_16x16x32_bf16 v[80:83], v[184:187], v[208:211], v[80:83]
	v_mfma_f32_16x16x32_bf16 v[68:71], v[176:179], v[216:219], v[68:71]
	v_mfma_f32_16x16x32_bf16 v[64:67], v[184:187], v[216:219], v[64:67]
	s_setprio 0
	s_barrier
	s_mov_b32 m0, s97
	v_lshl_add_u64 v[154:155], s[76:77], 0, v[130:131]
	ds_read_b128 v[188:191], v160 offset:16384
	ds_read_b128 v[192:195], v160 offset:17408
	ds_read_b128 v[196:199], v160 offset:18432
	ds_read_b128 v[200:203], v160 offset:19456
	ds_read_b128 v[204:207], v160 offset:20480
	ds_read_b128 v[208:211], v160 offset:21504
	ds_read_b128 v[212:215], v160 offset:22528
	ds_read_b128 v[216:219], v160 offset:23552
	global_load_lds_dwordx4 v[154:155], off
	v_lshl_add_u64 v[220:221], s[76:77], 0, v[134:135]
	s_mov_b32 m0, s12
	v_lshl_add_u64 v[222:223], s[78:79], 0, v[130:131]
	global_load_lds_dwordx4 v[220:221], off
	s_mov_b32 m0, vcc_hi
	v_lshl_add_u64 v[224:225], s[74:75], 0, v[132:133]
	global_load_lds_dwordx4 v[222:223], off
	v_lshl_add_u64 v[222:223], s[78:79], 0, v[134:135]
	s_mov_b32 m0, vcc_lo
	s_nop 0
	global_load_lds_dwordx4 v[222:223], off
	v_lshl_add_u64 v[222:223], s[74:75], 0, v[128:129]
	s_mov_b32 m0, s21
	s_nop 0
	global_load_lds_dwordx4 v[222:223], off
	s_mov_b32 m0, s29
	s_nop 0
	global_load_lds_dwordx4 v[224:225], off
	s_waitcnt vmcnt(8)
	s_waitcnt lgkmcnt(0)
	s_barrier
; #define PG8_STAGE(bufoff, gbase, voff) do { _Pragma("unroll") for (int _i = 0; _i < 2; ++_i) \
;         __builtin_amdgcn_global_load_lds((const unsigned*)((const char*)(gbase) + (voff)[_i]), (LAS unsigned*)(lds + (bufoff) + ldsw + _i * 8192), 16, 0, 0); } while (0)
; #define PG8_LDA(dst, b, h) do { _Pragma("unroll") for (int m = 0; m < 4; ++m) _Pragma("unroll") for (int k = 0; k < 2; ++k) dst[m][k] = *(const LAS bf16x8*)(lds + PG8_SA(b, h) + aoff + m * 2048 + k * 1024); } while (0)
; #define PG8_LDB(dst, b, h) do { _Pragma("unroll") for (int n = 0; n < 2; ++n) _Pragma("unroll") for (int k = 0; k < 2; ++k) dst[n][k] = *(const LAS bf16x8*)(lds + PG8_SB(b, h) + boff + n * 2048 + k * 1024); } while (0)
; #define PG8_MMA(ai, bj, At, Bt) do { __builtin_amdgcn_s_setprio(1); _Pragma("unroll") for (int m = 0; m < 4; ++m) _Pragma("unroll") for (int n = 0; n < 2; ++n) _Pragma("unroll") for (int k = 0; k < 2; ++k) \
;         acc[ai][bj][m][n] = __builtin_amdgcn_mfma_f32_16x16x32_bf16(Bt[n][k], At[m][k], acc[ai][bj][m][n], 0, 0, 0); __builtin_amdgcn_s_setprio(0); } while (0)
; #define PG8_WAIT_V(n) asm volatile("s_waitcnt vmcnt(" #n ")" ::: "memory")
; #define PG8_WAIT_L(n) asm volatile("s_waitcnt lgkmcnt(" #n ")" ::: "memory")
; #define PG8_BAR __builtin_amdgcn_s_barrier()
; #define PG8_SCHED __builtin_amdgcn_sched_barrier(0)
; template <class Epi, class Sched, bool ALIGN_EPI = false, bool SP2 = false>
; __device__ __forceinline__ void gemm_phase(LAS unsigned char* lds, const Gemm g, const Sched S, const Epi E) {
;     ...
;             PG8_WAIT_V(8); PG8_WAIT_L(0); PG8_BAR; PG8_MMA(1, 0, At, B0); PG8_MMA(1, 1, At, B1); PG8_BAR; PG8_SCHED;
;             PG8_LDB(B0, 1, 0); PG8_LDB(B1, 1, 1); PG8_SCHED; PG8_LDA(At, 1, 0); PG8_STAGE(PG8_SA(0, 1), a2 + hstepA, voffA);
;             PG8_WAIT_V(8); PG8_WAIT_L(0); PG8_BAR; PG8_MMA(0, 0, At, B0); PG8_MMA(0, 1, At, B1); PG8_BAR; PG8_SCHED;
	s_setprio 1
	s_waitcnt lgkmcnt(0)
	v_mfma_f32_16x16x32_bf16 v[60:63], v[146:149], v[188:191], v[60:63]
	v_mfma_f32_16x16x32_bf16 v[56:59], v[164:167], v[188:191], v[56:59]
	v_mfma_f32_16x16x32_bf16 v[44:47], v[146:149], v[196:199], v[44:47]
	v_mfma_f32_16x16x32_bf16 v[40:43], v[164:167], v[196:199], v[40:43]
	v_mfma_f32_16x16x32_bf16 v[28:31], v[146:149], v[204:207], v[28:31]
	v_mfma_f32_16x16x32_bf16 v[24:27], v[164:167], v[204:207], v[24:27]
	v_mfma_f32_16x16x32_bf16 v[12:15], v[146:149], v[212:215], v[12:15]
	v_mfma_f32_16x16x32_bf16 v[8:11], v[164:167], v[212:215], v[8:11]
	v_mfma_f32_16x16x32_bf16 v[60:63], v[150:153], v[192:195], v[60:63]
	v_mfma_f32_16x16x32_bf16 v[56:59], v[168:171], v[192:195], v[56:59]
	v_mfma_f32_16x16x32_bf16 v[44:47], v[150:153], v[200:203], v[44:47]
	v_mfma_f32_16x16x32_bf16 v[40:43], v[168:171], v[200:203], v[40:43]
	v_mfma_f32_16x16x32_bf16 v[28:31], v[150:153], v[208:211], v[28:31]
	v_mfma_f32_16x16x32_bf16 v[24:27], v[168:171], v[208:211], v[24:27]
	v_mfma_f32_16x16x32_bf16 v[12:15], v[150:153], v[216:219], v[12:15]
	v_mfma_f32_16x16x32_bf16 v[8:11], v[168:171], v[216:219], v[8:11]
	v_mfma_f32_16x16x32_bf16 v[52:55], v[172:175], v[188:191], v[52:55]
	v_mfma_f32_16x16x32_bf16 v[48:51], v[180:183], v[188:191], v[48:51]
	v_mfma_f32_16x16x32_bf16 v[36:39], v[172:175], v[196:199], v[36:39]
	v_mfma_f32_16x16x32_bf16 v[32:35], v[180:183], v[196:199], v[32:35]
	v_mfma_f32_16x16x32_bf16 v[20:23], v[172:175], v[204:207], v[20:23]
	v_mfma_f32_16x16x32_bf16 v[16:19], v[180:183], v[204:207], v[16:19]
	v_mfma_f32_16x16x32_bf16 v[4:7], v[172:175], v[212:215], v[4:7]
	v_mfma_f32_16x16x32_bf16 v[0:3], v[180:183], v[212:215], v[0:3]
	v_mfma_f32_16x16x32_bf16 v[52:55], v[176:179], v[192:195], v[52:55]
	v_mfma_f32_16x16x32_bf16 v[48:51], v[184:187], v[192:195], v[48:51]
	v_mfma_f32_16x16x32_bf16 v[36:39], v[176:179], v[200:203], v[36:39]
	v_mfma_f32_16x16x32_bf16 v[32:35], v[184:187], v[200:203], v[32:35]
	v_mfma_f32_16x16x32_bf16 v[20:23], v[176:179], v[208:211], v[20:23]
	v_mfma_f32_16x16x32_bf16 v[16:19], v[184:187], v[208:211], v[16:19]
	v_mfma_f32_16x16x32_bf16 v[4:7], v[176:179], v[216:219], v[4:7]
	v_mfma_f32_16x16x32_bf16 v[0:3], v[184:187], v[216:219], v[0:3]
	s_setprio 0
	s_barrier
	v_add_u32_e32 v163, s96, v141
	ds_read_b128 v[146:149], v163
	ds_read_b128 v[150:153], v163 offset:1024
	ds_read_b128 v[164:167], v163 offset:2048
	ds_read_b128 v[168:171], v163 offset:3072
	v_add_u32_e32 v163, s95, v141
	ds_read_b128 v[172:175], v163
	ds_read_b128 v[176:179], v163 offset:1024
	ds_read_b128 v[180:183], v163 offset:2048
	ds_read_b128 v[184:187], v163 offset:3072
	s_mov_b32 m0, s30
	v_lshl_add_u64 v[226:227], s[72:73], 0, v[128:129]
	ds_read_b128 v[188:191], v160 offset:32768
	ds_read_b128 v[192:195], v160 offset:33792
	ds_read_b128 v[196:199], v160 offset:34816
	ds_read_b128 v[200:203], v160 offset:35840
	ds_read_b128 v[204:207], v160 offset:36864
	ds_read_b128 v[208:211], v160 offset:37888
	ds_read_b128 v[212:215], v160 offset:38912
	ds_read_b128 v[216:219], v160 offset:39936
	global_load_lds_dwordx4 v[226:227], off
	v_lshl_add_u64 v[226:227], s[72:73], 0, v[132:133]
	s_mov_b32 m0, s31
	s_nop 0
	global_load_lds_dwordx4 v[226:227], off
	s_waitcnt vmcnt(8)
	s_waitcnt lgkmcnt(0)
	s_barrier
	s_setprio 1
	s_waitcnt lgkmcnt(0)
	v_mfma_f32_16x16x32_bf16 v[124:127], v[146:149], v[188:191], v[124:127]
	v_mfma_f32_16x16x32_bf16 v[120:123], v[164:167], v[188:191], v[120:123]
	v_mfma_f32_16x16x32_bf16 v[108:111], v[146:149], v[196:199], v[108:111]
	v_mfma_f32_16x16x32_bf16 v[104:107], v[164:167], v[196:199], v[104:107]
	v_mfma_f32_16x16x32_bf16 v[92:95], v[146:149], v[204:207], v[92:95]
	v_mfma_f32_16x16x32_bf16 v[88:91], v[164:167], v[204:207], v[88:91]
	v_mfma_f32_16x16x32_bf16 v[76:79], v[146:149], v[212:215], v[76:79]
	v_mfma_f32_16x16x32_bf16 v[72:75], v[164:167], v[212:215], v[72:75]
	v_mfma_f32_16x16x32_bf16 v[124:127], v[150:153], v[192:195], v[124:127]
	v_mfma_f32_16x16x32_bf16 v[120:123], v[168:171], v[192:195], v[120:123]
	v_mfma_f32_16x16x32_bf16 v[108:111], v[150:153], v[200:203], v[108:111]
	v_mfma_f32_16x16x32_bf16 v[104:107], v[168:171], v[200:203], v[104:107]
	v_mfma_f32_16x16x32_bf16 v[92:95], v[150:153], v[208:211], v[92:95]
	v_mfma_f32_16x16x32_bf16 v[88:91], v[168:171], v[208:211], v[88:91]
	v_mfma_f32_16x16x32_bf16 v[76:79], v[150:153], v[216:219], v[76:79]
	v_mfma_f32_16x16x32_bf16 v[72:75], v[168:171], v[216:219], v[72:75]
	v_mfma_f32_16x16x32_bf16 v[116:119], v[172:175], v[188:191], v[116:119]
	v_mfma_f32_16x16x32_bf16 v[112:115], v[180:183], v[188:191], v[112:115]
	v_mfma_f32_16x16x32_bf16 v[100:103], v[172:175], v[196:199], v[100:103]
	v_mfma_f32_16x16x32_bf16 v[96:99], v[180:183], v[196:199], v[96:99]
	v_mfma_f32_16x16x32_bf16 v[84:87], v[172:175], v[204:207], v[84:87]
	v_mfma_f32_16x16x32_bf16 v[80:83], v[180:183], v[204:207], v[80:83]
	v_mfma_f32_16x16x32_bf16 v[68:71], v[172:175], v[212:215], v[68:71]
	v_mfma_f32_16x16x32_bf16 v[64:67], v[180:183], v[212:215], v[64:67]
	v_mfma_f32_16x16x32_bf16 v[116:119], v[176:179], v[192:195], v[116:119]
	v_mfma_f32_16x16x32_bf16 v[112:115], v[184:187], v[192:195], v[112:115]
	v_mfma_f32_16x16x32_bf16 v[100:103], v[176:179], v[200:203], v[100:103]
	v_mfma_f32_16x16x32_bf16 v[96:99], v[184:187], v[200:203], v[96:99]
	v_mfma_f32_16x16x32_bf16 v[84:87], v[176:179], v[208:211], v[84:87]
	v_mfma_f32_16x16x32_bf16 v[80:83], v[184:187], v[208:211], v[80:83]
	v_mfma_f32_16x16x32_bf16 v[68:71], v[176:179], v[216:219], v[68:71]
	v_mfma_f32_16x16x32_bf16 v[64:67], v[184:187], v[216:219], v[64:67]
	s_setprio 0
	s_barrier
; #define PG8_STAGE(bufoff, gbase, voff) do { _Pragma("unroll") for (int _i = 0; _i < 2; ++_i) \
;         __builtin_amdgcn_global_load_lds((const unsigned*)((const char*)(gbase) + (voff)[_i]), (LAS unsigned*)(lds + (bufoff) + ldsw + _i * 8192), 16, 0, 0); } while (0)
; #define PG8_LDA(dst, b, h) do { _Pragma("unroll") for (int m = 0; m < 4; ++m) _Pragma("unroll") for (int k = 0; k < 2; ++k) dst[m][k] = *(const LAS bf16x8*)(lds + PG8_SA(b, h) + aoff + m * 2048 + k * 1024); } while (0)
; #define PG8_MMA(ai, bj, At, Bt) do { __builtin_amdgcn_s_setprio(1); _Pragma("unroll") for (int m = 0; m < 4; ++m) _Pragma("unroll") for (int n = 0; n < 2; ++n) _Pragma("unroll") for (int k = 0; k < 2; ++k) \
;         acc[ai][bj][m][n] = __builtin_amdgcn_mfma_f32_16x16x32_bf16(Bt[n][k], At[m][k], acc[ai][bj][m][n], 0, 0, 0); __builtin_amdgcn_s_setprio(0); } while (0)
; #define PG8_WAIT_V(n) asm volatile("s_waitcnt vmcnt(" #n ")" ::: "memory")
; #define PG8_WAIT_L(n) asm volatile("s_waitcnt lgkmcnt(" #n ")" ::: "memory")
; #define PG8_BAR __builtin_amdgcn_s_barrier()
; #define PG8_SCHED __builtin_amdgcn_sched_barrier(0)
; template <class Epi, class Sched, bool ALIGN_EPI = false, bool SP2 = false>
; __device__ __forceinline__ void gemm_phase(LAS unsigned char* lds, const Gemm g, const Sched S, const Epi E) {
;     ...
;             PG8_LDA(At, 1, 1); PG8_STAGE(PG8_SB(1, 0), b3, voffB); PG8_STAGE(PG8_SB(1, 1), b3 + hstepB, voffB); PG8_STAGE(PG8_SA(1, 0), a3, voffA);
;             PG8_WAIT_V(8); PG8_WAIT_L(0); PG8_BAR; PG8_MMA(1, 0, At, B0); PG8_MMA(1, 1, At, B1); PG8_BAR; PG8_SCHED;
	s_mov_b32 m0, s93
	v_lshl_add_u64 v[154:155], v[154:155], 0, s[18:19]
	ds_read_b128 v[188:191], v160 offset:49152
	ds_read_b128 v[192:195], v160 offset:50176
	ds_read_b128 v[196:199], v160 offset:51200
	ds_read_b128 v[200:203], v160 offset:52224
	ds_read_b128 v[204:207], v160 offset:53248
	ds_read_b128 v[208:211], v160 offset:54272
	ds_read_b128 v[212:215], v160 offset:55296
	ds_read_b128 v[216:219], v160 offset:56320
	global_load_lds_dwordx4 v[154:155], off
	v_lshl_add_u64 v[154:155], v[220:221], 0, s[18:19]
	s_mov_b32 m0, s91
	s_nop 0
	global_load_lds_dwordx4 v[154:155], off
	v_lshl_add_u64 v[154:155], s[70:71], 0, v[130:131]
	s_mov_b32 m0, s92
	s_nop 0
	global_load_lds_dwordx4 v[154:155], off
	v_lshl_add_u64 v[154:155], s[70:71], 0, v[134:135]
	s_mov_b32 m0, s90
	s_nop 0
	global_load_lds_dwordx4 v[154:155], off
	v_lshl_add_u64 v[154:155], v[222:223], 0, s[18:19]
	s_mov_b32 m0, s44
	s_nop 0
	global_load_lds_dwordx4 v[154:155], off
	v_lshl_add_u64 v[154:155], v[224:225], 0, s[18:19]
	s_mov_b32 m0, s45
	s_nop 0
	global_load_lds_dwordx4 v[154:155], off
	s_waitcnt vmcnt(8)
	s_waitcnt lgkmcnt(0)
	s_barrier
	s_setprio 1
	s_waitcnt lgkmcnt(0)
	v_mfma_f32_16x16x32_bf16 v[60:63], v[146:149], v[188:191], v[60:63]
	v_mfma_f32_16x16x32_bf16 v[56:59], v[164:167], v[188:191], v[56:59]
	v_mfma_f32_16x16x32_bf16 v[44:47], v[146:149], v[196:199], v[44:47]
	v_mfma_f32_16x16x32_bf16 v[40:43], v[164:167], v[196:199], v[40:43]
	v_mfma_f32_16x16x32_bf16 v[28:31], v[146:149], v[204:207], v[28:31]
	v_mfma_f32_16x16x32_bf16 v[24:27], v[164:167], v[204:207], v[24:27]
	v_mfma_f32_16x16x32_bf16 v[12:15], v[146:149], v[212:215], v[12:15]
	v_mfma_f32_16x16x32_bf16 v[8:11], v[164:167], v[212:215], v[8:11]
	v_mfma_f32_16x16x32_bf16 v[60:63], v[150:153], v[192:195], v[60:63]
	v_mfma_f32_16x16x32_bf16 v[56:59], v[168:171], v[192:195], v[56:59]
	v_mfma_f32_16x16x32_bf16 v[44:47], v[150:153], v[200:203], v[44:47]
	v_mfma_f32_16x16x32_bf16 v[40:43], v[168:171], v[200:203], v[40:43]
	v_mfma_f32_16x16x32_bf16 v[28:31], v[150:153], v[208:211], v[28:31]
	v_mfma_f32_16x16x32_bf16 v[24:27], v[168:171], v[208:211], v[24:27]
	v_mfma_f32_16x16x32_bf16 v[12:15], v[150:153], v[216:219], v[12:15]
	v_mfma_f32_16x16x32_bf16 v[8:11], v[168:171], v[216:219], v[8:11]
	v_mfma_f32_16x16x32_bf16 v[52:55], v[172:175], v[188:191], v[52:55]
	v_mfma_f32_16x16x32_bf16 v[48:51], v[180:183], v[188:191], v[48:51]
	v_mfma_f32_16x16x32_bf16 v[36:39], v[172:175], v[196:199], v[36:39]
	v_mfma_f32_16x16x32_bf16 v[32:35], v[180:183], v[196:199], v[32:35]
	v_mfma_f32_16x16x32_bf16 v[20:23], v[172:175], v[204:207], v[20:23]
	v_mfma_f32_16x16x32_bf16 v[16:19], v[180:183], v[204:207], v[16:19]
	v_mfma_f32_16x16x32_bf16 v[4:7], v[172:175], v[212:215], v[4:7]
	v_mfma_f32_16x16x32_bf16 v[0:3], v[180:183], v[212:215], v[0:3]
	v_mfma_f32_16x16x32_bf16 v[52:55], v[176:179], v[192:195], v[52:55]
	v_mfma_f32_16x16x32_bf16 v[48:51], v[184:187], v[192:195], v[48:51]
	v_mfma_f32_16x16x32_bf16 v[36:39], v[176:179], v[200:203], v[36:39]
	v_mfma_f32_16x16x32_bf16 v[32:35], v[184:187], v[200:203], v[32:35]
	v_mfma_f32_16x16x32_bf16 v[20:23], v[176:179], v[208:211], v[20:23]
	v_mfma_f32_16x16x32_bf16 v[16:19], v[184:187], v[208:211], v[16:19]
	v_mfma_f32_16x16x32_bf16 v[4:7], v[176:179], v[216:219], v[4:7]
	v_mfma_f32_16x16x32_bf16 v[0:3], v[184:187], v[216:219], v[0:3]
	s_setprio 0
	s_barrier
	s_andn2_b64 vcc, exec, s[8:9]
	s_mov_b64 s[70:71], -1
	s_mov_b64 s[8:9], 0
	s_mov_b64 s[72:73], 0x100
	s_cbranch_vccz .LBB0_1437
	s_and_b64 vcc, exec, s[54:55]
	s_cbranch_vccz .LBB0_1440
	s_barrier

; #define PG8_STAGE(bufoff, gbase, voff) do { _Pragma("unroll") for (int _i = 0; _i < 2; ++_i) \
;         __builtin_amdgcn_global_load_lds((const unsigned*)((const char*)(gbase) + (voff)[_i]), (LAS unsigned*)(lds + (bufoff) + ldsw + _i * 8192), 16, 0, 0); } while (0)
; #define PG8_LDA(dst, b, h) do { _Pragma("unroll") for (int m = 0; m < 4; ++m) _Pragma("unroll") for (int k = 0; k < 2; ++k) dst[m][k] = *(const LAS bf16x8*)(lds + PG8_SA(b, h) + aoff + m * 2048 + k * 1024); } while (0)
; #define PG8_LDB(dst, b, h) do { _Pragma("unroll") for (int n = 0; n < 2; ++n) _Pragma("unroll") for (int k = 0; k < 2; ++k) dst[n][k] = *(const LAS bf16x8*)(lds + PG8_SB(b, h) + boff + n * 2048 + k * 1024); } while (0)
; #define PG8_MMA(ai, bj, At, Bt) do { __builtin_amdgcn_s_setprio(1); _Pragma("unroll") for (int m = 0; m < 4; ++m) _Pragma("unroll") for (int n = 0; n < 2; ++n) _Pragma("unroll") for (int k = 0; k < 2; ++k) \
;         acc[ai][bj][m][n] = __builtin_amdgcn_mfma_f32_16x16x32_bf16(Bt[n][k], At[m][k], acc[ai][bj][m][n], 0, 0, 0); __builtin_amdgcn_s_setprio(0); } while (0)
; #define PG8_WAIT_V(n) asm volatile("s_waitcnt vmcnt(" #n ")" ::: "memory")
; #define PG8_WAIT_L(n) asm volatile("s_waitcnt lgkmcnt(" #n ")" ::: "memory")
; #define PG8_BAR __builtin_amdgcn_s_barrier()
; #define PG8_SCHED __builtin_amdgcn_sched_barrier(0)
; template <class Epi, class Sched, bool ALIGN_EPI = false, bool SP2 = false>
; __device__ __forceinline__ void gemm_phase(LAS unsigned char* lds, const Gemm g, const Sched S, const Epi E) {
;     ...
;             PG8_LDB(B0, 0, 0); PG8_LDB(B1, 0, 1); PG8_SCHED; PG8_LDA(At, 0, 0); PG8_STAGE(PG8_SA(1, 1), a1 + hstepA, voffA);
;             PG8_WAIT_V(8); PG8_WAIT_L(0); PG8_BAR; PG8_MMA(0, 0, At, B0); PG8_MMA(0, 1, At, B1); PG8_BAR; PG8_SCHED;
;             PG8_LDA(At, 0, 1); PG8_STAGE(PG8_SB(0, 0), b2, voffB); PG8_STAGE(PG8_SB(0, 1), b2 + hstepB, voffB); PG8_STAGE(PG8_SA(0, 0), a2, voffA);
;             PG8_WAIT_V(8); PG8_WAIT_L(0); PG8_BAR; PG8_MMA(1, 0, At, B0); PG8_MMA(1, 1, At, B1); PG8_BAR; PG8_SCHED;
.LBB0_1612:
	ds_read_b128 v[152:155], v149
	ds_read_b128 v[156:159], v149 offset:1024
	ds_read_b128 v[160:163], v149 offset:2048
	ds_read_b128 v[164:167], v149 offset:3072
	ds_read_b128 v[168:171], v150
	ds_read_b128 v[172:175], v150 offset:1024
	ds_read_b128 v[176:179], v150 offset:2048
	ds_read_b128 v[180:183], v150 offset:3072
	s_add_u32 s10, s54, 0x100
	s_addc_u32 s11, s55, 0
	s_cmp_eq_u32 s71, 12
	s_cselect_b32 s59, s49, s11
	s_cselect_b32 s58, s48, s10
	s_cselect_b32 s57, s19, s70
	s_cselect_b32 s56, s68, s69
	s_add_i32 m0, s21, 0xc000
	ds_read_b128 v[184:187], v151
	ds_read_b128 v[188:191], v151 offset:1024
	ds_read_b128 v[192:195], v151 offset:2048
	ds_read_b128 v[196:199], v151 offset:3072
	ds_read_b128 v[200:203], v151 offset:4096
	ds_read_b128 v[204:207], v151 offset:5120
	ds_read_b128 v[208:211], v151 offset:6144
	ds_read_b128 v[212:215], v151 offset:7168
	global_load_lds_dwordx4 v138, s[54:55]
	s_add_i32 m0, s21, 0xe000
	s_nop 0
	global_load_lds_dwordx4 v140, s[54:55]
	s_waitcnt vmcnt(8)
	s_waitcnt lgkmcnt(0)
	s_barrier
	s_setprio 1
	s_waitcnt lgkmcnt(0)
	v_mfma_f32_16x16x32_bf16 v[124:127], v[152:155], v[184:187], v[124:127]
	v_mfma_f32_16x16x32_bf16 v[120:123], v[160:163], v[184:187], v[120:123]
	v_mfma_f32_16x16x32_bf16 v[116:119], v[152:155], v[192:195], v[116:119]
	v_mfma_f32_16x16x32_bf16 v[112:115], v[160:163], v[192:195], v[112:115]
	v_mfma_f32_16x16x32_bf16 v[100:103], v[152:155], v[200:203], v[100:103]
	v_mfma_f32_16x16x32_bf16 v[96:99], v[160:163], v[200:203], v[96:99]
	v_mfma_f32_16x16x32_bf16 v[84:87], v[152:155], v[208:211], v[84:87]
	v_mfma_f32_16x16x32_bf16 v[80:83], v[160:163], v[208:211], v[80:83]
	v_mfma_f32_16x16x32_bf16 v[124:127], v[156:159], v[188:191], v[124:127]
	v_mfma_f32_16x16x32_bf16 v[120:123], v[164:167], v[188:191], v[120:123]
	v_mfma_f32_16x16x32_bf16 v[116:119], v[156:159], v[196:199], v[116:119]
	v_mfma_f32_16x16x32_bf16 v[112:115], v[164:167], v[196:199], v[112:115]
	v_mfma_f32_16x16x32_bf16 v[100:103], v[156:159], v[204:207], v[100:103]
	v_mfma_f32_16x16x32_bf16 v[96:99], v[164:167], v[204:207], v[96:99]
	v_mfma_f32_16x16x32_bf16 v[84:87], v[156:159], v[212:215], v[84:87]
	v_mfma_f32_16x16x32_bf16 v[80:83], v[164:167], v[212:215], v[80:83]
	v_mfma_f32_16x16x32_bf16 v[108:111], v[168:171], v[184:187], v[108:111]
	v_mfma_f32_16x16x32_bf16 v[104:107], v[176:179], v[184:187], v[104:107]
	v_mfma_f32_16x16x32_bf16 v[92:95], v[168:171], v[192:195], v[92:95]
	v_mfma_f32_16x16x32_bf16 v[88:91], v[176:179], v[192:195], v[88:91]
	v_mfma_f32_16x16x32_bf16 v[76:79], v[168:171], v[200:203], v[76:79]
	v_mfma_f32_16x16x32_bf16 v[72:75], v[176:179], v[200:203], v[72:75]
	v_mfma_f32_16x16x32_bf16 v[68:71], v[168:171], v[208:211], v[68:71]
	v_mfma_f32_16x16x32_bf16 v[64:67], v[176:179], v[208:211], v[64:67]
	v_mfma_f32_16x16x32_bf16 v[108:111], v[172:175], v[188:191], v[108:111]
	v_mfma_f32_16x16x32_bf16 v[104:107], v[180:183], v[188:191], v[104:107]
	v_mfma_f32_16x16x32_bf16 v[92:95], v[172:175], v[196:199], v[92:95]
	v_mfma_f32_16x16x32_bf16 v[88:91], v[180:183], v[196:199], v[88:91]
	v_mfma_f32_16x16x32_bf16 v[76:79], v[172:175], v[204:207], v[76:79]
	v_mfma_f32_16x16x32_bf16 v[72:75], v[180:183], v[204:207], v[72:75]
	v_mfma_f32_16x16x32_bf16 v[68:71], v[172:175], v[212:215], v[68:71]
	v_mfma_f32_16x16x32_bf16 v[64:67], v[180:183], v[212:215], v[64:67]
	s_setprio 0
	s_barrier
	s_add_i32 s34, s63, s20
	v_lshl_add_u64 v[216:217], s[56:57], 0, v[130:131]
	s_mov_b32 m0, s34
	ds_read_b128 v[184:187], v151 offset:16384
	ds_read_b128 v[188:191], v151 offset:17408
	ds_read_b128 v[192:195], v151 offset:18432
	ds_read_b128 v[196:199], v151 offset:19456
	ds_read_b128 v[200:203], v151 offset:20480
	ds_read_b128 v[204:207], v151 offset:21504
	ds_read_b128 v[208:211], v151 offset:22528
	ds_read_b128 v[212:215], v151 offset:23552
	global_load_lds_dwordx4 v[216:217], off
	s_add_i32 m0, s34, 0x2000
	s_add_u32 s34, s56, 0x40000
	v_lshl_add_u64 v[218:219], s[56:57], 0, v[134:135]
	s_addc_u32 s35, s57, 0
	s_add_i32 s54, s64, s20
	global_load_lds_dwordx4 v[218:219], off
	s_mov_b32 m0, s54
	v_lshl_add_u64 v[222:223], s[58:59], 0, v[132:133]
	global_load_lds_dwordx4 v130, s[34:35]
	s_add_i32 m0, s54, 0x2000
	s_nop 0
	global_load_lds_dwordx4 v134, s[34:35]
	v_lshl_add_u64 v[220:221], s[58:59], 0, v[128:129]
	s_mov_b32 m0, s21
	s_nop 0
	global_load_lds_dwordx4 v[220:221], off
	s_mov_b32 m0, s29
	s_nop 0
	global_load_lds_dwordx4 v[222:223], off
	s_waitcnt vmcnt(8)
	s_waitcnt lgkmcnt(0)
	s_barrier
	s_setprio 1
	s_waitcnt lgkmcnt(0)
	v_mfma_f32_16x16x32_bf16 v[60:63], v[152:155], v[184:187], v[60:63]
	v_mfma_f32_16x16x32_bf16 v[56:59], v[160:163], v[184:187], v[56:59]
	v_mfma_f32_16x16x32_bf16 v[52:55], v[152:155], v[192:195], v[52:55]
	v_mfma_f32_16x16x32_bf16 v[48:51], v[160:163], v[192:195], v[48:51]
	v_mfma_f32_16x16x32_bf16 v[36:39], v[152:155], v[200:203], v[36:39]
	v_mfma_f32_16x16x32_bf16 v[32:35], v[160:163], v[200:203], v[32:35]
	v_mfma_f32_16x16x32_bf16 v[20:23], v[152:155], v[208:211], v[20:23]
	v_mfma_f32_16x16x32_bf16 v[16:19], v[160:163], v[208:211], v[16:19]
	v_mfma_f32_16x16x32_bf16 v[60:63], v[156:159], v[188:191], v[60:63]
	v_mfma_f32_16x16x32_bf16 v[56:59], v[164:167], v[188:191], v[56:59]
	v_mfma_f32_16x16x32_bf16 v[52:55], v[156:159], v[196:199], v[52:55]
	v_mfma_f32_16x16x32_bf16 v[48:51], v[164:167], v[196:199], v[48:51]
	v_mfma_f32_16x16x32_bf16 v[36:39], v[156:159], v[204:207], v[36:39]
	v_mfma_f32_16x16x32_bf16 v[32:35], v[164:167], v[204:207], v[32:35]
	v_mfma_f32_16x16x32_bf16 v[20:23], v[156:159], v[212:215], v[20:23]
	v_mfma_f32_16x16x32_bf16 v[16:19], v[164:167], v[212:215], v[16:19]
	v_mfma_f32_16x16x32_bf16 v[44:47], v[168:171], v[184:187], v[44:47]
	v_mfma_f32_16x16x32_bf16 v[40:43], v[176:179], v[184:187], v[40:43]
	v_mfma_f32_16x16x32_bf16 v[28:31], v[168:171], v[192:195], v[28:31]
	v_mfma_f32_16x16x32_bf16 v[24:27], v[176:179], v[192:195], v[24:27]
	v_mfma_f32_16x16x32_bf16 v[12:15], v[168:171], v[200:203], v[12:15]
	v_mfma_f32_16x16x32_bf16 v[8:11], v[176:179], v[200:203], v[8:11]
	v_mfma_f32_16x16x32_bf16 v[4:7], v[168:171], v[208:211], v[4:7]
	v_mfma_f32_16x16x32_bf16 v[0:3], v[176:179], v[208:211], v[0:3]
	v_mfma_f32_16x16x32_bf16 v[44:47], v[172:175], v[188:191], v[44:47]
	v_mfma_f32_16x16x32_bf16 v[40:43], v[180:183], v[188:191], v[40:43]
	v_mfma_f32_16x16x32_bf16 v[28:31], v[172:175], v[196:199], v[28:31]
	v_mfma_f32_16x16x32_bf16 v[24:27], v[180:183], v[196:199], v[24:27]
	v_mfma_f32_16x16x32_bf16 v[12:15], v[172:175], v[204:207], v[12:15]
	v_mfma_f32_16x16x32_bf16 v[8:11], v[180:183], v[204:207], v[8:11]
	v_mfma_f32_16x16x32_bf16 v[4:7], v[172:175], v[212:215], v[4:7]
	v_mfma_f32_16x16x32_bf16 v[0:3], v[180:183], v[212:215], v[0:3]
	s_setprio 0
	s_barrier
; #define PG8_STAGE(bufoff, gbase, voff) do { _Pragma("unroll") for (int _i = 0; _i < 2; ++_i) \
;         __builtin_amdgcn_global_load_lds((const unsigned*)((const char*)(gbase) + (voff)[_i]), (LAS unsigned*)(lds + (bufoff) + ldsw + _i * 8192), 16, 0, 0); } while (0)
; #define PG8_LDA(dst, b, h) do { _Pragma("unroll") for (int m = 0; m < 4; ++m) _Pragma("unroll") for (int k = 0; k < 2; ++k) dst[m][k] = *(const LAS bf16x8*)(lds + PG8_SA(b, h) + aoff + m * 2048 + k * 1024); } while (0)
; #define PG8_LDB(dst, b, h) do { _Pragma("unroll") for (int n = 0; n < 2; ++n) _Pragma("unroll") for (int k = 0; k < 2; ++k) dst[n][k] = *(const LAS bf16x8*)(lds + PG8_SB(b, h) + boff + n * 2048 + k * 1024); } while (0)
; #define PG8_MMA(ai, bj, At, Bt) do { __builtin_amdgcn_s_setprio(1); _Pragma("unroll") for (int m = 0; m < 4; ++m) _Pragma("unroll") for (int n = 0; n < 2; ++n) _Pragma("unroll") for (int k = 0; k < 2; ++k) \
;         acc[ai][bj][m][n] = __builtin_amdgcn_mfma_f32_16x16x32_bf16(Bt[n][k], At[m][k], acc[ai][bj][m][n], 0, 0, 0); __builtin_amdgcn_s_setprio(0); } while (0)
; #define PG8_WAIT_V(n) asm volatile("s_waitcnt vmcnt(" #n ")" ::: "memory")
; #define PG8_WAIT_L(n) asm volatile("s_waitcnt lgkmcnt(" #n ")" ::: "memory")
; #define PG8_BAR __builtin_amdgcn_s_barrier()
; #define PG8_SCHED __builtin_amdgcn_sched_barrier(0)
; template <class Epi, class Sched, bool ALIGN_EPI = false, bool SP2 = false>
; __device__ __forceinline__ void gemm_phase(LAS unsigned char* lds, const Gemm g, const Sched S, const Epi E) {
;     ...
;             PG8_LDB(B0, 1, 0); PG8_LDB(B1, 1, 1); PG8_SCHED; PG8_LDA(At, 1, 0); PG8_STAGE(PG8_SA(0, 1), a2 + hstepA, voffA);
;             PG8_WAIT_V(8); PG8_WAIT_L(0); PG8_BAR; PG8_MMA(0, 0, At, B0); PG8_MMA(0, 1, At, B1); PG8_BAR; PG8_SCHED;
;             PG8_LDA(At, 1, 1); PG8_STAGE(PG8_SB(1, 0), b3, voffB); PG8_STAGE(PG8_SB(1, 1), b3 + hstepB, voffB); PG8_STAGE(PG8_SA(1, 0), a3, voffA);
;             PG8_WAIT_V(8); PG8_WAIT_L(0); PG8_BAR; PG8_MMA(1, 0, At, B0); PG8_MMA(1, 1, At, B1); PG8_BAR; PG8_SCHED;
	s_add_i32 s54, 0, 0x18000
	v_add_u32_e32 v136, s54, v147
	s_add_i32 s55, 0, 0x1c000
	ds_read_b128 v[152:155], v136
	ds_read_b128 v[156:159], v136 offset:1024
	ds_read_b128 v[160:163], v136 offset:2048
	ds_read_b128 v[164:167], v136 offset:3072
	v_add_u32_e32 v136, s55, v147
	ds_read_b128 v[168:171], v136
	ds_read_b128 v[172:175], v136 offset:1024
	ds_read_b128 v[176:179], v136 offset:2048
	ds_read_b128 v[180:183], v136 offset:3072
	s_add_u32 s34, s58, 0x130000
	s_addc_u32 s35, s59, 0
	s_mov_b32 m0, s30
	ds_read_b128 v[184:187], v151 offset:32768
	ds_read_b128 v[188:191], v151 offset:33792
	ds_read_b128 v[192:195], v151 offset:34816
	ds_read_b128 v[196:199], v151 offset:35840
	ds_read_b128 v[200:203], v151 offset:36864
	ds_read_b128 v[204:207], v151 offset:37888
	ds_read_b128 v[208:211], v151 offset:38912
	ds_read_b128 v[212:215], v151 offset:39936
	global_load_lds_dwordx4 v128, s[34:35]
	s_mov_b32 m0, s31
	s_nop 0
	global_load_lds_dwordx4 v132, s[34:35]
	s_waitcnt vmcnt(8)
	s_waitcnt lgkmcnt(0)
	s_barrier
	s_setprio 1
	s_waitcnt lgkmcnt(0)
	v_mfma_f32_16x16x32_bf16 v[124:127], v[152:155], v[184:187], v[124:127]
	v_mfma_f32_16x16x32_bf16 v[120:123], v[160:163], v[184:187], v[120:123]
	v_mfma_f32_16x16x32_bf16 v[116:119], v[152:155], v[192:195], v[116:119]
	v_mfma_f32_16x16x32_bf16 v[112:115], v[160:163], v[192:195], v[112:115]
	v_mfma_f32_16x16x32_bf16 v[100:103], v[152:155], v[200:203], v[100:103]
	v_mfma_f32_16x16x32_bf16 v[96:99], v[160:163], v[200:203], v[96:99]
	v_mfma_f32_16x16x32_bf16 v[84:87], v[152:155], v[208:211], v[84:87]
	v_mfma_f32_16x16x32_bf16 v[80:83], v[160:163], v[208:211], v[80:83]
	v_mfma_f32_16x16x32_bf16 v[124:127], v[156:159], v[188:191], v[124:127]
	v_mfma_f32_16x16x32_bf16 v[120:123], v[164:167], v[188:191], v[120:123]
	v_mfma_f32_16x16x32_bf16 v[116:119], v[156:159], v[196:199], v[116:119]
	v_mfma_f32_16x16x32_bf16 v[112:115], v[164:167], v[196:199], v[112:115]
	v_mfma_f32_16x16x32_bf16 v[100:103], v[156:159], v[204:207], v[100:103]
	v_mfma_f32_16x16x32_bf16 v[96:99], v[164:167], v[204:207], v[96:99]
	v_mfma_f32_16x16x32_bf16 v[84:87], v[156:159], v[212:215], v[84:87]
	v_mfma_f32_16x16x32_bf16 v[80:83], v[164:167], v[212:215], v[80:83]
	v_mfma_f32_16x16x32_bf16 v[108:111], v[168:171], v[184:187], v[108:111]
	v_mfma_f32_16x16x32_bf16 v[104:107], v[176:179], v[184:187], v[104:107]
	v_mfma_f32_16x16x32_bf16 v[92:95], v[168:171], v[192:195], v[92:95]
	v_mfma_f32_16x16x32_bf16 v[88:91], v[176:179], v[192:195], v[88:91]
	v_mfma_f32_16x16x32_bf16 v[76:79], v[168:171], v[200:203], v[76:79]
	v_mfma_f32_16x16x32_bf16 v[72:75], v[176:179], v[200:203], v[72:75]
	v_mfma_f32_16x16x32_bf16 v[68:71], v[168:171], v[208:211], v[68:71]
	v_mfma_f32_16x16x32_bf16 v[64:67], v[176:179], v[208:211], v[64:67]
	v_mfma_f32_16x16x32_bf16 v[108:111], v[172:175], v[188:191], v[108:111]
	v_mfma_f32_16x16x32_bf16 v[104:107], v[180:183], v[188:191], v[104:107]
	v_mfma_f32_16x16x32_bf16 v[92:95], v[172:175], v[196:199], v[92:95]
	v_mfma_f32_16x16x32_bf16 v[88:91], v[180:183], v[196:199], v[88:91]
	v_mfma_f32_16x16x32_bf16 v[76:79], v[172:175], v[204:207], v[76:79]
	v_mfma_f32_16x16x32_bf16 v[72:75], v[180:183], v[204:207], v[72:75]
	v_mfma_f32_16x16x32_bf16 v[68:71], v[172:175], v[212:215], v[68:71]
	v_mfma_f32_16x16x32_bf16 v[64:67], v[180:183], v[212:215], v[64:67]
	s_setprio 0
	s_barrier
	s_add_i32 s34, s54, s20
	v_lshl_add_u64 v[216:217], v[216:217], 0, s[14:15]
	s_mov_b32 m0, s34
	ds_read_b128 v[184:187], v151 offset:49152
	ds_read_b128 v[188:191], v151 offset:50176
	ds_read_b128 v[192:195], v151 offset:51200
	ds_read_b128 v[196:199], v151 offset:52224
	ds_read_b128 v[200:203], v151 offset:53248
	ds_read_b128 v[204:207], v151 offset:54272
	ds_read_b128 v[208:211], v151 offset:55296
	ds_read_b128 v[212:215], v151 offset:56320
	global_load_lds_dwordx4 v[216:217], off
	s_add_i32 m0, s34, 0x2000
	s_add_u32 s34, s56, 0x40080
	v_lshl_add_u64 v[216:217], v[218:219], 0, s[14:15]
	s_addc_u32 s35, s57, 0
	s_add_i32 s54, s55, s20
	global_load_lds_dwordx4 v[216:217], off
	s_mov_b32 m0, s54
	s_nop 0
	global_load_lds_dwordx4 v130, s[34:35]
	s_add_i32 m0, s54, 0x2000
	s_nop 0
	global_load_lds_dwordx4 v134, s[34:35]
	v_lshl_add_u64 v[216:217], v[220:221], 0, s[14:15]
	s_mov_b32 m0, s45
	s_nop 0
	global_load_lds_dwordx4 v[216:217], off
	v_lshl_add_u64 v[216:217], v[222:223], 0, s[14:15]
	s_mov_b32 m0, s60
	s_nop 0
	global_load_lds_dwordx4 v[216:217], off
	s_waitcnt vmcnt(8)
	s_waitcnt lgkmcnt(0)
	s_barrier
	s_setprio 1
	s_waitcnt lgkmcnt(0)
	v_mfma_f32_16x16x32_bf16 v[60:63], v[152:155], v[184:187], v[60:63]
	v_mfma_f32_16x16x32_bf16 v[56:59], v[160:163], v[184:187], v[56:59]
	v_mfma_f32_16x16x32_bf16 v[52:55], v[152:155], v[192:195], v[52:55]
	v_mfma_f32_16x16x32_bf16 v[48:51], v[160:163], v[192:195], v[48:51]
	v_mfma_f32_16x16x32_bf16 v[36:39], v[152:155], v[200:203], v[36:39]
	v_mfma_f32_16x16x32_bf16 v[32:35], v[160:163], v[200:203], v[32:35]
	v_mfma_f32_16x16x32_bf16 v[20:23], v[152:155], v[208:211], v[20:23]
	v_mfma_f32_16x16x32_bf16 v[16:19], v[160:163], v[208:211], v[16:19]
	v_mfma_f32_16x16x32_bf16 v[60:63], v[156:159], v[188:191], v[60:63]
	v_mfma_f32_16x16x32_bf16 v[56:59], v[164:167], v[188:191], v[56:59]
	v_mfma_f32_16x16x32_bf16 v[52:55], v[156:159], v[196:199], v[52:55]
	v_mfma_f32_16x16x32_bf16 v[48:51], v[164:167], v[196:199], v[48:51]
	v_mfma_f32_16x16x32_bf16 v[36:39], v[156:159], v[204:207], v[36:39]
	v_mfma_f32_16x16x32_bf16 v[32:35], v[164:167], v[204:207], v[32:35]
	v_mfma_f32_16x16x32_bf16 v[20:23], v[156:159], v[212:215], v[20:23]
	v_mfma_f32_16x16x32_bf16 v[16:19], v[164:167], v[212:215], v[16:19]
	v_mfma_f32_16x16x32_bf16 v[44:47], v[168:171], v[184:187], v[44:47]
	v_mfma_f32_16x16x32_bf16 v[40:43], v[176:179], v[184:187], v[40:43]
	v_mfma_f32_16x16x32_bf16 v[28:31], v[168:171], v[192:195], v[28:31]
	v_mfma_f32_16x16x32_bf16 v[24:27], v[176:179], v[192:195], v[24:27]
	v_mfma_f32_16x16x32_bf16 v[12:15], v[168:171], v[200:203], v[12:15]
	v_mfma_f32_16x16x32_bf16 v[8:11], v[176:179], v[200:203], v[8:11]
	v_mfma_f32_16x16x32_bf16 v[4:7], v[168:171], v[208:211], v[4:7]
	v_mfma_f32_16x16x32_bf16 v[0:3], v[176:179], v[208:211], v[0:3]
	v_mfma_f32_16x16x32_bf16 v[44:47], v[172:175], v[188:191], v[44:47]
	v_mfma_f32_16x16x32_bf16 v[40:43], v[180:183], v[188:191], v[40:43]
	v_mfma_f32_16x16x32_bf16 v[28:31], v[172:175], v[196:199], v[28:31]
	v_mfma_f32_16x16x32_bf16 v[24:27], v[180:183], v[196:199], v[24:27]
	v_mfma_f32_16x16x32_bf16 v[12:15], v[172:175], v[204:207], v[12:15]
	v_mfma_f32_16x16x32_bf16 v[8:11], v[180:183], v[204:207], v[8:11]
	v_mfma_f32_16x16x32_bf16 v[4:7], v[172:175], v[212:215], v[4:7]
	v_mfma_f32_16x16x32_bf16 v[0:3], v[180:183], v[212:215], v[0:3]
	s_setprio 0
	s_add_i32 s71, s71, 2
	s_add_u32 s69, s69, 0x100
	s_addc_u32 s70, s70, 0
	s_cmp_gt_u32 s71, 13
	s_mov_b64 s[54:55], s[10:11]
	s_barrier
	s_cbranch_scc0 .LBB0_1612
	s_and_b64 vcc, exec, s[16:17]
	s_cbranch_vccz .LBB0_1615
	s_barrier

; #define PG8_STAGE(bufoff, gbase, voff) do { _Pragma("unroll") for (int _i = 0; _i < 2; ++_i) \
;         __builtin_amdgcn_global_load_lds((const unsigned*)((const char*)(gbase) + (voff)[_i]), (LAS unsigned*)(lds + (bufoff) + ldsw + _i * 8192), 16, 0, 0); } while (0)
; #define PG8_LDA(dst, b, h) do { _Pragma("unroll") for (int m = 0; m < 4; ++m) _Pragma("unroll") for (int k = 0; k < 2; ++k) dst[m][k] = *(const LAS bf16x8*)(lds + PG8_SA(b, h) + aoff + m * 2048 + k * 1024); } while (0)
; #define PG8_LDB(dst, b, h) do { _Pragma("unroll") for (int n = 0; n < 2; ++n) _Pragma("unroll") for (int k = 0; k < 2; ++k) dst[n][k] = *(const LAS bf16x8*)(lds + PG8_SB(b, h) + boff + n * 2048 + k * 1024); } while (0)
; #define PG8_MMA(ai, bj, At, Bt) do { __builtin_amdgcn_s_setprio(1); _Pragma("unroll") for (int m = 0; m < 4; ++m) _Pragma("unroll") for (int n = 0; n < 2; ++n) _Pragma("unroll") for (int k = 0; k < 2; ++k) \
;         acc[ai][bj][m][n] = __builtin_amdgcn_mfma_f32_16x16x32_bf16(Bt[n][k], At[m][k], acc[ai][bj][m][n], 0, 0, 0); __builtin_amdgcn_s_setprio(0); } while (0)
; #define PG8_WAIT_V(n) asm volatile("s_waitcnt vmcnt(" #n ")" ::: "memory")
; #define PG8_WAIT_L(n) asm volatile("s_waitcnt lgkmcnt(" #n ")" ::: "memory")
; #define PG8_BAR __builtin_amdgcn_s_barrier()
; #define PG8_SCHED __builtin_amdgcn_sched_barrier(0)
; template <class Epi, class Sched, bool ALIGN_EPI = false, bool SP2 = false>
; __device__ __forceinline__ void gemm_phase(LAS unsigned char* lds, const Gemm g, const Sched S, const Epi E) {
;     ...
;             PG8_LDB(B0, 0, 0); PG8_LDB(B1, 0, 1); PG8_SCHED; PG8_LDA(At, 0, 0); PG8_STAGE(PG8_SA(1, 1), a1 + hstepA, voffA);
;             PG8_WAIT_V(8); PG8_WAIT_L(0); PG8_BAR; PG8_MMA(0, 0, At, B0); PG8_MMA(0, 1, At, B1); PG8_BAR; PG8_SCHED;
;             PG8_LDA(At, 0, 1); PG8_STAGE(PG8_SB(0, 0), b2, voffB); PG8_STAGE(PG8_SB(0, 1), b2 + hstepB, voffB); PG8_STAGE(PG8_SA(0, 0), a2, voffA);
;             PG8_WAIT_V(8); PG8_WAIT_L(0); PG8_BAR; PG8_MMA(1, 0, At, B0); PG8_MMA(1, 1, At, B1); PG8_BAR; PG8_SCHED;
.LBB0_1688:
	ds_read_b128 v[128:131], v167
	ds_read_b128 v[132:135], v167 offset:1024
	ds_read_b128 v[152:155], v167 offset:2048
	ds_read_b128 v[156:159], v167 offset:3072
	ds_read_b128 v[160:163], v168
	ds_read_b128 v[172:175], v168 offset:1024
	ds_read_b128 v[176:179], v168 offset:2048
	ds_read_b128 v[180:183], v168 offset:3072
	s_add_u32 s34, s52, 0xfff80080
	s_addc_u32 s35, s53, -1
	s_cmp_eq_u32 s66, 12
	s_cselect_b32 s57, s19, s35
	s_cselect_b32 s56, s62, s34
	s_cselect_b32 s55, s17, s65
	s_cselect_b32 s54, s63, s64
	s_add_i32 m0, s5, 0xc000
	ds_read_b128 v[184:187], v169
	ds_read_b128 v[188:191], v169 offset:1024
	ds_read_b128 v[192:195], v169 offset:2048
	ds_read_b128 v[196:199], v169 offset:3072
	ds_read_b128 v[200:203], v169 offset:4096
	ds_read_b128 v[204:207], v169 offset:5120
	ds_read_b128 v[208:211], v169 offset:6144
	ds_read_b128 v[212:215], v169 offset:7168
	global_load_lds_dwordx4 v144, s[52:53]
	s_add_i32 m0, s5, 0xe000
	s_nop 0
	global_load_lds_dwordx4 v146, s[52:53]
	s_waitcnt vmcnt(8)
	s_waitcnt lgkmcnt(0)
	s_barrier
	s_setprio 1
	s_waitcnt lgkmcnt(0)
	v_mfma_f32_16x16x32_bf16 v[124:127], v[128:131], v[184:187], v[124:127]
	v_mfma_f32_16x16x32_bf16 v[120:123], v[152:155], v[184:187], v[120:123]
	v_mfma_f32_16x16x32_bf16 v[108:111], v[128:131], v[192:195], v[108:111]
	v_mfma_f32_16x16x32_bf16 v[104:107], v[152:155], v[192:195], v[104:107]
	v_mfma_f32_16x16x32_bf16 v[92:95], v[128:131], v[200:203], v[92:95]
	v_mfma_f32_16x16x32_bf16 v[88:91], v[152:155], v[200:203], v[88:91]
	v_mfma_f32_16x16x32_bf16 v[76:79], v[128:131], v[208:211], v[76:79]
	v_mfma_f32_16x16x32_bf16 v[72:75], v[152:155], v[208:211], v[72:75]
	v_mfma_f32_16x16x32_bf16 v[124:127], v[132:135], v[188:191], v[124:127]
	v_mfma_f32_16x16x32_bf16 v[120:123], v[156:159], v[188:191], v[120:123]
	v_mfma_f32_16x16x32_bf16 v[108:111], v[132:135], v[196:199], v[108:111]
	v_mfma_f32_16x16x32_bf16 v[104:107], v[156:159], v[196:199], v[104:107]
	v_mfma_f32_16x16x32_bf16 v[92:95], v[132:135], v[204:207], v[92:95]
	v_mfma_f32_16x16x32_bf16 v[88:91], v[156:159], v[204:207], v[88:91]
	v_mfma_f32_16x16x32_bf16 v[76:79], v[132:135], v[212:215], v[76:79]
	v_mfma_f32_16x16x32_bf16 v[72:75], v[156:159], v[212:215], v[72:75]
	v_mfma_f32_16x16x32_bf16 v[116:119], v[160:163], v[184:187], v[116:119]
	v_mfma_f32_16x16x32_bf16 v[112:115], v[176:179], v[184:187], v[112:115]
	v_mfma_f32_16x16x32_bf16 v[100:103], v[160:163], v[192:195], v[100:103]
	v_mfma_f32_16x16x32_bf16 v[96:99], v[176:179], v[192:195], v[96:99]
	v_mfma_f32_16x16x32_bf16 v[84:87], v[160:163], v[200:203], v[84:87]
	v_mfma_f32_16x16x32_bf16 v[80:83], v[176:179], v[200:203], v[80:83]
	v_mfma_f32_16x16x32_bf16 v[68:71], v[160:163], v[208:211], v[68:71]
	v_mfma_f32_16x16x32_bf16 v[64:67], v[176:179], v[208:211], v[64:67]
	v_mfma_f32_16x16x32_bf16 v[116:119], v[172:175], v[188:191], v[116:119]
	v_mfma_f32_16x16x32_bf16 v[112:115], v[180:183], v[188:191], v[112:115]
	v_mfma_f32_16x16x32_bf16 v[100:103], v[172:175], v[196:199], v[100:103]
	v_mfma_f32_16x16x32_bf16 v[96:99], v[180:183], v[196:199], v[96:99]
	v_mfma_f32_16x16x32_bf16 v[84:87], v[172:175], v[204:207], v[84:87]
	v_mfma_f32_16x16x32_bf16 v[80:83], v[180:183], v[204:207], v[80:83]
	v_mfma_f32_16x16x32_bf16 v[68:71], v[172:175], v[212:215], v[68:71]
	v_mfma_f32_16x16x32_bf16 v[64:67], v[180:183], v[212:215], v[64:67]
	s_setprio 0
	s_barrier
	s_add_i32 s34, s58, s4
	v_lshl_add_u64 v[216:217], s[54:55], 0, v[138:139]
	s_mov_b32 m0, s34
	ds_read_b128 v[184:187], v169 offset:16384
	ds_read_b128 v[188:191], v169 offset:17408
	ds_read_b128 v[192:195], v169 offset:18432
	ds_read_b128 v[196:199], v169 offset:19456
	ds_read_b128 v[200:203], v169 offset:20480
	ds_read_b128 v[204:207], v169 offset:21504
	ds_read_b128 v[208:211], v169 offset:22528
	ds_read_b128 v[212:215], v169 offset:23552
	global_load_lds_dwordx4 v[216:217], off
	s_add_i32 m0, s34, 0x2000
	s_add_u32 s34, s54, 0x40000
	v_lshl_add_u64 v[218:219], s[54:55], 0, v[142:143]
	s_addc_u32 s35, s55, 0
	s_add_i32 s67, s59, s4
	global_load_lds_dwordx4 v[218:219], off
	s_mov_b32 m0, s67
	v_lshl_add_u64 v[222:223], s[56:57], 0, v[140:141]
	global_load_lds_dwordx4 v138, s[34:35]
	s_add_i32 m0, s67, 0x2000
	s_nop 0
	global_load_lds_dwordx4 v142, s[34:35]
	v_lshl_add_u64 v[220:221], s[56:57], 0, v[136:137]
	s_mov_b32 m0, s5
	s_nop 0
	global_load_lds_dwordx4 v[220:221], off
	s_mov_b32 m0, s20
	s_nop 0
	global_load_lds_dwordx4 v[222:223], off
	s_waitcnt vmcnt(8)
	s_waitcnt lgkmcnt(0)
	s_barrier
	s_setprio 1
	s_waitcnt lgkmcnt(0)
	v_mfma_f32_16x16x32_bf16 v[60:63], v[128:131], v[184:187], v[60:63]
	v_mfma_f32_16x16x32_bf16 v[56:59], v[152:155], v[184:187], v[56:59]
	v_mfma_f32_16x16x32_bf16 v[44:47], v[128:131], v[192:195], v[44:47]
	v_mfma_f32_16x16x32_bf16 v[40:43], v[152:155], v[192:195], v[40:43]
	v_mfma_f32_16x16x32_bf16 v[28:31], v[128:131], v[200:203], v[28:31]
	v_mfma_f32_16x16x32_bf16 v[24:27], v[152:155], v[200:203], v[24:27]
	v_mfma_f32_16x16x32_bf16 v[12:15], v[128:131], v[208:211], v[12:15]
	v_mfma_f32_16x16x32_bf16 v[8:11], v[152:155], v[208:211], v[8:11]
	v_mfma_f32_16x16x32_bf16 v[60:63], v[132:135], v[188:191], v[60:63]
	v_mfma_f32_16x16x32_bf16 v[56:59], v[156:159], v[188:191], v[56:59]
	v_mfma_f32_16x16x32_bf16 v[44:47], v[132:135], v[196:199], v[44:47]
	v_mfma_f32_16x16x32_bf16 v[40:43], v[156:159], v[196:199], v[40:43]
	v_mfma_f32_16x16x32_bf16 v[28:31], v[132:135], v[204:207], v[28:31]
	v_mfma_f32_16x16x32_bf16 v[24:27], v[156:159], v[204:207], v[24:27]
	v_mfma_f32_16x16x32_bf16 v[12:15], v[132:135], v[212:215], v[12:15]
	v_mfma_f32_16x16x32_bf16 v[8:11], v[156:159], v[212:215], v[8:11]
	v_mfma_f32_16x16x32_bf16 v[52:55], v[160:163], v[184:187], v[52:55]
	v_mfma_f32_16x16x32_bf16 v[48:51], v[176:179], v[184:187], v[48:51]
	v_mfma_f32_16x16x32_bf16 v[36:39], v[160:163], v[192:195], v[36:39]
	v_mfma_f32_16x16x32_bf16 v[32:35], v[176:179], v[192:195], v[32:35]
	v_mfma_f32_16x16x32_bf16 v[20:23], v[160:163], v[200:203], v[20:23]
	v_mfma_f32_16x16x32_bf16 v[16:19], v[176:179], v[200:203], v[16:19]
	v_mfma_f32_16x16x32_bf16 v[4:7], v[160:163], v[208:211], v[4:7]
	v_mfma_f32_16x16x32_bf16 v[0:3], v[176:179], v[208:211], v[0:3]
	v_mfma_f32_16x16x32_bf16 v[52:55], v[172:175], v[188:191], v[52:55]
	v_mfma_f32_16x16x32_bf16 v[48:51], v[180:183], v[188:191], v[48:51]
	v_mfma_f32_16x16x32_bf16 v[36:39], v[172:175], v[196:199], v[36:39]
	v_mfma_f32_16x16x32_bf16 v[32:35], v[180:183], v[196:199], v[32:35]
	v_mfma_f32_16x16x32_bf16 v[20:23], v[172:175], v[204:207], v[20:23]
	v_mfma_f32_16x16x32_bf16 v[16:19], v[180:183], v[204:207], v[16:19]
	v_mfma_f32_16x16x32_bf16 v[4:7], v[172:175], v[212:215], v[4:7]
	v_mfma_f32_16x16x32_bf16 v[0:3], v[180:183], v[212:215], v[0:3]
	s_setprio 0
	s_barrier
; #define PG8_STAGE(bufoff, gbase, voff) do { _Pragma("unroll") for (int _i = 0; _i < 2; ++_i) \
;         __builtin_amdgcn_global_load_lds((const unsigned*)((const char*)(gbase) + (voff)[_i]), (LAS unsigned*)(lds + (bufoff) + ldsw + _i * 8192), 16, 0, 0); } while (0)
; #define PG8_LDA(dst, b, h) do { _Pragma("unroll") for (int m = 0; m < 4; ++m) _Pragma("unroll") for (int k = 0; k < 2; ++k) dst[m][k] = *(const LAS bf16x8*)(lds + PG8_SA(b, h) + aoff + m * 2048 + k * 1024); } while (0)
; #define PG8_LDB(dst, b, h) do { _Pragma("unroll") for (int n = 0; n < 2; ++n) _Pragma("unroll") for (int k = 0; k < 2; ++k) dst[n][k] = *(const LAS bf16x8*)(lds + PG8_SB(b, h) + boff + n * 2048 + k * 1024); } while (0)
; #define PG8_MMA(ai, bj, At, Bt) do { __builtin_amdgcn_s_setprio(1); _Pragma("unroll") for (int m = 0; m < 4; ++m) _Pragma("unroll") for (int n = 0; n < 2; ++n) _Pragma("unroll") for (int k = 0; k < 2; ++k) \
;         acc[ai][bj][m][n] = __builtin_amdgcn_mfma_f32_16x16x32_bf16(Bt[n][k], At[m][k], acc[ai][bj][m][n], 0, 0, 0); __builtin_amdgcn_s_setprio(0); } while (0)
; #define PG8_WAIT_V(n) asm volatile("s_waitcnt vmcnt(" #n ")" ::: "memory")
; #define PG8_WAIT_L(n) asm volatile("s_waitcnt lgkmcnt(" #n ")" ::: "memory")
; #define PG8_BAR __builtin_amdgcn_s_barrier()
; #define PG8_SCHED __builtin_amdgcn_sched_barrier(0)
; template <class Epi, class Sched, bool ALIGN_EPI = false, bool SP2 = false>
; __device__ __forceinline__ void gemm_phase(LAS unsigned char* lds, const Gemm g, const Sched S, const Epi E) {
;     ...
;             PG8_LDB(B0, 1, 0); PG8_LDB(B1, 1, 1); PG8_SCHED; PG8_LDA(At, 1, 0); PG8_STAGE(PG8_SA(0, 1), a2 + hstepA, voffA);
;             PG8_WAIT_V(8); PG8_WAIT_L(0); PG8_BAR; PG8_MMA(0, 0, At, B0); PG8_MMA(0, 1, At, B1); PG8_BAR; PG8_SCHED;
;             PG8_LDA(At, 1, 1); PG8_STAGE(PG8_SB(1, 0), b3, voffB); PG8_STAGE(PG8_SB(1, 1), b3 + hstepB, voffB); PG8_STAGE(PG8_SA(1, 0), a3, voffA);
;             PG8_WAIT_V(8); PG8_WAIT_L(0); PG8_BAR; PG8_MMA(1, 0, At, B0); PG8_MMA(1, 1, At, B1); PG8_BAR; PG8_SCHED;
	s_add_i32 s67, 0, 0x18000
	s_add_i32 s68, 0, 0x1c000
	v_add_u32_e32 v156, s67, v165
	v_add_u32_e32 v171, s68, v165
	ds_read_b128 v[128:131], v156
	ds_read_b128 v[132:135], v156 offset:1024
	ds_read_b128 v[152:155], v156 offset:2048
	ds_read_b128 v[156:159], v156 offset:3072
	ds_read_b128 v[160:163], v171
	ds_read_b128 v[172:175], v171 offset:1024
	ds_read_b128 v[176:179], v171 offset:2048
	ds_read_b128 v[180:183], v171 offset:3072
	s_add_u32 s34, s56, 0x80000
	s_addc_u32 s35, s57, 0
	s_mov_b32 m0, s21
	ds_read_b128 v[184:187], v169 offset:32768
	ds_read_b128 v[188:191], v169 offset:33792
	ds_read_b128 v[192:195], v169 offset:34816
	ds_read_b128 v[196:199], v169 offset:35840
	ds_read_b128 v[200:203], v169 offset:36864
	ds_read_b128 v[204:207], v169 offset:37888
	ds_read_b128 v[208:211], v169 offset:38912
	ds_read_b128 v[212:215], v169 offset:39936
	global_load_lds_dwordx4 v136, s[34:35]
	s_mov_b32 m0, s29
	s_nop 0
	global_load_lds_dwordx4 v140, s[34:35]
	s_waitcnt vmcnt(8)
	s_waitcnt lgkmcnt(0)
	s_barrier
	s_setprio 1
	s_waitcnt lgkmcnt(0)
	v_mfma_f32_16x16x32_bf16 v[124:127], v[128:131], v[184:187], v[124:127]
	v_mfma_f32_16x16x32_bf16 v[120:123], v[152:155], v[184:187], v[120:123]
	v_mfma_f32_16x16x32_bf16 v[108:111], v[128:131], v[192:195], v[108:111]
	v_mfma_f32_16x16x32_bf16 v[104:107], v[152:155], v[192:195], v[104:107]
	v_mfma_f32_16x16x32_bf16 v[92:95], v[128:131], v[200:203], v[92:95]
	v_mfma_f32_16x16x32_bf16 v[88:91], v[152:155], v[200:203], v[88:91]
	v_mfma_f32_16x16x32_bf16 v[76:79], v[128:131], v[208:211], v[76:79]
	v_mfma_f32_16x16x32_bf16 v[72:75], v[152:155], v[208:211], v[72:75]
	v_mfma_f32_16x16x32_bf16 v[124:127], v[132:135], v[188:191], v[124:127]
	v_mfma_f32_16x16x32_bf16 v[120:123], v[156:159], v[188:191], v[120:123]
	v_mfma_f32_16x16x32_bf16 v[108:111], v[132:135], v[196:199], v[108:111]
	v_mfma_f32_16x16x32_bf16 v[104:107], v[156:159], v[196:199], v[104:107]
	v_mfma_f32_16x16x32_bf16 v[92:95], v[132:135], v[204:207], v[92:95]
	v_mfma_f32_16x16x32_bf16 v[88:91], v[156:159], v[204:207], v[88:91]
	v_mfma_f32_16x16x32_bf16 v[76:79], v[132:135], v[212:215], v[76:79]
	v_mfma_f32_16x16x32_bf16 v[72:75], v[156:159], v[212:215], v[72:75]
	v_mfma_f32_16x16x32_bf16 v[116:119], v[160:163], v[184:187], v[116:119]
	v_mfma_f32_16x16x32_bf16 v[112:115], v[176:179], v[184:187], v[112:115]
	v_mfma_f32_16x16x32_bf16 v[100:103], v[160:163], v[192:195], v[100:103]
	v_mfma_f32_16x16x32_bf16 v[96:99], v[176:179], v[192:195], v[96:99]
	v_mfma_f32_16x16x32_bf16 v[84:87], v[160:163], v[200:203], v[84:87]
	v_mfma_f32_16x16x32_bf16 v[80:83], v[176:179], v[200:203], v[80:83]
	v_mfma_f32_16x16x32_bf16 v[68:71], v[160:163], v[208:211], v[68:71]
	v_mfma_f32_16x16x32_bf16 v[64:67], v[176:179], v[208:211], v[64:67]
	v_mfma_f32_16x16x32_bf16 v[116:119], v[172:175], v[188:191], v[116:119]
	v_mfma_f32_16x16x32_bf16 v[112:115], v[180:183], v[188:191], v[112:115]
	v_mfma_f32_16x16x32_bf16 v[100:103], v[172:175], v[196:199], v[100:103]
	v_mfma_f32_16x16x32_bf16 v[96:99], v[180:183], v[196:199], v[96:99]
	v_mfma_f32_16x16x32_bf16 v[84:87], v[172:175], v[204:207], v[84:87]
	v_mfma_f32_16x16x32_bf16 v[80:83], v[180:183], v[204:207], v[80:83]
	v_mfma_f32_16x16x32_bf16 v[68:71], v[172:175], v[212:215], v[68:71]
	v_mfma_f32_16x16x32_bf16 v[64:67], v[180:183], v[212:215], v[64:67]
	s_setprio 0
	s_barrier
	s_add_i32 s34, s67, s4
	v_lshl_add_u64 v[216:217], v[216:217], 0, s[12:13]
	s_mov_b32 m0, s34
	ds_read_b128 v[184:187], v169 offset:49152
	ds_read_b128 v[188:191], v169 offset:50176
	ds_read_b128 v[192:195], v169 offset:51200
	ds_read_b128 v[196:199], v169 offset:52224
	ds_read_b128 v[200:203], v169 offset:53248
	ds_read_b128 v[204:207], v169 offset:54272
	ds_read_b128 v[208:211], v169 offset:55296
	ds_read_b128 v[212:215], v169 offset:56320
	global_load_lds_dwordx4 v[216:217], off
	s_add_i32 m0, s34, 0x2000
	s_add_u32 s34, s54, 0x40080
	v_lshl_add_u64 v[216:217], v[218:219], 0, s[12:13]
	s_addc_u32 s35, s55, 0
	s_add_i32 s54, s68, s4
	global_load_lds_dwordx4 v[216:217], off
	s_mov_b32 m0, s54
	s_nop 0
	global_load_lds_dwordx4 v138, s[34:35]
	s_add_i32 m0, s54, 0x2000
	s_nop 0
	global_load_lds_dwordx4 v142, s[34:35]
	v_lshl_add_u64 v[216:217], v[220:221], 0, s[12:13]
	s_mov_b32 m0, s31
	s_nop 0
	global_load_lds_dwordx4 v[216:217], off
	v_lshl_add_u64 v[216:217], v[222:223], 0, s[12:13]
	s_mov_b32 m0, s33
	s_nop 0
	global_load_lds_dwordx4 v[216:217], off
	s_waitcnt vmcnt(8)
	s_waitcnt lgkmcnt(0)
	s_barrier
	s_setprio 1
	s_waitcnt lgkmcnt(0)
	v_mfma_f32_16x16x32_bf16 v[60:63], v[128:131], v[184:187], v[60:63]
	v_mfma_f32_16x16x32_bf16 v[56:59], v[152:155], v[184:187], v[56:59]
	v_mfma_f32_16x16x32_bf16 v[44:47], v[128:131], v[192:195], v[44:47]
	v_mfma_f32_16x16x32_bf16 v[40:43], v[152:155], v[192:195], v[40:43]
	v_mfma_f32_16x16x32_bf16 v[28:31], v[128:131], v[200:203], v[28:31]
	v_mfma_f32_16x16x32_bf16 v[24:27], v[152:155], v[200:203], v[24:27]
	v_mfma_f32_16x16x32_bf16 v[12:15], v[128:131], v[208:211], v[12:15]
	v_mfma_f32_16x16x32_bf16 v[8:11], v[152:155], v[208:211], v[8:11]
	v_mfma_f32_16x16x32_bf16 v[60:63], v[132:135], v[188:191], v[60:63]
	v_mfma_f32_16x16x32_bf16 v[56:59], v[156:159], v[188:191], v[56:59]
	v_mfma_f32_16x16x32_bf16 v[44:47], v[132:135], v[196:199], v[44:47]
	v_mfma_f32_16x16x32_bf16 v[40:43], v[156:159], v[196:199], v[40:43]
	v_mfma_f32_16x16x32_bf16 v[28:31], v[132:135], v[204:207], v[28:31]
	v_mfma_f32_16x16x32_bf16 v[24:27], v[156:159], v[204:207], v[24:27]
	v_mfma_f32_16x16x32_bf16 v[12:15], v[132:135], v[212:215], v[12:15]
	v_mfma_f32_16x16x32_bf16 v[8:11], v[156:159], v[212:215], v[8:11]
	v_mfma_f32_16x16x32_bf16 v[52:55], v[160:163], v[184:187], v[52:55]
	v_mfma_f32_16x16x32_bf16 v[48:51], v[176:179], v[184:187], v[48:51]
	v_mfma_f32_16x16x32_bf16 v[36:39], v[160:163], v[192:195], v[36:39]
	v_mfma_f32_16x16x32_bf16 v[32:35], v[176:179], v[192:195], v[32:35]
	v_mfma_f32_16x16x32_bf16 v[20:23], v[160:163], v[200:203], v[20:23]
	v_mfma_f32_16x16x32_bf16 v[16:19], v[176:179], v[200:203], v[16:19]
	v_mfma_f32_16x16x32_bf16 v[4:7], v[160:163], v[208:211], v[4:7]
	v_mfma_f32_16x16x32_bf16 v[0:3], v[176:179], v[208:211], v[0:3]
	v_mfma_f32_16x16x32_bf16 v[52:55], v[172:175], v[188:191], v[52:55]
	v_mfma_f32_16x16x32_bf16 v[48:51], v[180:183], v[188:191], v[48:51]
	v_mfma_f32_16x16x32_bf16 v[36:39], v[172:175], v[196:199], v[36:39]
	v_mfma_f32_16x16x32_bf16 v[32:35], v[180:183], v[196:199], v[32:35]
	v_mfma_f32_16x16x32_bf16 v[20:23], v[172:175], v[204:207], v[20:23]
	v_mfma_f32_16x16x32_bf16 v[16:19], v[180:183], v[204:207], v[16:19]
	v_mfma_f32_16x16x32_bf16 v[4:7], v[172:175], v[212:215], v[4:7]
	v_mfma_f32_16x16x32_bf16 v[0:3], v[180:183], v[212:215], v[0:3]
	s_setprio 0
	s_add_i32 s66, s66, 2
	s_add_u32 s52, s52, 0x100
	s_addc_u32 s53, s53, 0
	s_add_u32 s64, s64, 0x100
	s_addc_u32 s65, s65, 0
	s_cmp_gt_u32 s66, 13
	s_barrier
	s_cbranch_scc0 .LBB0_1688
	s_and_b64 vcc, exec, s[14:15]
	s_cbranch_vccz .LBB0_1691
	s_barrier

; #define PG8_STAGE(bufoff, gbase, voff) do { _Pragma("unroll") for (int _i = 0; _i < 2; ++_i) \
;         __builtin_amdgcn_global_load_lds((const unsigned*)((const char*)(gbase) + (voff)[_i]), (LAS unsigned*)(lds + (bufoff) + ldsw + _i * 8192), 16, 0, 0); } while (0)
; #define PG8_LDA(dst, b, h) do { _Pragma("unroll") for (int m = 0; m < 4; ++m) _Pragma("unroll") for (int k = 0; k < 2; ++k) dst[m][k] = *(const LAS bf16x8*)(lds + PG8_SA(b, h) + aoff + m * 2048 + k * 1024); } while (0)
; #define PG8_LDB(dst, b, h) do { _Pragma("unroll") for (int n = 0; n < 2; ++n) _Pragma("unroll") for (int k = 0; k < 2; ++k) dst[n][k] = *(const LAS bf16x8*)(lds + PG8_SB(b, h) + boff + n * 2048 + k * 1024); } while (0)
; #define PG8_MMA(ai, bj, At, Bt) do { __builtin_amdgcn_s_setprio(1); _Pragma("unroll") for (int m = 0; m < 4; ++m) _Pragma("unroll") for (int n = 0; n < 2; ++n) _Pragma("unroll") for (int k = 0; k < 2; ++k) \
;         acc[ai][bj][m][n] = __builtin_amdgcn_mfma_f32_16x16x32_bf16(Bt[n][k], At[m][k], acc[ai][bj][m][n], 0, 0, 0); __builtin_amdgcn_s_setprio(0); } while (0)
; #define PG8_WAIT_V(n) asm volatile("s_waitcnt vmcnt(" #n ")" ::: "memory")
; #define PG8_WAIT_L(n) asm volatile("s_waitcnt lgkmcnt(" #n ")" ::: "memory")
; #define PG8_BAR __builtin_amdgcn_s_barrier()
; #define PG8_SCHED __builtin_amdgcn_sched_barrier(0)
; template <class Epi, class Sched, bool ALIGN_EPI = false, bool SP2 = false>
; __device__ __forceinline__ void gemm_phase(LAS unsigned char* lds, const Gemm g, const Sched S, const Epi E) {
;     ...
;             PG8_LDB(B0, 0, 0); PG8_LDB(B1, 0, 1); PG8_SCHED; PG8_LDA(At, 0, 0); PG8_STAGE(PG8_SA(1, 1), a1 + hstepA, voffA);
;             PG8_WAIT_V(8); PG8_WAIT_L(0); PG8_BAR; PG8_MMA(0, 0, At, B0); PG8_MMA(0, 1, At, B1); PG8_BAR; PG8_SCHED;
;             PG8_LDA(At, 0, 1); PG8_STAGE(PG8_SB(0, 0), b2, voffB); PG8_STAGE(PG8_SB(0, 1), b2 + hstepB, voffB); PG8_STAGE(PG8_SA(0, 0), a2, voffA);
;             PG8_WAIT_V(8); PG8_WAIT_L(0); PG8_BAR; PG8_MMA(1, 0, At, B0); PG8_MMA(1, 1, At, B1); PG8_BAR; PG8_SCHED;
.LBB0_1766:
	ds_read_b128 v[128:131], v173
	ds_read_b128 v[132:135], v173 offset:1024
	ds_read_b128 v[136:139], v173 offset:2048
	ds_read_b128 v[140:143], v173 offset:3072
	ds_read_b128 v[160:163], v174
	ds_read_b128 v[164:167], v174 offset:1024
	ds_read_b128 v[178:181], v174 offset:2048
	ds_read_b128 v[182:185], v174 offset:3072
	s_add_u32 s34, s56, 0xfffc0080
	s_addc_u32 s35, s57, -1
	s_cmp_eq_u32 s66, 12
	s_cselect_b32 s61, s19, s35
	s_cselect_b32 s60, s53, s34
	s_cselect_b32 s59, s17, s65
	s_cselect_b32 s58, s63, s64
	s_add_i32 m0, s5, 0xc000
	ds_read_b128 v[186:189], v175
	ds_read_b128 v[190:193], v175 offset:1024
	ds_read_b128 v[194:197], v175 offset:2048
	ds_read_b128 v[198:201], v175 offset:3072
	ds_read_b128 v[202:205], v175 offset:4096
	ds_read_b128 v[206:209], v175 offset:5120
	ds_read_b128 v[210:213], v175 offset:6144
	ds_read_b128 v[214:217], v175 offset:7168
	global_load_lds_dwordx4 v152, s[56:57]
	s_add_i32 m0, s5, 0xe000
	s_nop 0
	global_load_lds_dwordx4 v154, s[56:57]
	s_waitcnt vmcnt(8)
	s_waitcnt lgkmcnt(0)
	s_barrier
	s_setprio 1
	s_waitcnt lgkmcnt(0)
	v_mfma_f32_16x16x32_bf16 v[124:127], v[128:131], v[186:189], v[124:127]
	v_mfma_f32_16x16x32_bf16 v[120:123], v[136:139], v[186:189], v[120:123]
	v_mfma_f32_16x16x32_bf16 v[108:111], v[128:131], v[194:197], v[108:111]
	v_mfma_f32_16x16x32_bf16 v[104:107], v[136:139], v[194:197], v[104:107]
	v_mfma_f32_16x16x32_bf16 v[92:95], v[128:131], v[202:205], v[92:95]
	v_mfma_f32_16x16x32_bf16 v[88:91], v[136:139], v[202:205], v[88:91]
	v_mfma_f32_16x16x32_bf16 v[76:79], v[128:131], v[210:213], v[76:79]
	v_mfma_f32_16x16x32_bf16 v[72:75], v[136:139], v[210:213], v[72:75]
	v_mfma_f32_16x16x32_bf16 v[124:127], v[132:135], v[190:193], v[124:127]
	v_mfma_f32_16x16x32_bf16 v[120:123], v[140:143], v[190:193], v[120:123]
	v_mfma_f32_16x16x32_bf16 v[108:111], v[132:135], v[198:201], v[108:111]
	v_mfma_f32_16x16x32_bf16 v[104:107], v[140:143], v[198:201], v[104:107]
	v_mfma_f32_16x16x32_bf16 v[92:95], v[132:135], v[206:209], v[92:95]
	v_mfma_f32_16x16x32_bf16 v[88:91], v[140:143], v[206:209], v[88:91]
	v_mfma_f32_16x16x32_bf16 v[76:79], v[132:135], v[214:217], v[76:79]
	v_mfma_f32_16x16x32_bf16 v[72:75], v[140:143], v[214:217], v[72:75]
	v_mfma_f32_16x16x32_bf16 v[116:119], v[160:163], v[186:189], v[116:119]
	v_mfma_f32_16x16x32_bf16 v[112:115], v[178:181], v[186:189], v[112:115]
	v_mfma_f32_16x16x32_bf16 v[100:103], v[160:163], v[194:197], v[100:103]
	v_mfma_f32_16x16x32_bf16 v[96:99], v[178:181], v[194:197], v[96:99]
	v_mfma_f32_16x16x32_bf16 v[84:87], v[160:163], v[202:205], v[84:87]
	v_mfma_f32_16x16x32_bf16 v[80:83], v[178:181], v[202:205], v[80:83]
	v_mfma_f32_16x16x32_bf16 v[68:71], v[160:163], v[210:213], v[68:71]
	v_mfma_f32_16x16x32_bf16 v[64:67], v[178:181], v[210:213], v[64:67]
	v_mfma_f32_16x16x32_bf16 v[116:119], v[164:167], v[190:193], v[116:119]
	v_mfma_f32_16x16x32_bf16 v[112:115], v[182:185], v[190:193], v[112:115]
	v_mfma_f32_16x16x32_bf16 v[100:103], v[164:167], v[198:201], v[100:103]
	v_mfma_f32_16x16x32_bf16 v[96:99], v[182:185], v[198:201], v[96:99]
	v_mfma_f32_16x16x32_bf16 v[84:87], v[164:167], v[206:209], v[84:87]
	v_mfma_f32_16x16x32_bf16 v[80:83], v[182:185], v[206:209], v[80:83]
	v_mfma_f32_16x16x32_bf16 v[68:71], v[164:167], v[214:217], v[68:71]
	v_mfma_f32_16x16x32_bf16 v[64:67], v[182:185], v[214:217], v[64:67]
	s_setprio 0
	s_barrier
	s_add_i32 s34, s55, s4
	v_lshl_add_u64 v[168:169], s[58:59], 0, v[146:147]
	s_mov_b32 m0, s34
	ds_read_b128 v[186:189], v175 offset:16384
	ds_read_b128 v[190:193], v175 offset:17408
	ds_read_b128 v[194:197], v175 offset:18432
	ds_read_b128 v[198:201], v175 offset:19456
	ds_read_b128 v[202:205], v175 offset:20480
	ds_read_b128 v[206:209], v175 offset:21504
	ds_read_b128 v[210:213], v175 offset:22528
	ds_read_b128 v[214:217], v175 offset:23552
	global_load_lds_dwordx4 v[168:169], off
	s_add_i32 m0, s34, 0x2000
	s_add_u32 s34, s58, 0x40000
	v_lshl_add_u64 v[218:219], s[58:59], 0, v[150:151]
	s_addc_u32 s35, s59, 0
	s_add_i32 s67, s62, s4
	global_load_lds_dwordx4 v[218:219], off
	s_mov_b32 m0, s67
	v_lshl_add_u64 v[222:223], s[60:61], 0, v[148:149]
	global_load_lds_dwordx4 v146, s[34:35]
	s_add_i32 m0, s67, 0x2000
	s_nop 0
	global_load_lds_dwordx4 v150, s[34:35]
	v_lshl_add_u64 v[220:221], s[60:61], 0, v[144:145]
	s_mov_b32 m0, s5
	s_nop 0
	global_load_lds_dwordx4 v[220:221], off
	s_mov_b32 m0, s20
	s_nop 0
	global_load_lds_dwordx4 v[222:223], off
	s_waitcnt vmcnt(8)
	s_waitcnt lgkmcnt(0)
	s_barrier
	s_setprio 1
	s_waitcnt lgkmcnt(0)
	v_mfma_f32_16x16x32_bf16 v[60:63], v[128:131], v[186:189], v[60:63]
	v_mfma_f32_16x16x32_bf16 v[56:59], v[136:139], v[186:189], v[56:59]
	v_mfma_f32_16x16x32_bf16 v[44:47], v[128:131], v[194:197], v[44:47]
	v_mfma_f32_16x16x32_bf16 v[40:43], v[136:139], v[194:197], v[40:43]
	v_mfma_f32_16x16x32_bf16 v[28:31], v[128:131], v[202:205], v[28:31]
	v_mfma_f32_16x16x32_bf16 v[24:27], v[136:139], v[202:205], v[24:27]
	v_mfma_f32_16x16x32_bf16 v[12:15], v[128:131], v[210:213], v[12:15]
	v_mfma_f32_16x16x32_bf16 v[8:11], v[136:139], v[210:213], v[8:11]
	v_mfma_f32_16x16x32_bf16 v[60:63], v[132:135], v[190:193], v[60:63]
	v_mfma_f32_16x16x32_bf16 v[56:59], v[140:143], v[190:193], v[56:59]
	v_mfma_f32_16x16x32_bf16 v[44:47], v[132:135], v[198:201], v[44:47]
	v_mfma_f32_16x16x32_bf16 v[40:43], v[140:143], v[198:201], v[40:43]
	v_mfma_f32_16x16x32_bf16 v[28:31], v[132:135], v[206:209], v[28:31]
	v_mfma_f32_16x16x32_bf16 v[24:27], v[140:143], v[206:209], v[24:27]
	v_mfma_f32_16x16x32_bf16 v[12:15], v[132:135], v[214:217], v[12:15]
	v_mfma_f32_16x16x32_bf16 v[8:11], v[140:143], v[214:217], v[8:11]
	v_mfma_f32_16x16x32_bf16 v[52:55], v[160:163], v[186:189], v[52:55]
	v_mfma_f32_16x16x32_bf16 v[48:51], v[178:181], v[186:189], v[48:51]
	v_mfma_f32_16x16x32_bf16 v[36:39], v[160:163], v[194:197], v[36:39]
	v_mfma_f32_16x16x32_bf16 v[32:35], v[178:181], v[194:197], v[32:35]
	v_mfma_f32_16x16x32_bf16 v[20:23], v[160:163], v[202:205], v[20:23]
	v_mfma_f32_16x16x32_bf16 v[16:19], v[178:181], v[202:205], v[16:19]
	v_mfma_f32_16x16x32_bf16 v[4:7], v[160:163], v[210:213], v[4:7]
	v_mfma_f32_16x16x32_bf16 v[0:3], v[178:181], v[210:213], v[0:3]
	v_mfma_f32_16x16x32_bf16 v[52:55], v[164:167], v[190:193], v[52:55]
	v_mfma_f32_16x16x32_bf16 v[48:51], v[182:185], v[190:193], v[48:51]
	v_mfma_f32_16x16x32_bf16 v[36:39], v[164:167], v[198:201], v[36:39]
	v_mfma_f32_16x16x32_bf16 v[32:35], v[182:185], v[198:201], v[32:35]
	v_mfma_f32_16x16x32_bf16 v[20:23], v[164:167], v[206:209], v[20:23]
	v_mfma_f32_16x16x32_bf16 v[16:19], v[182:185], v[206:209], v[16:19]
	v_mfma_f32_16x16x32_bf16 v[4:7], v[164:167], v[214:217], v[4:7]
	v_mfma_f32_16x16x32_bf16 v[0:3], v[182:185], v[214:217], v[0:3]
	s_setprio 0
	s_barrier
; #define PG8_STAGE(bufoff, gbase, voff) do { _Pragma("unroll") for (int _i = 0; _i < 2; ++_i) \
;         __builtin_amdgcn_global_load_lds((const unsigned*)((const char*)(gbase) + (voff)[_i]), (LAS unsigned*)(lds + (bufoff) + ldsw + _i * 8192), 16, 0, 0); } while (0)
; #define PG8_LDA(dst, b, h) do { _Pragma("unroll") for (int m = 0; m < 4; ++m) _Pragma("unroll") for (int k = 0; k < 2; ++k) dst[m][k] = *(const LAS bf16x8*)(lds + PG8_SA(b, h) + aoff + m * 2048 + k * 1024); } while (0)
; #define PG8_LDB(dst, b, h) do { _Pragma("unroll") for (int n = 0; n < 2; ++n) _Pragma("unroll") for (int k = 0; k < 2; ++k) dst[n][k] = *(const LAS bf16x8*)(lds + PG8_SB(b, h) + boff + n * 2048 + k * 1024); } while (0)
; #define PG8_MMA(ai, bj, At, Bt) do { __builtin_amdgcn_s_setprio(1); _Pragma("unroll") for (int m = 0; m < 4; ++m) _Pragma("unroll") for (int n = 0; n < 2; ++n) _Pragma("unroll") for (int k = 0; k < 2; ++k) \
;         acc[ai][bj][m][n] = __builtin_amdgcn_mfma_f32_16x16x32_bf16(Bt[n][k], At[m][k], acc[ai][bj][m][n], 0, 0, 0); __builtin_amdgcn_s_setprio(0); } while (0)
; #define PG8_WAIT_V(n) asm volatile("s_waitcnt vmcnt(" #n ")" ::: "memory")
; #define PG8_WAIT_L(n) asm volatile("s_waitcnt lgkmcnt(" #n ")" ::: "memory")
; #define PG8_BAR __builtin_amdgcn_s_barrier()
; template <class Epi, class Sched, bool ALIGN_EPI = false, bool SP2 = false>
; __device__ __forceinline__ void gemm_phase(LAS unsigned char* lds, const Gemm g, const Sched S, const Epi E) {
;     ...
;         for (int t = 0; t < nt; t += 2) {
;             const bool last = (t == nt - 2);
;             const char* a1 = cA + (size_t)(t + 1) * kstep;
;             const char* a2 = last ? nA : cA + (size_t)(t + 2) * kstep; const char* b2 = last ? nB : cB + (size_t)(t + 2) * kstep;
;             const char* a3 = a2 + kstep; const char* b3 = b2 + kstep;
;             if (last && has_next) S.a_ready(nxt);
;     ...
;             PG8_LDB(B0, 1, 0); PG8_LDB(B1, 1, 1); PG8_SCHED; PG8_LDA(At, 1, 0); PG8_STAGE(PG8_SA(0, 1), a2 + hstepA, voffA);
;             PG8_WAIT_V(8); PG8_WAIT_L(0); PG8_BAR; PG8_MMA(0, 0, At, B0); PG8_MMA(0, 1, At, B1); PG8_BAR; PG8_SCHED;
;             PG8_LDA(At, 1, 1); PG8_STAGE(PG8_SB(1, 0), b3, voffB); PG8_STAGE(PG8_SB(1, 1), b3 + hstepB, voffB); PG8_STAGE(PG8_SA(1, 0), a3, voffA);
;             PG8_WAIT_V(8); PG8_WAIT_L(0); PG8_BAR; PG8_MMA(1, 0, At, B0); PG8_MMA(1, 1, At, B1); PG8_BAR; PG8_SCHED;
	s_add_i32 s67, 0, 0x18000
	s_add_i32 s68, 0, 0x1c000
	v_add_u32_e32 v140, s67, v171
	v_add_u32_e32 v177, s68, v171
	ds_read_b128 v[128:131], v140
	ds_read_b128 v[132:135], v140 offset:1024
	ds_read_b128 v[136:139], v140 offset:2048
	ds_read_b128 v[140:143], v140 offset:3072
	ds_read_b128 v[160:163], v177
	ds_read_b128 v[164:167], v177 offset:1024
	ds_read_b128 v[178:181], v177 offset:2048
	ds_read_b128 v[182:185], v177 offset:3072
	s_add_u32 s34, s60, 0x40000
	s_addc_u32 s35, s61, 0
	s_mov_b32 m0, s21
	ds_read_b128 v[186:189], v175 offset:32768
	ds_read_b128 v[190:193], v175 offset:33792
	ds_read_b128 v[194:197], v175 offset:34816
	ds_read_b128 v[198:201], v175 offset:35840
	ds_read_b128 v[202:205], v175 offset:36864
	ds_read_b128 v[206:209], v175 offset:37888
	ds_read_b128 v[210:213], v175 offset:38912
	ds_read_b128 v[214:217], v175 offset:39936
	global_load_lds_dwordx4 v144, s[34:35]
	s_mov_b32 m0, s29
	s_nop 0
	global_load_lds_dwordx4 v148, s[34:35]
	s_waitcnt vmcnt(8)
	s_waitcnt lgkmcnt(0)
	s_barrier
	s_setprio 1
	s_waitcnt lgkmcnt(0)
	v_mfma_f32_16x16x32_bf16 v[124:127], v[128:131], v[186:189], v[124:127]
	v_mfma_f32_16x16x32_bf16 v[120:123], v[136:139], v[186:189], v[120:123]
	v_mfma_f32_16x16x32_bf16 v[108:111], v[128:131], v[194:197], v[108:111]
	v_mfma_f32_16x16x32_bf16 v[104:107], v[136:139], v[194:197], v[104:107]
	v_mfma_f32_16x16x32_bf16 v[92:95], v[128:131], v[202:205], v[92:95]
	v_mfma_f32_16x16x32_bf16 v[88:91], v[136:139], v[202:205], v[88:91]
	v_mfma_f32_16x16x32_bf16 v[76:79], v[128:131], v[210:213], v[76:79]
	v_mfma_f32_16x16x32_bf16 v[72:75], v[136:139], v[210:213], v[72:75]
	v_mfma_f32_16x16x32_bf16 v[124:127], v[132:135], v[190:193], v[124:127]
	v_mfma_f32_16x16x32_bf16 v[120:123], v[140:143], v[190:193], v[120:123]
	v_mfma_f32_16x16x32_bf16 v[108:111], v[132:135], v[198:201], v[108:111]
	v_mfma_f32_16x16x32_bf16 v[104:107], v[140:143], v[198:201], v[104:107]
	v_mfma_f32_16x16x32_bf16 v[92:95], v[132:135], v[206:209], v[92:95]
	v_mfma_f32_16x16x32_bf16 v[88:91], v[140:143], v[206:209], v[88:91]
	v_mfma_f32_16x16x32_bf16 v[76:79], v[132:135], v[214:217], v[76:79]
	v_mfma_f32_16x16x32_bf16 v[72:75], v[140:143], v[214:217], v[72:75]
	v_mfma_f32_16x16x32_bf16 v[116:119], v[160:163], v[186:189], v[116:119]
	v_mfma_f32_16x16x32_bf16 v[112:115], v[178:181], v[186:189], v[112:115]
	v_mfma_f32_16x16x32_bf16 v[100:103], v[160:163], v[194:197], v[100:103]
	v_mfma_f32_16x16x32_bf16 v[96:99], v[178:181], v[194:197], v[96:99]
	v_mfma_f32_16x16x32_bf16 v[84:87], v[160:163], v[202:205], v[84:87]
	v_mfma_f32_16x16x32_bf16 v[80:83], v[178:181], v[202:205], v[80:83]
	v_mfma_f32_16x16x32_bf16 v[68:71], v[160:163], v[210:213], v[68:71]
	v_mfma_f32_16x16x32_bf16 v[64:67], v[178:181], v[210:213], v[64:67]
	v_mfma_f32_16x16x32_bf16 v[116:119], v[164:167], v[190:193], v[116:119]
	v_mfma_f32_16x16x32_bf16 v[112:115], v[182:185], v[190:193], v[112:115]
	v_mfma_f32_16x16x32_bf16 v[100:103], v[164:167], v[198:201], v[100:103]
	v_mfma_f32_16x16x32_bf16 v[96:99], v[182:185], v[198:201], v[96:99]
	v_mfma_f32_16x16x32_bf16 v[84:87], v[164:167], v[206:209], v[84:87]
	v_mfma_f32_16x16x32_bf16 v[80:83], v[182:185], v[206:209], v[80:83]
	v_mfma_f32_16x16x32_bf16 v[68:71], v[164:167], v[214:217], v[68:71]
	v_mfma_f32_16x16x32_bf16 v[64:67], v[182:185], v[214:217], v[64:67]
	s_setprio 0
	s_barrier
	s_add_i32 s34, s67, s4
	v_lshl_add_u64 v[168:169], v[168:169], 0, s[12:13]
	s_mov_b32 m0, s34
	ds_read_b128 v[186:189], v175 offset:49152
	ds_read_b128 v[190:193], v175 offset:50176
	ds_read_b128 v[194:197], v175 offset:51200
	ds_read_b128 v[198:201], v175 offset:52224
	ds_read_b128 v[202:205], v175 offset:53248
	ds_read_b128 v[206:209], v175 offset:54272
	ds_read_b128 v[210:213], v175 offset:55296
	ds_read_b128 v[214:217], v175 offset:56320
	global_load_lds_dwordx4 v[168:169], off
	s_add_i32 m0, s34, 0x2000
	s_add_u32 s34, s58, 0x40080
	v_lshl_add_u64 v[168:169], v[218:219], 0, s[12:13]
	s_addc_u32 s35, s59, 0
	s_add_i32 s58, s68, s4
	global_load_lds_dwordx4 v[168:169], off
	s_mov_b32 m0, s58
	s_nop 0
	global_load_lds_dwordx4 v146, s[34:35]
	s_add_i32 m0, s58, 0x2000
	s_nop 0
	global_load_lds_dwordx4 v150, s[34:35]
	v_lshl_add_u64 v[168:169], v[220:221], 0, s[12:13]
	s_mov_b32 m0, s31
	s_nop 0
	global_load_lds_dwordx4 v[168:169], off
	v_lshl_add_u64 v[168:169], v[222:223], 0, s[12:13]
	s_mov_b32 m0, s33
	s_nop 0
	global_load_lds_dwordx4 v[168:169], off
	s_waitcnt vmcnt(8)
	s_waitcnt lgkmcnt(0)
	s_barrier
	s_setprio 1
	s_waitcnt lgkmcnt(0)
	v_mfma_f32_16x16x32_bf16 v[60:63], v[128:131], v[186:189], v[60:63]
	v_mfma_f32_16x16x32_bf16 v[56:59], v[136:139], v[186:189], v[56:59]
	v_mfma_f32_16x16x32_bf16 v[44:47], v[128:131], v[194:197], v[44:47]
	v_mfma_f32_16x16x32_bf16 v[40:43], v[136:139], v[194:197], v[40:43]
	v_mfma_f32_16x16x32_bf16 v[28:31], v[128:131], v[202:205], v[28:31]
	v_mfma_f32_16x16x32_bf16 v[24:27], v[136:139], v[202:205], v[24:27]
	v_mfma_f32_16x16x32_bf16 v[12:15], v[128:131], v[210:213], v[12:15]
	v_mfma_f32_16x16x32_bf16 v[8:11], v[136:139], v[210:213], v[8:11]
	v_mfma_f32_16x16x32_bf16 v[60:63], v[132:135], v[190:193], v[60:63]
	v_mfma_f32_16x16x32_bf16 v[56:59], v[140:143], v[190:193], v[56:59]
	v_mfma_f32_16x16x32_bf16 v[44:47], v[132:135], v[198:201], v[44:47]
	v_mfma_f32_16x16x32_bf16 v[40:43], v[140:143], v[198:201], v[40:43]
	v_mfma_f32_16x16x32_bf16 v[28:31], v[132:135], v[206:209], v[28:31]
	v_mfma_f32_16x16x32_bf16 v[24:27], v[140:143], v[206:209], v[24:27]
	v_mfma_f32_16x16x32_bf16 v[12:15], v[132:135], v[214:217], v[12:15]
	v_mfma_f32_16x16x32_bf16 v[8:11], v[140:143], v[214:217], v[8:11]
	v_mfma_f32_16x16x32_bf16 v[52:55], v[160:163], v[186:189], v[52:55]
	v_mfma_f32_16x16x32_bf16 v[48:51], v[178:181], v[186:189], v[48:51]
	v_mfma_f32_16x16x32_bf16 v[36:39], v[160:163], v[194:197], v[36:39]
	v_mfma_f32_16x16x32_bf16 v[32:35], v[178:181], v[194:197], v[32:35]
	v_mfma_f32_16x16x32_bf16 v[20:23], v[160:163], v[202:205], v[20:23]
	v_mfma_f32_16x16x32_bf16 v[16:19], v[178:181], v[202:205], v[16:19]
	v_mfma_f32_16x16x32_bf16 v[4:7], v[160:163], v[210:213], v[4:7]
	v_mfma_f32_16x16x32_bf16 v[0:3], v[178:181], v[210:213], v[0:3]
	v_mfma_f32_16x16x32_bf16 v[52:55], v[164:167], v[190:193], v[52:55]
	v_mfma_f32_16x16x32_bf16 v[48:51], v[182:185], v[190:193], v[48:51]
	v_mfma_f32_16x16x32_bf16 v[36:39], v[164:167], v[198:201], v[36:39]
	v_mfma_f32_16x16x32_bf16 v[32:35], v[182:185], v[198:201], v[32:35]
	v_mfma_f32_16x16x32_bf16 v[20:23], v[164:167], v[206:209], v[20:23]
	v_mfma_f32_16x16x32_bf16 v[16:19], v[182:185], v[206:209], v[16:19]
	v_mfma_f32_16x16x32_bf16 v[4:7], v[164:167], v[214:217], v[4:7]
	v_mfma_f32_16x16x32_bf16 v[0:3], v[182:185], v[214:217], v[0:3]
	s_setprio 0
	s_add_i32 s66, s66, 2
	s_add_u32 s56, s56, 0x100
	s_addc_u32 s57, s57, 0
	s_add_u32 s64, s64, 0x100
	s_addc_u32 s65, s65, 0
	s_cmp_gt_u32 s66, 13
	s_barrier
	s_cbranch_scc0 .LBB0_1766
	s_and_b64 vcc, exec, s[14:15]
	s_cbranch_vccz .LBB0_1769
	s_barrier

; #define PG8_STAGE(bufoff, gbase, voff) do { _Pragma("unroll") for (int _i = 0; _i < 2; ++_i) \
;         __builtin_amdgcn_global_load_lds((const unsigned*)((const char*)(gbase) + (voff)[_i]), (LAS unsigned*)(lds + (bufoff) + ldsw + _i * 8192), 16, 0, 0); } while (0)
; #define PG8_LDA(dst, b, h) do { _Pragma("unroll") for (int m = 0; m < 4; ++m) _Pragma("unroll") for (int k = 0; k < 2; ++k) dst[m][k] = *(const LAS bf16x8*)(lds + PG8_SA(b, h) + aoff + m * 2048 + k * 1024); } while (0)
; #define PG8_LDB(dst, b, h) do { _Pragma("unroll") for (int n = 0; n < 2; ++n) _Pragma("unroll") for (int k = 0; k < 2; ++k) dst[n][k] = *(const LAS bf16x8*)(lds + PG8_SB(b, h) + boff + n * 2048 + k * 1024); } while (0)
; #define PG8_MMA(ai, bj, At, Bt) do { __builtin_amdgcn_s_setprio(1); _Pragma("unroll") for (int m = 0; m < 4; ++m) _Pragma("unroll") for (int n = 0; n < 2; ++n) _Pragma("unroll") for (int k = 0; k < 2; ++k) \
;         acc[ai][bj][m][n] = __builtin_amdgcn_mfma_f32_16x16x32_bf16(Bt[n][k], At[m][k], acc[ai][bj][m][n], 0, 0, 0); __builtin_amdgcn_s_setprio(0); } while (0)
; #define PG8_WAIT_V(n) asm volatile("s_waitcnt vmcnt(" #n ")" ::: "memory")
; #define PG8_WAIT_L(n) asm volatile("s_waitcnt lgkmcnt(" #n ")" ::: "memory")
; template <class Epi, class Sched, bool ALIGN_EPI = false, bool SP2 = false>
; __device__ __forceinline__ void gemm_phase(LAS unsigned char* lds, const Gemm g, const Sched S, const Epi E) {
;     ...
;         for (int t = 0; t < nt; t += 2) {
;             const bool last = (t == nt - 2);
;             const char* a1 = cA + (size_t)(t + 1) * kstep;
;             const char* a2 = last ? nA : cA + (size_t)(t + 2) * kstep; const char* b2 = last ? nB : cB + (size_t)(t + 2) * kstep;
;             const char* a3 = a2 + kstep; const char* b3 = b2 + kstep;
;             if (last && has_next) S.a_ready(nxt);
;             if constexpr (SP2) {
;             PG8_LDB(B0, 0, 0); PG8_LDB(B1, 0, 1); PG8_SCHED; PG8_LDA(At, 0, 0); PG8_STAGE(PG8_SA(1, 1), a1 + hstepA, voffA);
;             PG8_WAIT_V(8); PG8_WAIT_L(0); PG8_BAR; PG8_MMA(0, 0, At, B0); PG8_MMA(0, 1, At, B1); PG8_BAR; PG8_SCHED;
;             PG8_LDA(At, 0, 1); PG8_STAGE(PG8_SB(0, 0), b2, voffB); PG8_STAGE(PG8_SB(0, 1), b2 + hstepB, voffB); PG8_STAGE(PG8_SA(0, 0), a2, voffA);
;             PG8_WAIT_V(8); PG8_WAIT_L(0); PG8_BAR; PG8_MMA(1, 0, At, B0); PG8_MMA(1, 1, At, B1); PG8_BAR; PG8_SCHED;
.LBB0_1850:
	ds_read_b128 v[166:169], v155
	ds_read_b128 v[170:173], v155 offset:1024
	ds_read_b128 v[174:177], v155 offset:2048
	ds_read_b128 v[178:181], v155 offset:3072
	ds_read_b128 v[182:185], v159
	ds_read_b128 v[186:189], v159 offset:1024
	ds_read_b128 v[190:193], v159 offset:2048
	ds_read_b128 v[194:197], v159 offset:3072
	s_add_u32 s12, s10, 0xfff80080
	s_addc_u32 s13, s11, -1
	s_cmp_eq_u32 s51, 12
	s_cselect_b32 s15, s16, s13
	s_cselect_b32 s14, s17, s12
	s_cselect_b32 s13, s18, s23
	s_cselect_b32 s12, s19, s22
	s_add_i32 m0, s20, 0xc000
	ds_read_b128 v[198:201], v163
	ds_read_b128 v[202:205], v163 offset:1024
	ds_read_b128 v[206:209], v163 offset:2048
	ds_read_b128 v[210:213], v163 offset:3072
	ds_read_b128 v[214:217], v163 offset:4096
	ds_read_b128 v[218:221], v163 offset:5120
	ds_read_b128 v[222:225], v163 offset:6144
	ds_read_b128 v[226:229], v163 offset:7168
	global_load_lds_dwordx4 v136, s[10:11]
	s_add_i32 m0, s20, 0xe000
	s_nop 0
	global_load_lds_dwordx4 v138, s[10:11]
	s_waitcnt vmcnt(8)
	s_waitcnt lgkmcnt(0)
	s_barrier
	s_setprio 1
	s_waitcnt lgkmcnt(0)
	v_mfma_f32_16x16x32_bf16 v[124:127], v[166:169], v[198:201], v[124:127]
	v_mfma_f32_16x16x32_bf16 v[120:123], v[174:177], v[198:201], v[120:123]
	v_mfma_f32_16x16x32_bf16 v[108:111], v[166:169], v[206:209], v[108:111]
	v_mfma_f32_16x16x32_bf16 v[104:107], v[174:177], v[206:209], v[104:107]
	v_mfma_f32_16x16x32_bf16 v[92:95], v[166:169], v[214:217], v[92:95]
	v_mfma_f32_16x16x32_bf16 v[88:91], v[174:177], v[214:217], v[88:91]
	v_mfma_f32_16x16x32_bf16 v[76:79], v[166:169], v[222:225], v[76:79]
	v_mfma_f32_16x16x32_bf16 v[72:75], v[174:177], v[222:225], v[72:75]
	v_mfma_f32_16x16x32_bf16 v[124:127], v[170:173], v[202:205], v[124:127]
	v_mfma_f32_16x16x32_bf16 v[120:123], v[178:181], v[202:205], v[120:123]
	v_mfma_f32_16x16x32_bf16 v[108:111], v[170:173], v[210:213], v[108:111]
	v_mfma_f32_16x16x32_bf16 v[104:107], v[178:181], v[210:213], v[104:107]
	v_mfma_f32_16x16x32_bf16 v[92:95], v[170:173], v[218:221], v[92:95]
	v_mfma_f32_16x16x32_bf16 v[88:91], v[178:181], v[218:221], v[88:91]
	v_mfma_f32_16x16x32_bf16 v[76:79], v[170:173], v[226:229], v[76:79]
	v_mfma_f32_16x16x32_bf16 v[72:75], v[178:181], v[226:229], v[72:75]
	v_mfma_f32_16x16x32_bf16 v[116:119], v[182:185], v[198:201], v[116:119]
	v_mfma_f32_16x16x32_bf16 v[112:115], v[190:193], v[198:201], v[112:115]
	v_mfma_f32_16x16x32_bf16 v[100:103], v[182:185], v[206:209], v[100:103]
	v_mfma_f32_16x16x32_bf16 v[96:99], v[190:193], v[206:209], v[96:99]
	v_mfma_f32_16x16x32_bf16 v[84:87], v[182:185], v[214:217], v[84:87]
	v_mfma_f32_16x16x32_bf16 v[80:83], v[190:193], v[214:217], v[80:83]
	v_mfma_f32_16x16x32_bf16 v[68:71], v[182:185], v[222:225], v[68:71]
	v_mfma_f32_16x16x32_bf16 v[64:67], v[190:193], v[222:225], v[64:67]
	v_mfma_f32_16x16x32_bf16 v[116:119], v[186:189], v[202:205], v[116:119]
	v_mfma_f32_16x16x32_bf16 v[112:115], v[194:197], v[202:205], v[112:115]
	v_mfma_f32_16x16x32_bf16 v[100:103], v[186:189], v[210:213], v[100:103]
	v_mfma_f32_16x16x32_bf16 v[96:99], v[194:197], v[210:213], v[96:99]
	v_mfma_f32_16x16x32_bf16 v[84:87], v[186:189], v[218:221], v[84:87]
	v_mfma_f32_16x16x32_bf16 v[80:83], v[194:197], v[218:221], v[80:83]
	v_mfma_f32_16x16x32_bf16 v[68:71], v[186:189], v[226:229], v[68:71]
	v_mfma_f32_16x16x32_bf16 v[64:67], v[194:197], v[226:229], v[64:67]
	s_setprio 0
	s_barrier
	s_add_i32 s34, s61, s4
	v_lshl_add_u64 v[144:145], s[12:13], 0, v[132:133]
	s_mov_b32 m0, s34
	ds_read_b128 v[198:201], v163 offset:16384
	ds_read_b128 v[202:205], v163 offset:17408
	ds_read_b128 v[206:209], v163 offset:18432
	ds_read_b128 v[210:213], v163 offset:19456
	ds_read_b128 v[214:217], v163 offset:20480
	ds_read_b128 v[218:221], v163 offset:21504
	ds_read_b128 v[222:225], v163 offset:22528
	ds_read_b128 v[226:229], v163 offset:23552
	global_load_lds_dwordx4 v[144:145], off
	s_add_i32 m0, s34, 0x2000
	s_add_u32 s34, s12, 0x40000
	v_lshl_add_u64 v[152:153], s[12:13], 0, v[128:129]
	s_addc_u32 s35, s13, 0
	s_add_i32 s53, s62, s4
	global_load_lds_dwordx4 v[152:153], off
	s_mov_b32 m0, s53
	v_lshl_add_u64 v[160:161], s[14:15], 0, v[130:131]
	global_load_lds_dwordx4 v132, s[34:35]
	s_add_i32 m0, s53, 0x2000
	s_nop 0
	global_load_lds_dwordx4 v128, s[34:35]
	v_lshl_add_u64 v[156:157], s[14:15], 0, v[134:135]
	s_mov_b32 m0, s20
	s_nop 0
	global_load_lds_dwordx4 v[156:157], off
	s_mov_b32 m0, s21
	s_nop 0
	global_load_lds_dwordx4 v[160:161], off
	s_waitcnt vmcnt(8)
	s_waitcnt lgkmcnt(0)
	s_barrier
	s_setprio 1
	s_waitcnt lgkmcnt(0)
	v_mfma_f32_16x16x32_bf16 v[60:63], v[166:169], v[198:201], v[60:63]
	v_mfma_f32_16x16x32_bf16 v[56:59], v[174:177], v[198:201], v[56:59]
	v_mfma_f32_16x16x32_bf16 v[44:47], v[166:169], v[206:209], v[44:47]
	v_mfma_f32_16x16x32_bf16 v[40:43], v[174:177], v[206:209], v[40:43]
	v_mfma_f32_16x16x32_bf16 v[28:31], v[166:169], v[214:217], v[28:31]
	v_mfma_f32_16x16x32_bf16 v[24:27], v[174:177], v[214:217], v[24:27]
	v_mfma_f32_16x16x32_bf16 v[12:15], v[166:169], v[222:225], v[12:15]
	v_mfma_f32_16x16x32_bf16 v[8:11], v[174:177], v[222:225], v[8:11]
	v_mfma_f32_16x16x32_bf16 v[60:63], v[170:173], v[202:205], v[60:63]
	v_mfma_f32_16x16x32_bf16 v[56:59], v[178:181], v[202:205], v[56:59]
	v_mfma_f32_16x16x32_bf16 v[44:47], v[170:173], v[210:213], v[44:47]
	v_mfma_f32_16x16x32_bf16 v[40:43], v[178:181], v[210:213], v[40:43]
	v_mfma_f32_16x16x32_bf16 v[28:31], v[170:173], v[218:221], v[28:31]
	v_mfma_f32_16x16x32_bf16 v[24:27], v[178:181], v[218:221], v[24:27]
	v_mfma_f32_16x16x32_bf16 v[12:15], v[170:173], v[226:229], v[12:15]
	v_mfma_f32_16x16x32_bf16 v[8:11], v[178:181], v[226:229], v[8:11]
	v_mfma_f32_16x16x32_bf16 v[52:55], v[182:185], v[198:201], v[52:55]
	v_mfma_f32_16x16x32_bf16 v[48:51], v[190:193], v[198:201], v[48:51]
	v_mfma_f32_16x16x32_bf16 v[36:39], v[182:185], v[206:209], v[36:39]
	v_mfma_f32_16x16x32_bf16 v[32:35], v[190:193], v[206:209], v[32:35]
	v_mfma_f32_16x16x32_bf16 v[20:23], v[182:185], v[214:217], v[20:23]
	v_mfma_f32_16x16x32_bf16 v[16:19], v[190:193], v[214:217], v[16:19]
	v_mfma_f32_16x16x32_bf16 v[4:7], v[182:185], v[222:225], v[4:7]
	v_mfma_f32_16x16x32_bf16 v[0:3], v[190:193], v[222:225], v[0:3]
	v_mfma_f32_16x16x32_bf16 v[52:55], v[186:189], v[202:205], v[52:55]
	v_mfma_f32_16x16x32_bf16 v[48:51], v[194:197], v[202:205], v[48:51]
	v_mfma_f32_16x16x32_bf16 v[36:39], v[186:189], v[210:213], v[36:39]
	v_mfma_f32_16x16x32_bf16 v[32:35], v[194:197], v[210:213], v[32:35]
	v_mfma_f32_16x16x32_bf16 v[20:23], v[186:189], v[218:221], v[20:23]
	v_mfma_f32_16x16x32_bf16 v[16:19], v[194:197], v[218:221], v[16:19]
	v_mfma_f32_16x16x32_bf16 v[4:7], v[186:189], v[226:229], v[4:7]
	v_mfma_f32_16x16x32_bf16 v[0:3], v[194:197], v[226:229], v[0:3]
	s_setprio 0
	s_barrier
; #define PG8_STAGE(bufoff, gbase, voff) do { _Pragma("unroll") for (int _i = 0; _i < 2; ++_i) \
;         __builtin_amdgcn_global_load_lds((const unsigned*)((const char*)(gbase) + (voff)[_i]), (LAS unsigned*)(lds + (bufoff) + ldsw + _i * 8192), 16, 0, 0); } while (0)
; #define PG8_LDA(dst, b, h) do { _Pragma("unroll") for (int m = 0; m < 4; ++m) _Pragma("unroll") for (int k = 0; k < 2; ++k) dst[m][k] = *(const LAS bf16x8*)(lds + PG8_SA(b, h) + aoff + m * 2048 + k * 1024); } while (0)
; #define PG8_LDB(dst, b, h) do { _Pragma("unroll") for (int n = 0; n < 2; ++n) _Pragma("unroll") for (int k = 0; k < 2; ++k) dst[n][k] = *(const LAS bf16x8*)(lds + PG8_SB(b, h) + boff + n * 2048 + k * 1024); } while (0)
; #define PG8_MMA(ai, bj, At, Bt) do { __builtin_amdgcn_s_setprio(1); _Pragma("unroll") for (int m = 0; m < 4; ++m) _Pragma("unroll") for (int n = 0; n < 2; ++n) _Pragma("unroll") for (int k = 0; k < 2; ++k) \
;         acc[ai][bj][m][n] = __builtin_amdgcn_mfma_f32_16x16x32_bf16(Bt[n][k], At[m][k], acc[ai][bj][m][n], 0, 0, 0); __builtin_amdgcn_s_setprio(0); } while (0)
; #define PG8_WAIT_V(n) asm volatile("s_waitcnt vmcnt(" #n ")" ::: "memory")
; #define PG8_WAIT_L(n) asm volatile("s_waitcnt lgkmcnt(" #n ")" ::: "memory")
; #define PG8_BAR __builtin_amdgcn_s_barrier()
; #define PG8_SCHED __builtin_amdgcn_sched_barrier(0)
; template <class Epi, class Sched, bool ALIGN_EPI = false, bool SP2 = false>
; __device__ __forceinline__ void gemm_phase(LAS unsigned char* lds, const Gemm g, const Sched S, const Epi E) {
;     ...
;             PG8_LDB(B0, 1, 0); PG8_LDB(B1, 1, 1); PG8_SCHED; PG8_LDA(At, 1, 0); PG8_STAGE(PG8_SA(0, 1), a2 + hstepA, voffA);
;             PG8_WAIT_V(8); PG8_WAIT_L(0); PG8_BAR; PG8_MMA(0, 0, At, B0); PG8_MMA(0, 1, At, B1); PG8_BAR; PG8_SCHED;
;             PG8_LDA(At, 1, 1); PG8_STAGE(PG8_SB(1, 0), b3, voffB); PG8_STAGE(PG8_SB(1, 1), b3 + hstepB, voffB); PG8_STAGE(PG8_SA(1, 0), a3, voffA);
;             PG8_WAIT_V(8); PG8_WAIT_L(0); PG8_BAR; PG8_MMA(1, 0, At, B0); PG8_MMA(1, 1, At, B1); PG8_BAR; PG8_SCHED;
	s_add_i32 s34, 0, 0x18000
	v_add_u32_e32 v146, s34, v149
	s_add_i32 s35, 0, 0x1c000
	ds_read_b128 v[166:169], v146
	ds_read_b128 v[170:173], v146 offset:1024
	ds_read_b128 v[174:177], v146 offset:2048
	ds_read_b128 v[178:181], v146 offset:3072
	v_add_u32_e32 v146, s35, v149
	ds_read_b128 v[182:185], v146
	ds_read_b128 v[186:189], v146 offset:1024
	ds_read_b128 v[190:193], v146 offset:2048
	ds_read_b128 v[194:197], v146 offset:3072
	s_add_u32 s14, s14, 0x80000
	s_addc_u32 s15, s15, 0
	s_mov_b32 m0, s29
	ds_read_b128 v[198:201], v163 offset:32768
	ds_read_b128 v[202:205], v163 offset:33792
	ds_read_b128 v[206:209], v163 offset:34816
	ds_read_b128 v[210:213], v163 offset:35840
	ds_read_b128 v[214:217], v163 offset:36864
	ds_read_b128 v[218:221], v163 offset:37888
	ds_read_b128 v[222:225], v163 offset:38912
	ds_read_b128 v[226:229], v163 offset:39936
	global_load_lds_dwordx4 v134, s[14:15]
	s_mov_b32 m0, s30
	s_nop 0
	global_load_lds_dwordx4 v130, s[14:15]
	s_waitcnt vmcnt(8)
	s_waitcnt lgkmcnt(0)
	s_barrier
	s_setprio 1
	s_waitcnt lgkmcnt(0)
	v_mfma_f32_16x16x32_bf16 v[124:127], v[166:169], v[198:201], v[124:127]
	v_mfma_f32_16x16x32_bf16 v[120:123], v[174:177], v[198:201], v[120:123]
	v_mfma_f32_16x16x32_bf16 v[108:111], v[166:169], v[206:209], v[108:111]
	v_mfma_f32_16x16x32_bf16 v[104:107], v[174:177], v[206:209], v[104:107]
	v_mfma_f32_16x16x32_bf16 v[92:95], v[166:169], v[214:217], v[92:95]
	v_mfma_f32_16x16x32_bf16 v[88:91], v[174:177], v[214:217], v[88:91]
	v_mfma_f32_16x16x32_bf16 v[76:79], v[166:169], v[222:225], v[76:79]
	v_mfma_f32_16x16x32_bf16 v[72:75], v[174:177], v[222:225], v[72:75]
	v_mfma_f32_16x16x32_bf16 v[124:127], v[170:173], v[202:205], v[124:127]
	v_mfma_f32_16x16x32_bf16 v[120:123], v[178:181], v[202:205], v[120:123]
	v_mfma_f32_16x16x32_bf16 v[108:111], v[170:173], v[210:213], v[108:111]
	v_mfma_f32_16x16x32_bf16 v[104:107], v[178:181], v[210:213], v[104:107]
	v_mfma_f32_16x16x32_bf16 v[92:95], v[170:173], v[218:221], v[92:95]
	v_mfma_f32_16x16x32_bf16 v[88:91], v[178:181], v[218:221], v[88:91]
	v_mfma_f32_16x16x32_bf16 v[76:79], v[170:173], v[226:229], v[76:79]
	v_mfma_f32_16x16x32_bf16 v[72:75], v[178:181], v[226:229], v[72:75]
	v_mfma_f32_16x16x32_bf16 v[116:119], v[182:185], v[198:201], v[116:119]
	v_mfma_f32_16x16x32_bf16 v[112:115], v[190:193], v[198:201], v[112:115]
	v_mfma_f32_16x16x32_bf16 v[100:103], v[182:185], v[206:209], v[100:103]
	v_mfma_f32_16x16x32_bf16 v[96:99], v[190:193], v[206:209], v[96:99]
	v_mfma_f32_16x16x32_bf16 v[84:87], v[182:185], v[214:217], v[84:87]
	v_mfma_f32_16x16x32_bf16 v[80:83], v[190:193], v[214:217], v[80:83]
	v_mfma_f32_16x16x32_bf16 v[68:71], v[182:185], v[222:225], v[68:71]
	v_mfma_f32_16x16x32_bf16 v[64:67], v[190:193], v[222:225], v[64:67]
	v_mfma_f32_16x16x32_bf16 v[116:119], v[186:189], v[202:205], v[116:119]
	v_mfma_f32_16x16x32_bf16 v[112:115], v[194:197], v[202:205], v[112:115]
	v_mfma_f32_16x16x32_bf16 v[100:103], v[186:189], v[210:213], v[100:103]
	v_mfma_f32_16x16x32_bf16 v[96:99], v[194:197], v[210:213], v[96:99]
	v_mfma_f32_16x16x32_bf16 v[84:87], v[186:189], v[218:221], v[84:87]
	v_mfma_f32_16x16x32_bf16 v[80:83], v[194:197], v[218:221], v[80:83]
	v_mfma_f32_16x16x32_bf16 v[68:71], v[186:189], v[226:229], v[68:71]
	v_mfma_f32_16x16x32_bf16 v[64:67], v[194:197], v[226:229], v[64:67]
	s_setprio 0
	s_barrier
	s_add_i32 s14, s34, s4
	v_lshl_add_u64 v[144:145], v[144:145], 0, s[46:47]
	s_mov_b32 m0, s14
	ds_read_b128 v[198:201], v163 offset:49152
	ds_read_b128 v[202:205], v163 offset:50176
	ds_read_b128 v[206:209], v163 offset:51200
	ds_read_b128 v[210:213], v163 offset:52224
	ds_read_b128 v[214:217], v163 offset:53248
	ds_read_b128 v[218:221], v163 offset:54272
	ds_read_b128 v[222:225], v163 offset:55296
	ds_read_b128 v[226:229], v163 offset:56320
	global_load_lds_dwordx4 v[144:145], off
	s_add_i32 m0, s14, 0x2000
	s_add_u32 s12, s12, 0x40080
	v_lshl_add_u64 v[144:145], v[152:153], 0, s[46:47]
	s_addc_u32 s13, s13, 0
	s_add_i32 s14, s35, s4
	global_load_lds_dwordx4 v[144:145], off
	s_mov_b32 m0, s14
	s_nop 0
	global_load_lds_dwordx4 v132, s[12:13]
	s_add_i32 m0, s14, 0x2000
	s_nop 0
	global_load_lds_dwordx4 v128, s[12:13]
	v_lshl_add_u64 v[144:145], v[156:157], 0, s[46:47]
	s_mov_b32 m0, s33
	s_nop 0
	global_load_lds_dwordx4 v[144:145], off
	v_lshl_add_u64 v[144:145], v[160:161], 0, s[46:47]
	s_mov_b32 m0, s58
	s_nop 0
	global_load_lds_dwordx4 v[144:145], off
	s_waitcnt vmcnt(8)
	s_waitcnt lgkmcnt(0)
	s_barrier
	s_setprio 1
	s_waitcnt lgkmcnt(0)
	v_mfma_f32_16x16x32_bf16 v[60:63], v[166:169], v[198:201], v[60:63]
	v_mfma_f32_16x16x32_bf16 v[56:59], v[174:177], v[198:201], v[56:59]
	v_mfma_f32_16x16x32_bf16 v[44:47], v[166:169], v[206:209], v[44:47]
	v_mfma_f32_16x16x32_bf16 v[40:43], v[174:177], v[206:209], v[40:43]
	v_mfma_f32_16x16x32_bf16 v[28:31], v[166:169], v[214:217], v[28:31]
	v_mfma_f32_16x16x32_bf16 v[24:27], v[174:177], v[214:217], v[24:27]
	v_mfma_f32_16x16x32_bf16 v[12:15], v[166:169], v[222:225], v[12:15]
	v_mfma_f32_16x16x32_bf16 v[8:11], v[174:177], v[222:225], v[8:11]
	v_mfma_f32_16x16x32_bf16 v[60:63], v[170:173], v[202:205], v[60:63]
	v_mfma_f32_16x16x32_bf16 v[56:59], v[178:181], v[202:205], v[56:59]
	v_mfma_f32_16x16x32_bf16 v[44:47], v[170:173], v[210:213], v[44:47]
	v_mfma_f32_16x16x32_bf16 v[40:43], v[178:181], v[210:213], v[40:43]
	v_mfma_f32_16x16x32_bf16 v[28:31], v[170:173], v[218:221], v[28:31]
	v_mfma_f32_16x16x32_bf16 v[24:27], v[178:181], v[218:221], v[24:27]
	v_mfma_f32_16x16x32_bf16 v[12:15], v[170:173], v[226:229], v[12:15]
	v_mfma_f32_16x16x32_bf16 v[8:11], v[178:181], v[226:229], v[8:11]
	v_mfma_f32_16x16x32_bf16 v[52:55], v[182:185], v[198:201], v[52:55]
	v_mfma_f32_16x16x32_bf16 v[48:51], v[190:193], v[198:201], v[48:51]
	v_mfma_f32_16x16x32_bf16 v[36:39], v[182:185], v[206:209], v[36:39]
	v_mfma_f32_16x16x32_bf16 v[32:35], v[190:193], v[206:209], v[32:35]
	v_mfma_f32_16x16x32_bf16 v[20:23], v[182:185], v[214:217], v[20:23]
	v_mfma_f32_16x16x32_bf16 v[16:19], v[190:193], v[214:217], v[16:19]
	v_mfma_f32_16x16x32_bf16 v[4:7], v[182:185], v[222:225], v[4:7]
	v_mfma_f32_16x16x32_bf16 v[0:3], v[190:193], v[222:225], v[0:3]
	v_mfma_f32_16x16x32_bf16 v[52:55], v[186:189], v[202:205], v[52:55]
	v_mfma_f32_16x16x32_bf16 v[48:51], v[194:197], v[202:205], v[48:51]
	v_mfma_f32_16x16x32_bf16 v[36:39], v[186:189], v[210:213], v[36:39]
	v_mfma_f32_16x16x32_bf16 v[32:35], v[194:197], v[210:213], v[32:35]
	v_mfma_f32_16x16x32_bf16 v[20:23], v[186:189], v[218:221], v[20:23]
	v_mfma_f32_16x16x32_bf16 v[16:19], v[194:197], v[218:221], v[16:19]
	v_mfma_f32_16x16x32_bf16 v[4:7], v[186:189], v[226:229], v[4:7]
	v_mfma_f32_16x16x32_bf16 v[0:3], v[194:197], v[226:229], v[0:3]
	s_setprio 0
	s_add_i32 s51, s51, 2
	s_add_u32 s10, s10, 0x100
	s_addc_u32 s11, s11, 0
	s_add_u32 s22, s22, 0x100
	s_addc_u32 s23, s23, 0
	s_cmp_gt_u32 s51, 13
	s_barrier
	s_cbranch_scc0 .LBB0_1850
	s_and_b64 vcc, exec, s[48:49]
	s_cbranch_vccz .LBB0_1853
	s_barrier

; #define PG8_STAGE(bufoff, gbase, voff) do { _Pragma("unroll") for (int _i = 0; _i < 2; ++_i) \
;         __builtin_amdgcn_global_load_lds((const unsigned*)((const char*)(gbase) + (voff)[_i]), (LAS unsigned*)(lds + (bufoff) + ldsw + _i * 8192), 16, 0, 0); } while (0)
; #define PG8_LDA(dst, b, h) do { _Pragma("unroll") for (int m = 0; m < 4; ++m) _Pragma("unroll") for (int k = 0; k < 2; ++k) dst[m][k] = *(const LAS bf16x8*)(lds + PG8_SA(b, h) + aoff + m * 2048 + k * 1024); } while (0)
; #define PG8_LDB(dst, b, h) do { _Pragma("unroll") for (int n = 0; n < 2; ++n) _Pragma("unroll") for (int k = 0; k < 2; ++k) dst[n][k] = *(const LAS bf16x8*)(lds + PG8_SB(b, h) + boff + n * 2048 + k * 1024); } while (0)
; #define PG8_MMA(ai, bj, At, Bt) do { __builtin_amdgcn_s_setprio(1); _Pragma("unroll") for (int m = 0; m < 4; ++m) _Pragma("unroll") for (int n = 0; n < 2; ++n) _Pragma("unroll") for (int k = 0; k < 2; ++k) \
;         acc[ai][bj][m][n] = __builtin_amdgcn_mfma_f32_16x16x32_bf16(Bt[n][k], At[m][k], acc[ai][bj][m][n], 0, 0, 0); __builtin_amdgcn_s_setprio(0); } while (0)
; #define PG8_WAIT_V(n) asm volatile("s_waitcnt vmcnt(" #n ")" ::: "memory")
; #define PG8_WAIT_L(n) asm volatile("s_waitcnt lgkmcnt(" #n ")" ::: "memory")
; template <class Epi, class Sched, bool ALIGN_EPI = false, bool SP2 = false>
; __device__ __forceinline__ void gemm_phase(LAS unsigned char* lds, const Gemm g, const Sched S, const Epi E) {
;     ...
;         for (int t = 0; t < nt; t += 2) {
;             const bool last = (t == nt - 2);
;             const char* a1 = cA + (size_t)(t + 1) * kstep;
;             const char* a2 = last ? nA : cA + (size_t)(t + 2) * kstep; const char* b2 = last ? nB : cB + (size_t)(t + 2) * kstep;
;             const char* a3 = a2 + kstep; const char* b3 = b2 + kstep;
;             if (last && has_next) S.a_ready(nxt);
;             if constexpr (SP2) {
;             PG8_LDB(B0, 0, 0); PG8_LDB(B1, 0, 1); PG8_SCHED; PG8_LDA(At, 0, 0); PG8_STAGE(PG8_SA(1, 1), a1 + hstepA, voffA);
;             PG8_WAIT_V(8); PG8_WAIT_L(0); PG8_BAR; PG8_MMA(0, 0, At, B0); PG8_MMA(0, 1, At, B1); PG8_BAR; PG8_SCHED;
;             PG8_LDA(At, 0, 1); PG8_STAGE(PG8_SB(0, 0), b2, voffB); PG8_STAGE(PG8_SB(0, 1), b2 + hstepB, voffB); PG8_STAGE(PG8_SA(0, 0), a2, voffA);
;             PG8_WAIT_V(8); PG8_WAIT_L(0); PG8_BAR; PG8_MMA(1, 0, At, B0); PG8_MMA(1, 1, At, B1); PG8_BAR; PG8_SCHED;
.LBB0_1930:
	ds_read_b128 v[144:147], v155
	ds_read_b128 v[148:151], v155 offset:1024
	ds_read_b128 v[158:161], v155 offset:2048
	ds_read_b128 v[162:165], v155 offset:3072
	ds_read_b128 v[166:169], v156
	ds_read_b128 v[170:173], v156 offset:1024
	ds_read_b128 v[174:177], v156 offset:2048
	ds_read_b128 v[178:181], v156 offset:3072
	s_add_u32 s44, s42, 0x100
	s_addc_u32 s45, s43, 0
	s_cmp_eq_u32 s66, 40
	s_cselect_b32 s49, s7, s45
	s_cselect_b32 s48, s6, s44
	s_cselect_b32 s47, s39, s65
	s_cselect_b32 s46, s38, s64
	s_add_i32 m0, s21, 0xc000
	ds_read_b128 v[182:185], v157
	ds_read_b128 v[186:189], v157 offset:1024
	ds_read_b128 v[190:193], v157 offset:2048
	ds_read_b128 v[194:197], v157 offset:3072
	ds_read_b128 v[198:201], v157 offset:4096
	ds_read_b128 v[202:205], v157 offset:5120
	ds_read_b128 v[206:209], v157 offset:6144
	ds_read_b128 v[210:213], v157 offset:7168
	global_load_lds_dwordx4 v136, s[42:43]
	s_add_i32 m0, s21, 0xe000
	s_nop 0
	global_load_lds_dwordx4 v138, s[42:43]
	s_waitcnt vmcnt(8)
	s_waitcnt lgkmcnt(0)
	s_barrier
	s_setprio 1
	s_waitcnt lgkmcnt(0)
	v_mfma_f32_16x16x32_bf16 v[124:127], v[144:147], v[182:185], v[124:127]
	v_mfma_f32_16x16x32_bf16 v[120:123], v[158:161], v[182:185], v[120:123]
	v_mfma_f32_16x16x32_bf16 v[108:111], v[144:147], v[190:193], v[108:111]
	v_mfma_f32_16x16x32_bf16 v[104:107], v[158:161], v[190:193], v[104:107]
	v_mfma_f32_16x16x32_bf16 v[92:95], v[144:147], v[198:201], v[92:95]
	v_mfma_f32_16x16x32_bf16 v[88:91], v[158:161], v[198:201], v[88:91]
	v_mfma_f32_16x16x32_bf16 v[76:79], v[144:147], v[206:209], v[76:79]
	v_mfma_f32_16x16x32_bf16 v[72:75], v[158:161], v[206:209], v[72:75]
	v_mfma_f32_16x16x32_bf16 v[124:127], v[148:151], v[186:189], v[124:127]
	v_mfma_f32_16x16x32_bf16 v[120:123], v[162:165], v[186:189], v[120:123]
	v_mfma_f32_16x16x32_bf16 v[108:111], v[148:151], v[194:197], v[108:111]
	v_mfma_f32_16x16x32_bf16 v[104:107], v[162:165], v[194:197], v[104:107]
	v_mfma_f32_16x16x32_bf16 v[92:95], v[148:151], v[202:205], v[92:95]
	v_mfma_f32_16x16x32_bf16 v[88:91], v[162:165], v[202:205], v[88:91]
	v_mfma_f32_16x16x32_bf16 v[76:79], v[148:151], v[210:213], v[76:79]
	v_mfma_f32_16x16x32_bf16 v[72:75], v[162:165], v[210:213], v[72:75]
	v_mfma_f32_16x16x32_bf16 v[116:119], v[166:169], v[182:185], v[116:119]
	v_mfma_f32_16x16x32_bf16 v[112:115], v[174:177], v[182:185], v[112:115]
	v_mfma_f32_16x16x32_bf16 v[100:103], v[166:169], v[190:193], v[100:103]
	v_mfma_f32_16x16x32_bf16 v[96:99], v[174:177], v[190:193], v[96:99]
	v_mfma_f32_16x16x32_bf16 v[84:87], v[166:169], v[198:201], v[84:87]
	v_mfma_f32_16x16x32_bf16 v[80:83], v[174:177], v[198:201], v[80:83]
	v_mfma_f32_16x16x32_bf16 v[68:71], v[166:169], v[206:209], v[68:71]
	v_mfma_f32_16x16x32_bf16 v[64:67], v[174:177], v[206:209], v[64:67]
	v_mfma_f32_16x16x32_bf16 v[116:119], v[170:173], v[186:189], v[116:119]
	v_mfma_f32_16x16x32_bf16 v[112:115], v[178:181], v[186:189], v[112:115]
	v_mfma_f32_16x16x32_bf16 v[100:103], v[170:173], v[194:197], v[100:103]
	v_mfma_f32_16x16x32_bf16 v[96:99], v[178:181], v[194:197], v[96:99]
	v_mfma_f32_16x16x32_bf16 v[84:87], v[170:173], v[202:205], v[84:87]
	v_mfma_f32_16x16x32_bf16 v[80:83], v[178:181], v[202:205], v[80:83]
	v_mfma_f32_16x16x32_bf16 v[68:71], v[170:173], v[210:213], v[68:71]
	v_mfma_f32_16x16x32_bf16 v[64:67], v[178:181], v[210:213], v[64:67]
	s_setprio 0
	s_barrier
	s_add_i32 s34, s54, s20
	v_lshl_add_u64 v[214:215], s[46:47], 0, v[130:131]
	s_mov_b32 m0, s34
	ds_read_b128 v[182:185], v157 offset:16384
	ds_read_b128 v[186:189], v157 offset:17408
	ds_read_b128 v[190:193], v157 offset:18432
	ds_read_b128 v[194:197], v157 offset:19456
	ds_read_b128 v[198:201], v157 offset:20480
	ds_read_b128 v[202:205], v157 offset:21504
	ds_read_b128 v[206:209], v157 offset:22528
	ds_read_b128 v[210:213], v157 offset:23552
	global_load_lds_dwordx4 v[214:215], off
	s_add_i32 m0, s34, 0x2000
	s_add_u32 s34, s46, 0xb0000
	v_lshl_add_u64 v[216:217], s[46:47], 0, v[134:135]
	s_addc_u32 s35, s47, 0
	s_add_i32 s42, s55, s20
	global_load_lds_dwordx4 v[216:217], off
	s_mov_b32 m0, s42
	v_lshl_add_u64 v[220:221], s[48:49], 0, v[132:133]
	global_load_lds_dwordx4 v130, s[34:35]
	s_add_i32 m0, s42, 0x2000
	s_nop 0
	global_load_lds_dwordx4 v134, s[34:35]
	v_lshl_add_u64 v[218:219], s[48:49], 0, v[128:129]
	s_mov_b32 m0, s21
	s_nop 0
	global_load_lds_dwordx4 v[218:219], off
	s_mov_b32 m0, s29
	s_nop 0
	global_load_lds_dwordx4 v[220:221], off
	s_waitcnt vmcnt(8)
	s_waitcnt lgkmcnt(0)
	s_barrier
	s_setprio 1
	s_waitcnt lgkmcnt(0)
	v_mfma_f32_16x16x32_bf16 v[60:63], v[144:147], v[182:185], v[60:63]
	v_mfma_f32_16x16x32_bf16 v[56:59], v[158:161], v[182:185], v[56:59]
	v_mfma_f32_16x16x32_bf16 v[44:47], v[144:147], v[190:193], v[44:47]
	v_mfma_f32_16x16x32_bf16 v[40:43], v[158:161], v[190:193], v[40:43]
	v_mfma_f32_16x16x32_bf16 v[28:31], v[144:147], v[198:201], v[28:31]
	v_mfma_f32_16x16x32_bf16 v[24:27], v[158:161], v[198:201], v[24:27]
	v_mfma_f32_16x16x32_bf16 v[12:15], v[144:147], v[206:209], v[12:15]
	v_mfma_f32_16x16x32_bf16 v[8:11], v[158:161], v[206:209], v[8:11]
	v_mfma_f32_16x16x32_bf16 v[60:63], v[148:151], v[186:189], v[60:63]
	v_mfma_f32_16x16x32_bf16 v[56:59], v[162:165], v[186:189], v[56:59]
	v_mfma_f32_16x16x32_bf16 v[44:47], v[148:151], v[194:197], v[44:47]
	v_mfma_f32_16x16x32_bf16 v[40:43], v[162:165], v[194:197], v[40:43]
	v_mfma_f32_16x16x32_bf16 v[28:31], v[148:151], v[202:205], v[28:31]
	v_mfma_f32_16x16x32_bf16 v[24:27], v[162:165], v[202:205], v[24:27]
	v_mfma_f32_16x16x32_bf16 v[12:15], v[148:151], v[210:213], v[12:15]
	v_mfma_f32_16x16x32_bf16 v[8:11], v[162:165], v[210:213], v[8:11]
	v_mfma_f32_16x16x32_bf16 v[52:55], v[166:169], v[182:185], v[52:55]
	v_mfma_f32_16x16x32_bf16 v[48:51], v[174:177], v[182:185], v[48:51]
	v_mfma_f32_16x16x32_bf16 v[36:39], v[166:169], v[190:193], v[36:39]
	v_mfma_f32_16x16x32_bf16 v[32:35], v[174:177], v[190:193], v[32:35]
	v_mfma_f32_16x16x32_bf16 v[20:23], v[166:169], v[198:201], v[20:23]
	v_mfma_f32_16x16x32_bf16 v[16:19], v[174:177], v[198:201], v[16:19]
	v_mfma_f32_16x16x32_bf16 v[4:7], v[166:169], v[206:209], v[4:7]
	v_mfma_f32_16x16x32_bf16 v[0:3], v[174:177], v[206:209], v[0:3]
	v_mfma_f32_16x16x32_bf16 v[52:55], v[170:173], v[186:189], v[52:55]
	v_mfma_f32_16x16x32_bf16 v[48:51], v[178:181], v[186:189], v[48:51]
	v_mfma_f32_16x16x32_bf16 v[36:39], v[170:173], v[194:197], v[36:39]
	v_mfma_f32_16x16x32_bf16 v[32:35], v[178:181], v[194:197], v[32:35]
	v_mfma_f32_16x16x32_bf16 v[20:23], v[170:173], v[202:205], v[20:23]
	v_mfma_f32_16x16x32_bf16 v[16:19], v[178:181], v[202:205], v[16:19]
	v_mfma_f32_16x16x32_bf16 v[4:7], v[170:173], v[210:213], v[4:7]
	v_mfma_f32_16x16x32_bf16 v[0:3], v[178:181], v[210:213], v[0:3]
	s_setprio 0
	s_barrier
; #define PG8_STAGE(bufoff, gbase, voff) do { _Pragma("unroll") for (int _i = 0; _i < 2; ++_i) \
;         __builtin_amdgcn_global_load_lds((const unsigned*)((const char*)(gbase) + (voff)[_i]), (LAS unsigned*)(lds + (bufoff) + ldsw + _i * 8192), 16, 0, 0); } while (0)
; #define PG8_LDA(dst, b, h) do { _Pragma("unroll") for (int m = 0; m < 4; ++m) _Pragma("unroll") for (int k = 0; k < 2; ++k) dst[m][k] = *(const LAS bf16x8*)(lds + PG8_SA(b, h) + aoff + m * 2048 + k * 1024); } while (0)
; #define PG8_LDB(dst, b, h) do { _Pragma("unroll") for (int n = 0; n < 2; ++n) _Pragma("unroll") for (int k = 0; k < 2; ++k) dst[n][k] = *(const LAS bf16x8*)(lds + PG8_SB(b, h) + boff + n * 2048 + k * 1024); } while (0)
; #define PG8_MMA(ai, bj, At, Bt) do { __builtin_amdgcn_s_setprio(1); _Pragma("unroll") for (int m = 0; m < 4; ++m) _Pragma("unroll") for (int n = 0; n < 2; ++n) _Pragma("unroll") for (int k = 0; k < 2; ++k) \
;         acc[ai][bj][m][n] = __builtin_amdgcn_mfma_f32_16x16x32_bf16(Bt[n][k], At[m][k], acc[ai][bj][m][n], 0, 0, 0); __builtin_amdgcn_s_setprio(0); } while (0)
; #define PG8_WAIT_V(n) asm volatile("s_waitcnt vmcnt(" #n ")" ::: "memory")
; #define PG8_WAIT_L(n) asm volatile("s_waitcnt lgkmcnt(" #n ")" ::: "memory")
; #define PG8_BAR __builtin_amdgcn_s_barrier()
; #define PG8_SCHED __builtin_amdgcn_sched_barrier(0)
; template <class Epi, class Sched, bool ALIGN_EPI = false, bool SP2 = false>
; __device__ __forceinline__ void gemm_phase(LAS unsigned char* lds, const Gemm g, const Sched S, const Epi E) {
;     ...
;             PG8_LDB(B0, 1, 0); PG8_LDB(B1, 1, 1); PG8_SCHED; PG8_LDA(At, 1, 0); PG8_STAGE(PG8_SA(0, 1), a2 + hstepA, voffA);
;             PG8_WAIT_V(8); PG8_WAIT_L(0); PG8_BAR; PG8_MMA(0, 0, At, B0); PG8_MMA(0, 1, At, B1); PG8_BAR; PG8_SCHED;
;             PG8_LDA(At, 1, 1); PG8_STAGE(PG8_SB(1, 0), b3, voffB); PG8_STAGE(PG8_SB(1, 1), b3 + hstepB, voffB); PG8_STAGE(PG8_SA(1, 0), a3, voffA);
;             PG8_WAIT_V(8); PG8_WAIT_L(0); PG8_BAR; PG8_MMA(1, 0, At, B0); PG8_MMA(1, 1, At, B1); PG8_BAR; PG8_SCHED;
	s_add_i32 s42, 0, 0x18000
	s_add_i32 s43, 0, 0x1c000
	v_add_u32_e32 v162, s42, v153
	v_add_u32_e32 v178, s43, v153
	ds_read_b128 v[144:147], v162
	ds_read_b128 v[148:151], v162 offset:1024
	ds_read_b128 v[158:161], v162 offset:2048
	ds_read_b128 v[162:165], v162 offset:3072
	ds_read_b128 v[166:169], v178
	ds_read_b128 v[170:173], v178 offset:1024
	ds_read_b128 v[174:177], v178 offset:2048
	ds_read_b128 v[178:181], v178 offset:3072
	s_add_u32 s34, s48, 0xb0000
	s_addc_u32 s35, s49, 0
	s_mov_b32 m0, s30
	ds_read_b128 v[182:185], v157 offset:32768
	ds_read_b128 v[186:189], v157 offset:33792
	ds_read_b128 v[190:193], v157 offset:34816
	ds_read_b128 v[194:197], v157 offset:35840
	ds_read_b128 v[198:201], v157 offset:36864
	ds_read_b128 v[202:205], v157 offset:37888
	ds_read_b128 v[206:209], v157 offset:38912
	ds_read_b128 v[210:213], v157 offset:39936
	global_load_lds_dwordx4 v128, s[34:35]
	s_mov_b32 m0, s31
	s_nop 0
	global_load_lds_dwordx4 v132, s[34:35]
	s_waitcnt vmcnt(8)
	s_waitcnt lgkmcnt(0)
	s_barrier
	s_setprio 1
	s_waitcnt lgkmcnt(0)
	v_mfma_f32_16x16x32_bf16 v[124:127], v[144:147], v[182:185], v[124:127]
	v_mfma_f32_16x16x32_bf16 v[120:123], v[158:161], v[182:185], v[120:123]
	v_mfma_f32_16x16x32_bf16 v[108:111], v[144:147], v[190:193], v[108:111]
	v_mfma_f32_16x16x32_bf16 v[104:107], v[158:161], v[190:193], v[104:107]
	v_mfma_f32_16x16x32_bf16 v[92:95], v[144:147], v[198:201], v[92:95]
	v_mfma_f32_16x16x32_bf16 v[88:91], v[158:161], v[198:201], v[88:91]
	v_mfma_f32_16x16x32_bf16 v[76:79], v[144:147], v[206:209], v[76:79]
	v_mfma_f32_16x16x32_bf16 v[72:75], v[158:161], v[206:209], v[72:75]
	v_mfma_f32_16x16x32_bf16 v[124:127], v[148:151], v[186:189], v[124:127]
	v_mfma_f32_16x16x32_bf16 v[120:123], v[162:165], v[186:189], v[120:123]
	v_mfma_f32_16x16x32_bf16 v[108:111], v[148:151], v[194:197], v[108:111]
	v_mfma_f32_16x16x32_bf16 v[104:107], v[162:165], v[194:197], v[104:107]
	v_mfma_f32_16x16x32_bf16 v[92:95], v[148:151], v[202:205], v[92:95]
	v_mfma_f32_16x16x32_bf16 v[88:91], v[162:165], v[202:205], v[88:91]
	v_mfma_f32_16x16x32_bf16 v[76:79], v[148:151], v[210:213], v[76:79]
	v_mfma_f32_16x16x32_bf16 v[72:75], v[162:165], v[210:213], v[72:75]
	v_mfma_f32_16x16x32_bf16 v[116:119], v[166:169], v[182:185], v[116:119]
	v_mfma_f32_16x16x32_bf16 v[112:115], v[174:177], v[182:185], v[112:115]
	v_mfma_f32_16x16x32_bf16 v[100:103], v[166:169], v[190:193], v[100:103]
	v_mfma_f32_16x16x32_bf16 v[96:99], v[174:177], v[190:193], v[96:99]
	v_mfma_f32_16x16x32_bf16 v[84:87], v[166:169], v[198:201], v[84:87]
	v_mfma_f32_16x16x32_bf16 v[80:83], v[174:177], v[198:201], v[80:83]
	v_mfma_f32_16x16x32_bf16 v[68:71], v[166:169], v[206:209], v[68:71]
	v_mfma_f32_16x16x32_bf16 v[64:67], v[174:177], v[206:209], v[64:67]
	v_mfma_f32_16x16x32_bf16 v[116:119], v[170:173], v[186:189], v[116:119]
	v_mfma_f32_16x16x32_bf16 v[112:115], v[178:181], v[186:189], v[112:115]
	v_mfma_f32_16x16x32_bf16 v[100:103], v[170:173], v[194:197], v[100:103]
	v_mfma_f32_16x16x32_bf16 v[96:99], v[178:181], v[194:197], v[96:99]
	v_mfma_f32_16x16x32_bf16 v[84:87], v[170:173], v[202:205], v[84:87]
	v_mfma_f32_16x16x32_bf16 v[80:83], v[178:181], v[202:205], v[80:83]
	v_mfma_f32_16x16x32_bf16 v[68:71], v[170:173], v[210:213], v[68:71]
	v_mfma_f32_16x16x32_bf16 v[64:67], v[178:181], v[210:213], v[64:67]
	s_setprio 0
	s_barrier
	s_add_i32 s34, s42, s20
	v_lshl_add_u64 v[214:215], v[214:215], 0, s[12:13]
	s_mov_b32 m0, s34
	ds_read_b128 v[182:185], v157 offset:49152
	ds_read_b128 v[186:189], v157 offset:50176
	ds_read_b128 v[190:193], v157 offset:51200
	ds_read_b128 v[194:197], v157 offset:52224
	ds_read_b128 v[198:201], v157 offset:53248
	ds_read_b128 v[202:205], v157 offset:54272
	ds_read_b128 v[206:209], v157 offset:55296
	ds_read_b128 v[210:213], v157 offset:56320
	global_load_lds_dwordx4 v[214:215], off
	s_add_i32 m0, s34, 0x2000
	s_add_u32 s34, s46, 0xb0080
	v_lshl_add_u64 v[214:215], v[216:217], 0, s[12:13]
	s_addc_u32 s35, s47, 0
	s_add_i32 s42, s43, s20
	global_load_lds_dwordx4 v[214:215], off
	s_mov_b32 m0, s42
	s_nop 0
	global_load_lds_dwordx4 v130, s[34:35]
	s_add_i32 m0, s42, 0x2000
	s_nop 0
	global_load_lds_dwordx4 v134, s[34:35]
	v_lshl_add_u64 v[214:215], v[218:219], 0, s[12:13]
	s_mov_b32 m0, s50
	s_nop 0
	global_load_lds_dwordx4 v[214:215], off
	v_lshl_add_u64 v[214:215], v[220:221], 0, s[12:13]
	s_mov_b32 m0, s51
	s_nop 0
	global_load_lds_dwordx4 v[214:215], off
	s_waitcnt vmcnt(8)
	s_waitcnt lgkmcnt(0)
	s_barrier
	s_setprio 1
	s_waitcnt lgkmcnt(0)
	v_mfma_f32_16x16x32_bf16 v[60:63], v[144:147], v[182:185], v[60:63]
	v_mfma_f32_16x16x32_bf16 v[56:59], v[158:161], v[182:185], v[56:59]
	v_mfma_f32_16x16x32_bf16 v[44:47], v[144:147], v[190:193], v[44:47]
	v_mfma_f32_16x16x32_bf16 v[40:43], v[158:161], v[190:193], v[40:43]
	v_mfma_f32_16x16x32_bf16 v[28:31], v[144:147], v[198:201], v[28:31]
	v_mfma_f32_16x16x32_bf16 v[24:27], v[158:161], v[198:201], v[24:27]
	v_mfma_f32_16x16x32_bf16 v[12:15], v[144:147], v[206:209], v[12:15]
	v_mfma_f32_16x16x32_bf16 v[8:11], v[158:161], v[206:209], v[8:11]
	v_mfma_f32_16x16x32_bf16 v[60:63], v[148:151], v[186:189], v[60:63]
	v_mfma_f32_16x16x32_bf16 v[56:59], v[162:165], v[186:189], v[56:59]
	v_mfma_f32_16x16x32_bf16 v[44:47], v[148:151], v[194:197], v[44:47]
	v_mfma_f32_16x16x32_bf16 v[40:43], v[162:165], v[194:197], v[40:43]
	v_mfma_f32_16x16x32_bf16 v[28:31], v[148:151], v[202:205], v[28:31]
	v_mfma_f32_16x16x32_bf16 v[24:27], v[162:165], v[202:205], v[24:27]
	v_mfma_f32_16x16x32_bf16 v[12:15], v[148:151], v[210:213], v[12:15]
	v_mfma_f32_16x16x32_bf16 v[8:11], v[162:165], v[210:213], v[8:11]
	v_mfma_f32_16x16x32_bf16 v[52:55], v[166:169], v[182:185], v[52:55]
	v_mfma_f32_16x16x32_bf16 v[48:51], v[174:177], v[182:185], v[48:51]
	v_mfma_f32_16x16x32_bf16 v[36:39], v[166:169], v[190:193], v[36:39]
	v_mfma_f32_16x16x32_bf16 v[32:35], v[174:177], v[190:193], v[32:35]
	v_mfma_f32_16x16x32_bf16 v[20:23], v[166:169], v[198:201], v[20:23]
	v_mfma_f32_16x16x32_bf16 v[16:19], v[174:177], v[198:201], v[16:19]
	v_mfma_f32_16x16x32_bf16 v[4:7], v[166:169], v[206:209], v[4:7]
	v_mfma_f32_16x16x32_bf16 v[0:3], v[174:177], v[206:209], v[0:3]
	v_mfma_f32_16x16x32_bf16 v[52:55], v[170:173], v[186:189], v[52:55]
	v_mfma_f32_16x16x32_bf16 v[48:51], v[178:181], v[186:189], v[48:51]
	v_mfma_f32_16x16x32_bf16 v[36:39], v[170:173], v[194:197], v[36:39]
	v_mfma_f32_16x16x32_bf16 v[32:35], v[178:181], v[194:197], v[32:35]
	v_mfma_f32_16x16x32_bf16 v[20:23], v[170:173], v[202:205], v[20:23]
	v_mfma_f32_16x16x32_bf16 v[16:19], v[178:181], v[202:205], v[16:19]
	v_mfma_f32_16x16x32_bf16 v[4:7], v[170:173], v[210:213], v[4:7]
	v_mfma_f32_16x16x32_bf16 v[0:3], v[178:181], v[210:213], v[0:3]
	s_setprio 0
	s_add_i32 s66, s66, 2
	s_add_u32 s64, s64, 0x100
	s_addc_u32 s65, s65, 0
	s_cmp_gt_u32 s66, 41
	s_mov_b64 s[42:43], s[44:45]
	s_barrier
	s_cbranch_scc0 .LBB0_1930
	s_and_b64 vcc, exec, s[14:15]
	s_cbranch_vccz .LBB0_1933
	s_barrier
